# GEMM K-loops: last 2 LDS-DMA issues of the 6-DMA phases moved into the wave's own MFMA block, vmcnt(6)
# baseline (speedup 1.0000x reference)
; #define PG8_STAGE(bufoff, gbase, voff) do { _Pragma("unroll") for (int _i = 0; _i < 2; ++_i) \
;         __builtin_amdgcn_global_load_lds((const unsigned*)((const char*)(gbase) + (voff)[_i]), (LAS unsigned*)(lds + (bufoff) + ldsw + _i * 8192), 16, 0, 0); } while (0)
; #define PG8_LDA(dst, b, h) do { _Pragma("unroll") for (int m = 0; m < 4; ++m) _Pragma("unroll") for (int k = 0; k < 2; ++k) dst[m][k] = *(const LAS bf16x8*)(lds + PG8_SA(b, h) + aoff + m * 2048 + k * 1024); } while (0)
; #define PG8_LDB(dst, b, h) do { _Pragma("unroll") for (int n = 0; n < 2; ++n) _Pragma("unroll") for (int k = 0; k < 2; ++k) dst[n][k] = *(const LAS bf16x8*)(lds + PG8_SB(b, h) + boff + n * 2048 + k * 1024); } while (0)
; #define PG8_MMA(ai, bj, At, Bt) do { __builtin_amdgcn_s_setprio(1); _Pragma("unroll") for (int m = 0; m < 4; ++m) _Pragma("unroll") for (int n = 0; n < 2; ++n) _Pragma("unroll") for (int k = 0; k < 2; ++k) \
;         acc[ai][bj][m][n] = __builtin_amdgcn_mfma_f32_16x16x32_bf16(Bt[n][k], At[m][k], acc[ai][bj][m][n], 0, 0, 0); __builtin_amdgcn_s_setprio(0); } while (0)
; #define PG8_WAIT_V(n) asm volatile("s_waitcnt vmcnt(" #n ")" ::: "memory")
; #define PG8_WAIT_L(n) asm volatile("s_waitcnt lgkmcnt(" #n ")" ::: "memory")
; #define PG8_BAR __builtin_amdgcn_s_barrier()
; #define PG8_SCHED __builtin_amdgcn_sched_barrier(0)
; template <class Epi, class Sched>
; DI void gemm_phase(LAS unsigned char* lds, const int K, const Sched& S, const Epi& E) {
;     ...
;             const bool last = (t == nt - 2);
;             const char* a1 = cA + (size_t)(t + 1) * kstep;
;             const char* a2 = last ? nA : cA + (size_t)(t + 2) * kstep; const char* b2 = last ? nB : cB + (size_t)(t + 2) * kstep;
;             const char* a3 = a2 + kstep; const char* b3 = b2 + kstep;
;             PG8_LDB(B0, 0, 0); PG8_LDB(B1, 0, 1); PG8_SCHED; PG8_LDA(At, 0, 0); PG8_STAGE(PG8_SA(1, 1), a1 + hstep, voffA);
;             PG8_WAIT_V(8); PG8_WAIT_L(0); PG8_BAR; PG8_MMA(0, 0, At, B0); PG8_MMA(0, 1, At, B1); PG8_BAR; PG8_SCHED;
;             PG8_LDA(At, 0, 1); PG8_STAGE(PG8_SB(0, 0), b2, voffB); PG8_STAGE(PG8_SB(0, 1), b2 + hstep, voffB); PG8_STAGE(PG8_SA(0, 0), a2, voffA);
;             PG8_WAIT_V(8); PG8_WAIT_L(0); PG8_BAR; PG8_MMA(1, 0, At, B0); PG8_MMA(1, 1, At, B1); PG8_BAR; PG8_SCHED;
.LBB0_218:
	s_add_u32 s80, s78, 0xfffc0080
	s_addc_u32 s81, s79, -1
	s_add_i32 vcc_lo, 0, 0x10000
	s_cmp_eq_u32 s87, 12
	s_cselect_b32 s83, s45, s81
	s_cselect_b32 s82, s73, s80
	s_cselect_b32 s81, s77, s86
	s_cselect_b32 s80, s84, s85
	s_add_i32 s63, 0, 0x14000
	v_add_u32_e32 v142, vcc_lo, v201
	v_add_u32_e32 v158, s63, v201
	ds_read_b128 v[130:133], v142
	ds_read_b128 v[134:137], v142 offset:1024
	ds_read_b128 v[138:141], v142 offset:2048
	ds_read_b128 v[142:145], v142 offset:3072
	ds_read_b128 v[146:149], v158
	ds_read_b128 v[150:153], v158 offset:1024
	ds_read_b128 v[154:157], v158 offset:2048
	ds_read_b128 v[158:161], v158 offset:3072
	v_lshl_add_u64 v[198:199], s[78:79], 0, v[172:173]
	s_add_i32 m0, s56, 0xc000
	ds_read_b128 v[174:177], v202
	ds_read_b128 v[182:185], v202 offset:1024
	ds_read_b128 v[190:193], v202 offset:2048
	ds_read_b128 v[194:197], v202 offset:3072
	ds_read_b128 v[212:215], v202 offset:4096
	ds_read_b128 v[216:219], v202 offset:5120
	ds_read_b128 v[220:223], v202 offset:6144
	ds_read_b128 v[224:227], v202 offset:7168
	global_load_lds_dwordx4 v[198:199], off
	v_lshl_add_u64 v[198:199], s[78:79], 0, v[170:171]
	s_add_i32 m0, s56, 0xe000
	s_nop 0
	global_load_lds_dwordx4 v[198:199], off
	s_waitcnt vmcnt(8)
	s_waitcnt lgkmcnt(0)
	s_barrier
	s_setprio 1
	s_waitcnt lgkmcnt(0)
	v_mfma_f32_16x16x32_bf16 v[126:129], v[130:133], v[174:177], v[126:129]
	v_mfma_f32_16x16x32_bf16 v[122:125], v[138:141], v[174:177], v[122:125]
	v_mfma_f32_16x16x32_bf16 v[110:113], v[130:133], v[190:193], v[110:113]
	v_mfma_f32_16x16x32_bf16 v[106:109], v[138:141], v[190:193], v[106:109]
	v_mfma_f32_16x16x32_bf16 v[94:97], v[130:133], v[212:215], v[94:97]
	v_mfma_f32_16x16x32_bf16 v[90:93], v[138:141], v[212:215], v[90:93]
	v_mfma_f32_16x16x32_bf16 v[78:81], v[130:133], v[220:223], v[78:81]
	v_mfma_f32_16x16x32_bf16 v[74:77], v[138:141], v[220:223], v[74:77]
	v_mfma_f32_16x16x32_bf16 v[126:129], v[134:137], v[182:185], v[126:129]
	v_mfma_f32_16x16x32_bf16 v[122:125], v[142:145], v[182:185], v[122:125]
	v_mfma_f32_16x16x32_bf16 v[110:113], v[134:137], v[194:197], v[110:113]
	v_mfma_f32_16x16x32_bf16 v[106:109], v[142:145], v[194:197], v[106:109]
	v_mfma_f32_16x16x32_bf16 v[94:97], v[134:137], v[216:219], v[94:97]
	v_mfma_f32_16x16x32_bf16 v[90:93], v[142:145], v[216:219], v[90:93]
	v_mfma_f32_16x16x32_bf16 v[78:81], v[134:137], v[224:227], v[78:81]
	v_mfma_f32_16x16x32_bf16 v[74:77], v[142:145], v[224:227], v[74:77]
	s_setprio 0
	s_setprio 1
	v_mfma_f32_16x16x32_bf16 v[118:121], v[146:149], v[174:177], v[118:121]
	v_mfma_f32_16x16x32_bf16 v[114:117], v[154:157], v[174:177], v[114:117]
	v_mfma_f32_16x16x32_bf16 v[102:105], v[146:149], v[190:193], v[102:105]
	v_mfma_f32_16x16x32_bf16 v[98:101], v[154:157], v[190:193], v[98:101]
	v_mfma_f32_16x16x32_bf16 v[86:89], v[146:149], v[212:215], v[86:89]
	v_mfma_f32_16x16x32_bf16 v[82:85], v[154:157], v[212:215], v[82:85]
	v_mfma_f32_16x16x32_bf16 v[70:73], v[146:149], v[220:223], v[70:73]
	v_mfma_f32_16x16x32_bf16 v[66:69], v[154:157], v[220:223], v[66:69]
	v_mfma_f32_16x16x32_bf16 v[118:121], v[150:153], v[182:185], v[118:121]
	v_mfma_f32_16x16x32_bf16 v[114:117], v[158:161], v[182:185], v[114:117]
	v_mfma_f32_16x16x32_bf16 v[102:105], v[150:153], v[194:197], v[102:105]
	v_mfma_f32_16x16x32_bf16 v[98:101], v[158:161], v[194:197], v[98:101]
	v_mfma_f32_16x16x32_bf16 v[86:89], v[150:153], v[216:219], v[86:89]
	v_mfma_f32_16x16x32_bf16 v[82:85], v[158:161], v[216:219], v[82:85]
	v_mfma_f32_16x16x32_bf16 v[70:73], v[150:153], v[224:227], v[70:73]
	v_mfma_f32_16x16x32_bf16 v[66:69], v[158:161], v[224:227], v[66:69]
	s_setprio 0
	s_barrier
	s_add_i32 vcc_lo, vcc_lo, s55
	v_lshl_add_u64 v[198:199], s[80:81], 0, v[164:165]
	s_mov_b32 m0, vcc_lo
	ds_read_b128 v[174:177], v202 offset:16384
	ds_read_b128 v[182:185], v202 offset:17408
	ds_read_b128 v[190:193], v202 offset:18432
	ds_read_b128 v[194:197], v202 offset:19456
	ds_read_b128 v[212:215], v202 offset:20480
	ds_read_b128 v[216:219], v202 offset:21504
	ds_read_b128 v[220:223], v202 offset:22528
	ds_read_b128 v[224:227], v202 offset:23552
	global_load_lds_dwordx4 v[198:199], off
	s_add_i32 m0, vcc_lo, 0x2000
	s_add_u32 vcc_lo, s80, 0x40000
	v_lshl_add_u64 v[204:205], s[80:81], 0, v[168:169]
	s_addc_u32 vcc_hi, s81, 0
	s_add_i32 s63, s63, s55
	global_load_lds_dwordx4 v[204:205], off
	v_lshl_add_u64 v[228:229], vcc, 0, v[164:165]
	s_mov_b32 m0, s63
	v_lshl_add_u64 v[230:231], s[82:83], 0, v[166:167]
	global_load_lds_dwordx4 v[228:229], off
	v_lshl_add_u64 v[228:229], vcc, 0, v[168:169]
	s_add_i32 m0, s63, 0x2000
	s_nop 0
	global_load_lds_dwordx4 v[228:229], off
	s_waitcnt vmcnt(6)
	s_waitcnt lgkmcnt(0)
	s_barrier
; #define PG8_STAGE(bufoff, gbase, voff) do { _Pragma("unroll") for (int _i = 0; _i < 2; ++_i) \
;         __builtin_amdgcn_global_load_lds((const unsigned*)((const char*)(gbase) + (voff)[_i]), (LAS unsigned*)(lds + (bufoff) + ldsw + _i * 8192), 16, 0, 0); } while (0)
; #define PG8_LDA(dst, b, h) do { _Pragma("unroll") for (int m = 0; m < 4; ++m) _Pragma("unroll") for (int k = 0; k < 2; ++k) dst[m][k] = *(const LAS bf16x8*)(lds + PG8_SA(b, h) + aoff + m * 2048 + k * 1024); } while (0)
; #define PG8_LDB(dst, b, h) do { _Pragma("unroll") for (int n = 0; n < 2; ++n) _Pragma("unroll") for (int k = 0; k < 2; ++k) dst[n][k] = *(const LAS bf16x8*)(lds + PG8_SB(b, h) + boff + n * 2048 + k * 1024); } while (0)
; #define PG8_MMA(ai, bj, At, Bt) do { __builtin_amdgcn_s_setprio(1); _Pragma("unroll") for (int m = 0; m < 4; ++m) _Pragma("unroll") for (int n = 0; n < 2; ++n) _Pragma("unroll") for (int k = 0; k < 2; ++k) \
;         acc[ai][bj][m][n] = __builtin_amdgcn_mfma_f32_16x16x32_bf16(Bt[n][k], At[m][k], acc[ai][bj][m][n], 0, 0, 0); __builtin_amdgcn_s_setprio(0); } while (0)
; #define PG8_WAIT_V(n) asm volatile("s_waitcnt vmcnt(" #n ")" ::: "memory")
; #define PG8_WAIT_L(n) asm volatile("s_waitcnt lgkmcnt(" #n ")" ::: "memory")
; #define PG8_BAR __builtin_amdgcn_s_barrier()
; #define PG8_SCHED __builtin_amdgcn_sched_barrier(0)
; template <class Epi, class Sched>
; DI void gemm_phase(LAS unsigned char* lds, const int K, const Sched& S, const Epi& E) {
;     ...
;             PG8_WAIT_V(8); PG8_WAIT_L(0); PG8_BAR; PG8_MMA(1, 0, At, B0); PG8_MMA(1, 1, At, B1); PG8_BAR; PG8_SCHED;
;             PG8_LDB(B0, 1, 0); PG8_LDB(B1, 1, 1); PG8_SCHED; PG8_LDA(At, 1, 0); PG8_STAGE(PG8_SA(0, 1), a2 + hstep, voffA);
;             PG8_WAIT_V(8); PG8_WAIT_L(0); PG8_BAR; PG8_MMA(0, 0, At, B0); PG8_MMA(0, 1, At, B1); PG8_BAR; PG8_SCHED;
	s_setprio 1
	s_waitcnt lgkmcnt(0)
	v_mfma_f32_16x16x32_bf16 v[62:65], v[130:133], v[174:177], v[62:65]
	v_mfma_f32_16x16x32_bf16 v[58:61], v[138:141], v[174:177], v[58:61]
	v_mfma_f32_16x16x32_bf16 v[46:49], v[130:133], v[190:193], v[46:49]
	v_mfma_f32_16x16x32_bf16 v[42:45], v[138:141], v[190:193], v[42:45]
	v_mfma_f32_16x16x32_bf16 v[30:33], v[130:133], v[212:215], v[30:33]
	v_mfma_f32_16x16x32_bf16 v[26:29], v[138:141], v[212:215], v[26:29]
	v_mfma_f32_16x16x32_bf16 v[14:17], v[130:133], v[220:223], v[14:17]
	v_mfma_f32_16x16x32_bf16 v[10:13], v[138:141], v[220:223], v[10:13]
	v_lshl_add_u64 v[228:229], s[82:83], 0, v[162:163]
	s_mov_b32 m0, s56
	s_nop 0
	global_load_lds_dwordx4 v[228:229], off
	v_mfma_f32_16x16x32_bf16 v[62:65], v[134:137], v[182:185], v[62:65]
	v_mfma_f32_16x16x32_bf16 v[58:61], v[142:145], v[182:185], v[58:61]
	v_mfma_f32_16x16x32_bf16 v[46:49], v[134:137], v[194:197], v[46:49]
	v_mfma_f32_16x16x32_bf16 v[42:45], v[142:145], v[194:197], v[42:45]
	v_mfma_f32_16x16x32_bf16 v[30:33], v[134:137], v[216:219], v[30:33]
	v_mfma_f32_16x16x32_bf16 v[26:29], v[142:145], v[216:219], v[26:29]
	v_mfma_f32_16x16x32_bf16 v[14:17], v[134:137], v[224:227], v[14:17]
	v_mfma_f32_16x16x32_bf16 v[10:13], v[142:145], v[224:227], v[10:13]
	s_setprio 0
	s_setprio 1
	v_mfma_f32_16x16x32_bf16 v[54:57], v[146:149], v[174:177], v[54:57]
	v_mfma_f32_16x16x32_bf16 v[50:53], v[154:157], v[174:177], v[50:53]
	v_mfma_f32_16x16x32_bf16 v[38:41], v[146:149], v[190:193], v[38:41]
	v_mfma_f32_16x16x32_bf16 v[34:37], v[154:157], v[190:193], v[34:37]
	v_mfma_f32_16x16x32_bf16 v[22:25], v[146:149], v[212:215], v[22:25]
	v_mfma_f32_16x16x32_bf16 v[18:21], v[154:157], v[212:215], v[18:21]
	v_mfma_f32_16x16x32_bf16 v[6:9], v[146:149], v[220:223], v[6:9]
	v_mfma_f32_16x16x32_bf16 v[2:5], v[154:157], v[220:223], v[2:5]
	s_mov_b32 m0, s57
	s_nop 0
	global_load_lds_dwordx4 v[230:231], off
	v_mfma_f32_16x16x32_bf16 v[54:57], v[150:153], v[182:185], v[54:57]
	v_mfma_f32_16x16x32_bf16 v[50:53], v[158:161], v[182:185], v[50:53]
	v_mfma_f32_16x16x32_bf16 v[38:41], v[150:153], v[194:197], v[38:41]
	v_mfma_f32_16x16x32_bf16 v[34:37], v[158:161], v[194:197], v[34:37]
	v_mfma_f32_16x16x32_bf16 v[22:25], v[150:153], v[216:219], v[22:25]
	v_mfma_f32_16x16x32_bf16 v[18:21], v[158:161], v[216:219], v[18:21]
	v_mfma_f32_16x16x32_bf16 v[6:9], v[150:153], v[224:227], v[6:9]
	v_mfma_f32_16x16x32_bf16 v[2:5], v[158:161], v[224:227], v[2:5]
	s_setprio 0
	s_barrier
	s_add_i32 s63, 0, 0x18000
	s_add_i32 vcc_lo, 0, 0x1c000
	v_add_u32_e32 v142, s63, v201
	v_add_u32_e32 v158, vcc_lo, v201
	ds_read_b128 v[130:133], v142
	ds_read_b128 v[134:137], v142 offset:1024
	ds_read_b128 v[138:141], v142 offset:2048
	ds_read_b128 v[142:145], v142 offset:3072
	ds_read_b128 v[146:149], v158
	ds_read_b128 v[150:153], v158 offset:1024
	ds_read_b128 v[154:157], v158 offset:2048
	ds_read_b128 v[158:161], v158 offset:3072
	s_add_u32 s82, s82, 0x40000
	s_addc_u32 s83, s83, 0
	s_mov_b32 m0, s58
	v_lshl_add_u64 v[232:233], s[82:83], 0, v[162:163]
	ds_read_b128 v[174:177], v202 offset:32768
	ds_read_b128 v[182:185], v202 offset:33792
	ds_read_b128 v[190:193], v202 offset:34816
	ds_read_b128 v[194:197], v202 offset:35840
	ds_read_b128 v[212:215], v202 offset:36864
	ds_read_b128 v[216:219], v202 offset:37888
	ds_read_b128 v[220:223], v202 offset:38912
	ds_read_b128 v[224:227], v202 offset:39936
	global_load_lds_dwordx4 v[232:233], off
	v_lshl_add_u64 v[232:233], s[82:83], 0, v[166:167]
	s_mov_b32 m0, s59
	s_nop 0
	global_load_lds_dwordx4 v[232:233], off
	s_waitcnt vmcnt(8)
	s_waitcnt lgkmcnt(0)
	s_barrier
	s_setprio 1
	s_waitcnt lgkmcnt(0)
	v_mfma_f32_16x16x32_bf16 v[126:129], v[130:133], v[174:177], v[126:129]
	v_mfma_f32_16x16x32_bf16 v[122:125], v[138:141], v[174:177], v[122:125]
	v_mfma_f32_16x16x32_bf16 v[110:113], v[130:133], v[190:193], v[110:113]
	v_mfma_f32_16x16x32_bf16 v[106:109], v[138:141], v[190:193], v[106:109]
	v_mfma_f32_16x16x32_bf16 v[94:97], v[130:133], v[212:215], v[94:97]
	v_mfma_f32_16x16x32_bf16 v[90:93], v[138:141], v[212:215], v[90:93]
	v_mfma_f32_16x16x32_bf16 v[78:81], v[130:133], v[220:223], v[78:81]
	v_mfma_f32_16x16x32_bf16 v[74:77], v[138:141], v[220:223], v[74:77]
	v_mfma_f32_16x16x32_bf16 v[126:129], v[134:137], v[182:185], v[126:129]
	v_mfma_f32_16x16x32_bf16 v[122:125], v[142:145], v[182:185], v[122:125]
	v_mfma_f32_16x16x32_bf16 v[110:113], v[134:137], v[194:197], v[110:113]
	v_mfma_f32_16x16x32_bf16 v[106:109], v[142:145], v[194:197], v[106:109]
	v_mfma_f32_16x16x32_bf16 v[94:97], v[134:137], v[216:219], v[94:97]
	v_mfma_f32_16x16x32_bf16 v[90:93], v[142:145], v[216:219], v[90:93]
	v_mfma_f32_16x16x32_bf16 v[78:81], v[134:137], v[224:227], v[78:81]
	v_mfma_f32_16x16x32_bf16 v[74:77], v[142:145], v[224:227], v[74:77]
	s_setprio 0
	s_setprio 1
	v_mfma_f32_16x16x32_bf16 v[118:121], v[146:149], v[174:177], v[118:121]
	v_mfma_f32_16x16x32_bf16 v[114:117], v[154:157], v[174:177], v[114:117]
	v_mfma_f32_16x16x32_bf16 v[102:105], v[146:149], v[190:193], v[102:105]
	v_mfma_f32_16x16x32_bf16 v[98:101], v[154:157], v[190:193], v[98:101]
	v_mfma_f32_16x16x32_bf16 v[86:89], v[146:149], v[212:215], v[86:89]
	v_mfma_f32_16x16x32_bf16 v[82:85], v[154:157], v[212:215], v[82:85]
	v_mfma_f32_16x16x32_bf16 v[70:73], v[146:149], v[220:223], v[70:73]
	v_mfma_f32_16x16x32_bf16 v[66:69], v[154:157], v[220:223], v[66:69]
	v_mfma_f32_16x16x32_bf16 v[118:121], v[150:153], v[182:185], v[118:121]
	v_mfma_f32_16x16x32_bf16 v[114:117], v[158:161], v[182:185], v[114:117]
	v_mfma_f32_16x16x32_bf16 v[102:105], v[150:153], v[194:197], v[102:105]
	v_mfma_f32_16x16x32_bf16 v[98:101], v[158:161], v[194:197], v[98:101]
	v_mfma_f32_16x16x32_bf16 v[86:89], v[150:153], v[216:219], v[86:89]
	v_mfma_f32_16x16x32_bf16 v[82:85], v[158:161], v[216:219], v[82:85]
	v_mfma_f32_16x16x32_bf16 v[70:73], v[150:153], v[224:227], v[70:73]
	v_mfma_f32_16x16x32_bf16 v[66:69], v[158:161], v[224:227], v[66:69]
	s_setprio 0
	s_barrier
; #define PG8_STAGE(bufoff, gbase, voff) do { _Pragma("unroll") for (int _i = 0; _i < 2; ++_i) \
;         __builtin_amdgcn_global_load_lds((const unsigned*)((const char*)(gbase) + (voff)[_i]), (LAS unsigned*)(lds + (bufoff) + ldsw + _i * 8192), 16, 0, 0); } while (0)
; #define PG8_LDA(dst, b, h) do { _Pragma("unroll") for (int m = 0; m < 4; ++m) _Pragma("unroll") for (int k = 0; k < 2; ++k) dst[m][k] = *(const LAS bf16x8*)(lds + PG8_SA(b, h) + aoff + m * 2048 + k * 1024); } while (0)
; #define PG8_MMA(ai, bj, At, Bt) do { __builtin_amdgcn_s_setprio(1); _Pragma("unroll") for (int m = 0; m < 4; ++m) _Pragma("unroll") for (int n = 0; n < 2; ++n) _Pragma("unroll") for (int k = 0; k < 2; ++k) \
;         acc[ai][bj][m][n] = __builtin_amdgcn_mfma_f32_16x16x32_bf16(Bt[n][k], At[m][k], acc[ai][bj][m][n], 0, 0, 0); __builtin_amdgcn_s_setprio(0); } while (0)
; #define PG8_WAIT_V(n) asm volatile("s_waitcnt vmcnt(" #n ")" ::: "memory")
; #define PG8_WAIT_L(n) asm volatile("s_waitcnt lgkmcnt(" #n ")" ::: "memory")
; #define PG8_BAR __builtin_amdgcn_s_barrier()
; #define PG8_SCHED __builtin_amdgcn_sched_barrier(0)
; template <class Epi, class Sched>
; DI void gemm_phase(LAS unsigned char* lds, const int K, const Sched& S, const Epi& E) {
;     ...
;             PG8_LDA(At, 1, 1); PG8_STAGE(PG8_SB(1, 0), b3, voffB); PG8_STAGE(PG8_SB(1, 1), b3 + hstep, voffB); PG8_STAGE(PG8_SA(1, 0), a3, voffA);
;             PG8_WAIT_V(8); PG8_WAIT_L(0); PG8_BAR; PG8_MMA(1, 0, At, B0); PG8_MMA(1, 1, At, B1); PG8_BAR; PG8_SCHED;
;         }
;         if (wr == 0) PG8_BAR;
	s_add_i32 s63, s63, s55
	v_lshl_add_u64 v[198:199], v[198:199], 0, s[90:91]
	s_mov_b32 m0, s63
	ds_read_b128 v[174:177], v202 offset:49152
	ds_read_b128 v[182:185], v202 offset:50176
	ds_read_b128 v[190:193], v202 offset:51200
	ds_read_b128 v[194:197], v202 offset:52224
	ds_read_b128 v[212:215], v202 offset:53248
	ds_read_b128 v[216:219], v202 offset:54272
	ds_read_b128 v[220:223], v202 offset:55296
	ds_read_b128 v[224:227], v202 offset:56320
	global_load_lds_dwordx4 v[198:199], off
	s_add_i32 m0, s63, 0x2000
	s_add_u32 s80, s80, 0x40080
	v_lshl_add_u64 v[198:199], v[204:205], 0, s[90:91]
	s_addc_u32 s81, s81, 0
	s_add_i32 s63, vcc_lo, s55
	global_load_lds_dwordx4 v[198:199], off
	v_lshl_add_u64 v[198:199], s[80:81], 0, v[164:165]
	s_mov_b32 m0, s63
	s_nop 0
	global_load_lds_dwordx4 v[198:199], off
	v_lshl_add_u64 v[198:199], s[80:81], 0, v[168:169]
	s_add_i32 m0, s63, 0x2000
	s_nop 0
	global_load_lds_dwordx4 v[198:199], off
	s_waitcnt vmcnt(6)
	s_waitcnt lgkmcnt(0)
	s_barrier
	s_setprio 1
	s_waitcnt lgkmcnt(0)
	v_mfma_f32_16x16x32_bf16 v[62:65], v[130:133], v[174:177], v[62:65]
	v_mfma_f32_16x16x32_bf16 v[58:61], v[138:141], v[174:177], v[58:61]
	v_mfma_f32_16x16x32_bf16 v[46:49], v[130:133], v[190:193], v[46:49]
	v_mfma_f32_16x16x32_bf16 v[42:45], v[138:141], v[190:193], v[42:45]
	v_mfma_f32_16x16x32_bf16 v[30:33], v[130:133], v[212:215], v[30:33]
	v_mfma_f32_16x16x32_bf16 v[26:29], v[138:141], v[212:215], v[26:29]
	v_mfma_f32_16x16x32_bf16 v[14:17], v[130:133], v[220:223], v[14:17]
	v_mfma_f32_16x16x32_bf16 v[10:13], v[138:141], v[220:223], v[10:13]
	v_lshl_add_u64 v[198:199], v[228:229], 0, s[90:91]
	s_mov_b32 m0, s47
	s_nop 0
	global_load_lds_dwordx4 v[198:199], off
	v_mfma_f32_16x16x32_bf16 v[62:65], v[134:137], v[182:185], v[62:65]
	v_mfma_f32_16x16x32_bf16 v[58:61], v[142:145], v[182:185], v[58:61]
	v_mfma_f32_16x16x32_bf16 v[46:49], v[134:137], v[194:197], v[46:49]
	v_mfma_f32_16x16x32_bf16 v[42:45], v[142:145], v[194:197], v[42:45]
	v_mfma_f32_16x16x32_bf16 v[30:33], v[134:137], v[216:219], v[30:33]
	v_mfma_f32_16x16x32_bf16 v[26:29], v[142:145], v[216:219], v[26:29]
	v_mfma_f32_16x16x32_bf16 v[14:17], v[134:137], v[224:227], v[14:17]
	v_mfma_f32_16x16x32_bf16 v[10:13], v[142:145], v[224:227], v[10:13]
	s_setprio 0
	s_setprio 1
	v_mfma_f32_16x16x32_bf16 v[54:57], v[146:149], v[174:177], v[54:57]
	v_mfma_f32_16x16x32_bf16 v[50:53], v[154:157], v[174:177], v[50:53]
	v_mfma_f32_16x16x32_bf16 v[38:41], v[146:149], v[190:193], v[38:41]
	v_mfma_f32_16x16x32_bf16 v[34:37], v[154:157], v[190:193], v[34:37]
	v_mfma_f32_16x16x32_bf16 v[22:25], v[146:149], v[212:215], v[22:25]
	v_mfma_f32_16x16x32_bf16 v[18:21], v[154:157], v[212:215], v[18:21]
	v_mfma_f32_16x16x32_bf16 v[6:9], v[146:149], v[220:223], v[6:9]
	v_mfma_f32_16x16x32_bf16 v[2:5], v[154:157], v[220:223], v[2:5]
	v_lshl_add_u64 v[198:199], v[230:231], 0, s[90:91]
	s_mov_b32 m0, s62
	s_nop 0
	global_load_lds_dwordx4 v[198:199], off
	v_mfma_f32_16x16x32_bf16 v[54:57], v[150:153], v[182:185], v[54:57]
	v_mfma_f32_16x16x32_bf16 v[50:53], v[158:161], v[182:185], v[50:53]
	v_mfma_f32_16x16x32_bf16 v[38:41], v[150:153], v[194:197], v[38:41]
	v_mfma_f32_16x16x32_bf16 v[34:37], v[158:161], v[194:197], v[34:37]
	v_mfma_f32_16x16x32_bf16 v[22:25], v[150:153], v[216:219], v[22:25]
	v_mfma_f32_16x16x32_bf16 v[18:21], v[158:161], v[216:219], v[18:21]
	v_mfma_f32_16x16x32_bf16 v[6:9], v[150:153], v[224:227], v[6:9]
	v_mfma_f32_16x16x32_bf16 v[2:5], v[158:161], v[224:227], v[2:5]
	s_setprio 0
	s_barrier
	s_add_i32 s87, s87, 2
	s_add_u32 s85, s85, 0x100
	s_addc_u32 s86, s86, 0
	s_add_u32 s78, s78, 0x100
	s_addc_u32 s79, s79, 0
	s_cmp_gt_u32 s87, 13
	s_cbranch_scc0 .LBB0_218
	s_and_b64 vcc, exec, s[50:51]
	s_cbranch_vccz .LBB0_221
	s_barrier

; #define PG8_STAGE(bufoff, gbase, voff) do { _Pragma("unroll") for (int _i = 0; _i < 2; ++_i) \
;         __builtin_amdgcn_global_load_lds((const unsigned*)((const char*)(gbase) + (voff)[_i]), (LAS unsigned*)(lds + (bufoff) + ldsw + _i * 8192), 16, 0, 0); } while (0)
; #define PG8_LDA(dst, b, h) do { _Pragma("unroll") for (int m = 0; m < 4; ++m) _Pragma("unroll") for (int k = 0; k < 2; ++k) dst[m][k] = *(const LAS bf16x8*)(lds + PG8_SA(b, h) + aoff + m * 2048 + k * 1024); } while (0)
; #define PG8_LDB(dst, b, h) do { _Pragma("unroll") for (int n = 0; n < 2; ++n) _Pragma("unroll") for (int k = 0; k < 2; ++k) dst[n][k] = *(const LAS bf16x8*)(lds + PG8_SB(b, h) + boff + n * 2048 + k * 1024); } while (0)
; #define PG8_MMA(ai, bj, At, Bt) do { __builtin_amdgcn_s_setprio(1); _Pragma("unroll") for (int m = 0; m < 4; ++m) _Pragma("unroll") for (int n = 0; n < 2; ++n) _Pragma("unroll") for (int k = 0; k < 2; ++k) \
;         acc[ai][bj][m][n] = __builtin_amdgcn_mfma_f32_16x16x32_bf16(Bt[n][k], At[m][k], acc[ai][bj][m][n], 0, 0, 0); __builtin_amdgcn_s_setprio(0); } while (0)
; #define PG8_WAIT_V(n) asm volatile("s_waitcnt vmcnt(" #n ")" ::: "memory")
; #define PG8_WAIT_L(n) asm volatile("s_waitcnt lgkmcnt(" #n ")" ::: "memory")
; #define PG8_BAR __builtin_amdgcn_s_barrier()
; #define PG8_SCHED __builtin_amdgcn_sched_barrier(0)
; template <class Epi, class Sched>
; DI void gemm_phase(LAS unsigned char* lds, const int K, const Sched& S, const Epi& E) {
;     ...
;             const bool last = (t == nt - 2);
;             const char* a1 = cA + (size_t)(t + 1) * kstep;
;             const char* a2 = last ? nA : cA + (size_t)(t + 2) * kstep; const char* b2 = last ? nB : cB + (size_t)(t + 2) * kstep;
;             const char* a3 = a2 + kstep; const char* b3 = b2 + kstep;
;             PG8_LDB(B0, 0, 0); PG8_LDB(B1, 0, 1); PG8_SCHED; PG8_LDA(At, 0, 0); PG8_STAGE(PG8_SA(1, 1), a1 + hstep, voffA);
;             PG8_WAIT_V(8); PG8_WAIT_L(0); PG8_BAR; PG8_MMA(0, 0, At, B0); PG8_MMA(0, 1, At, B1); PG8_BAR; PG8_SCHED;
;             PG8_LDA(At, 0, 1); PG8_STAGE(PG8_SB(0, 0), b2, voffB); PG8_STAGE(PG8_SB(0, 1), b2 + hstep, voffB); PG8_STAGE(PG8_SA(0, 0), a2, voffA);
;             PG8_WAIT_V(8); PG8_WAIT_L(0); PG8_BAR; PG8_MMA(1, 0, At, B0); PG8_MMA(1, 1, At, B1); PG8_BAR; PG8_SCHED;
.LBB0_338:
	s_add_u32 s58, s56, 0xfffc0080
	s_addc_u32 s59, s57, -1
	s_add_i32 s79, 0, 0x10000
	s_cmp_eq_u32 s78, 12
	s_cselect_b32 s61, s53, s59
	s_cselect_b32 s60, s52, s58
	v_add_u32_e32 v142, s79, v145
	s_cselect_b32 s59, s55, s51
	s_cselect_b32 s58, s54, s49
	s_add_i32 s82, 0, 0x14000
	ds_read_b128 v[148:151], v142
	ds_read_b128 v[152:155], v142 offset:1024
	ds_read_b128 v[156:159], v142 offset:2048
	ds_read_b128 v[160:163], v142 offset:3072
	v_add_u32_e32 v142, s82, v145
	ds_read_b128 v[164:167], v142
	ds_read_b128 v[168:171], v142 offset:1024
	ds_read_b128 v[172:175], v142 offset:2048
	ds_read_b128 v[182:185], v142 offset:3072
	v_lshl_add_u64 v[142:143], s[56:57], 0, v[140:141]
	s_add_i32 m0, s67, 0xc000
	ds_read_b128 v[190:193], v146
	ds_read_b128 v[194:197], v146 offset:1024
	ds_read_b128 v[198:201], v146 offset:2048
	ds_read_b128 v[202:205], v146 offset:3072
	ds_read_b128 v[212:215], v146 offset:4096
	ds_read_b128 v[216:219], v146 offset:5120
	ds_read_b128 v[220:223], v146 offset:6144
	ds_read_b128 v[224:227], v146 offset:7168
	global_load_lds_dwordx4 v[142:143], off
	v_lshl_add_u64 v[142:143], s[56:57], 0, v[138:139]
	s_add_i32 m0, s67, 0xe000
	s_nop 0
	global_load_lds_dwordx4 v[142:143], off
	s_waitcnt vmcnt(8)
	s_waitcnt lgkmcnt(0)
	s_barrier
	s_setprio 1
	s_waitcnt lgkmcnt(0)
	v_mfma_f32_16x16x32_bf16 v[126:129], v[148:151], v[190:193], v[126:129]
	v_mfma_f32_16x16x32_bf16 v[122:125], v[156:159], v[190:193], v[122:125]
	v_mfma_f32_16x16x32_bf16 v[110:113], v[148:151], v[198:201], v[110:113]
	v_mfma_f32_16x16x32_bf16 v[106:109], v[156:159], v[198:201], v[106:109]
	v_mfma_f32_16x16x32_bf16 v[94:97], v[148:151], v[212:215], v[94:97]
	v_mfma_f32_16x16x32_bf16 v[90:93], v[156:159], v[212:215], v[90:93]
	v_mfma_f32_16x16x32_bf16 v[78:81], v[148:151], v[220:223], v[78:81]
	v_mfma_f32_16x16x32_bf16 v[74:77], v[156:159], v[220:223], v[74:77]
	v_mfma_f32_16x16x32_bf16 v[126:129], v[152:155], v[194:197], v[126:129]
	v_mfma_f32_16x16x32_bf16 v[122:125], v[160:163], v[194:197], v[122:125]
	v_mfma_f32_16x16x32_bf16 v[110:113], v[152:155], v[202:205], v[110:113]
	v_mfma_f32_16x16x32_bf16 v[106:109], v[160:163], v[202:205], v[106:109]
	v_mfma_f32_16x16x32_bf16 v[94:97], v[152:155], v[216:219], v[94:97]
	v_mfma_f32_16x16x32_bf16 v[90:93], v[160:163], v[216:219], v[90:93]
	v_mfma_f32_16x16x32_bf16 v[78:81], v[152:155], v[224:227], v[78:81]
	v_mfma_f32_16x16x32_bf16 v[74:77], v[160:163], v[224:227], v[74:77]
	s_setprio 0
	s_setprio 1
	v_mfma_f32_16x16x32_bf16 v[118:121], v[164:167], v[190:193], v[118:121]
	v_mfma_f32_16x16x32_bf16 v[114:117], v[172:175], v[190:193], v[114:117]
	v_mfma_f32_16x16x32_bf16 v[102:105], v[164:167], v[198:201], v[102:105]
	v_mfma_f32_16x16x32_bf16 v[98:101], v[172:175], v[198:201], v[98:101]
	v_mfma_f32_16x16x32_bf16 v[86:89], v[164:167], v[212:215], v[86:89]
	v_mfma_f32_16x16x32_bf16 v[82:85], v[172:175], v[212:215], v[82:85]
	v_mfma_f32_16x16x32_bf16 v[70:73], v[164:167], v[220:223], v[70:73]
	v_mfma_f32_16x16x32_bf16 v[66:69], v[172:175], v[220:223], v[66:69]
	v_mfma_f32_16x16x32_bf16 v[118:121], v[168:171], v[194:197], v[118:121]
	v_mfma_f32_16x16x32_bf16 v[114:117], v[182:185], v[194:197], v[114:117]
	v_mfma_f32_16x16x32_bf16 v[102:105], v[168:171], v[202:205], v[102:105]
	v_mfma_f32_16x16x32_bf16 v[98:101], v[182:185], v[202:205], v[98:101]
	v_mfma_f32_16x16x32_bf16 v[86:89], v[168:171], v[216:219], v[86:89]
	v_mfma_f32_16x16x32_bf16 v[82:85], v[182:185], v[216:219], v[82:85]
	v_mfma_f32_16x16x32_bf16 v[70:73], v[168:171], v[224:227], v[70:73]
	v_mfma_f32_16x16x32_bf16 v[66:69], v[182:185], v[224:227], v[66:69]
	s_setprio 0
	s_barrier
	s_add_i32 s79, s79, s66
	v_lshl_add_u64 v[142:143], s[58:59], 0, v[134:135]
	s_mov_b32 m0, s79
	ds_read_b128 v[190:193], v146 offset:16384
	ds_read_b128 v[194:197], v146 offset:17408
	ds_read_b128 v[198:201], v146 offset:18432
	ds_read_b128 v[202:205], v146 offset:19456
	ds_read_b128 v[212:215], v146 offset:20480
	ds_read_b128 v[216:219], v146 offset:21504
	ds_read_b128 v[220:223], v146 offset:22528
	ds_read_b128 v[224:227], v146 offset:23552
	global_load_lds_dwordx4 v[142:143], off
	s_add_i32 m0, s79, 0x2000
	s_add_u32 s80, s58, 0x40000
	v_lshl_add_u64 v[176:177], s[58:59], 0, v[130:131]
	s_addc_u32 s81, s59, 0
	s_add_i32 s79, s82, s66
	global_load_lds_dwordx4 v[176:177], off
	v_lshl_add_u64 v[228:229], s[80:81], 0, v[134:135]
	s_mov_b32 m0, s79
	v_lshl_add_u64 v[230:231], s[60:61], 0, v[132:133]
	global_load_lds_dwordx4 v[228:229], off
	v_lshl_add_u64 v[228:229], s[80:81], 0, v[130:131]
	s_add_i32 m0, s79, 0x2000
	s_nop 0
	global_load_lds_dwordx4 v[228:229], off
	s_waitcnt vmcnt(6)
	s_waitcnt lgkmcnt(0)
	s_barrier
; #define PG8_STAGE(bufoff, gbase, voff) do { _Pragma("unroll") for (int _i = 0; _i < 2; ++_i) \
;         __builtin_amdgcn_global_load_lds((const unsigned*)((const char*)(gbase) + (voff)[_i]), (LAS unsigned*)(lds + (bufoff) + ldsw + _i * 8192), 16, 0, 0); } while (0)
; #define PG8_LDA(dst, b, h) do { _Pragma("unroll") for (int m = 0; m < 4; ++m) _Pragma("unroll") for (int k = 0; k < 2; ++k) dst[m][k] = *(const LAS bf16x8*)(lds + PG8_SA(b, h) + aoff + m * 2048 + k * 1024); } while (0)
; #define PG8_LDB(dst, b, h) do { _Pragma("unroll") for (int n = 0; n < 2; ++n) _Pragma("unroll") for (int k = 0; k < 2; ++k) dst[n][k] = *(const LAS bf16x8*)(lds + PG8_SB(b, h) + boff + n * 2048 + k * 1024); } while (0)
; #define PG8_MMA(ai, bj, At, Bt) do { __builtin_amdgcn_s_setprio(1); _Pragma("unroll") for (int m = 0; m < 4; ++m) _Pragma("unroll") for (int n = 0; n < 2; ++n) _Pragma("unroll") for (int k = 0; k < 2; ++k) \
;         acc[ai][bj][m][n] = __builtin_amdgcn_mfma_f32_16x16x32_bf16(Bt[n][k], At[m][k], acc[ai][bj][m][n], 0, 0, 0); __builtin_amdgcn_s_setprio(0); } while (0)
; #define PG8_WAIT_V(n) asm volatile("s_waitcnt vmcnt(" #n ")" ::: "memory")
; #define PG8_WAIT_L(n) asm volatile("s_waitcnt lgkmcnt(" #n ")" ::: "memory")
; #define PG8_BAR __builtin_amdgcn_s_barrier()
; #define PG8_SCHED __builtin_amdgcn_sched_barrier(0)
; template <class Epi, class Sched>
; DI void gemm_phase(LAS unsigned char* lds, const int K, const Sched& S, const Epi& E) {
;     ...
;             PG8_WAIT_V(8); PG8_WAIT_L(0); PG8_BAR; PG8_MMA(1, 0, At, B0); PG8_MMA(1, 1, At, B1); PG8_BAR; PG8_SCHED;
;             PG8_LDB(B0, 1, 0); PG8_LDB(B1, 1, 1); PG8_SCHED; PG8_LDA(At, 1, 0); PG8_STAGE(PG8_SA(0, 1), a2 + hstep, voffA);
;             PG8_WAIT_V(8); PG8_WAIT_L(0); PG8_BAR; PG8_MMA(0, 0, At, B0); PG8_MMA(0, 1, At, B1); PG8_BAR; PG8_SCHED;
	s_setprio 1
	s_waitcnt lgkmcnt(0)
	v_mfma_f32_16x16x32_bf16 v[62:65], v[148:151], v[190:193], v[62:65]
	v_mfma_f32_16x16x32_bf16 v[58:61], v[156:159], v[190:193], v[58:61]
	v_mfma_f32_16x16x32_bf16 v[46:49], v[148:151], v[198:201], v[46:49]
	v_mfma_f32_16x16x32_bf16 v[42:45], v[156:159], v[198:201], v[42:45]
	v_mfma_f32_16x16x32_bf16 v[30:33], v[148:151], v[212:215], v[30:33]
	v_mfma_f32_16x16x32_bf16 v[26:29], v[156:159], v[212:215], v[26:29]
	v_mfma_f32_16x16x32_bf16 v[14:17], v[148:151], v[220:223], v[14:17]
	v_mfma_f32_16x16x32_bf16 v[10:13], v[156:159], v[220:223], v[10:13]
	v_lshl_add_u64 v[228:229], s[60:61], 0, v[136:137]
	s_mov_b32 m0, s67
	s_nop 0
	global_load_lds_dwordx4 v[228:229], off
	v_mfma_f32_16x16x32_bf16 v[62:65], v[152:155], v[194:197], v[62:65]
	v_mfma_f32_16x16x32_bf16 v[58:61], v[160:163], v[194:197], v[58:61]
	v_mfma_f32_16x16x32_bf16 v[46:49], v[152:155], v[202:205], v[46:49]
	v_mfma_f32_16x16x32_bf16 v[42:45], v[160:163], v[202:205], v[42:45]
	v_mfma_f32_16x16x32_bf16 v[30:33], v[152:155], v[216:219], v[30:33]
	v_mfma_f32_16x16x32_bf16 v[26:29], v[160:163], v[216:219], v[26:29]
	v_mfma_f32_16x16x32_bf16 v[14:17], v[152:155], v[224:227], v[14:17]
	v_mfma_f32_16x16x32_bf16 v[10:13], v[160:163], v[224:227], v[10:13]
	s_setprio 0
	s_setprio 1
	v_mfma_f32_16x16x32_bf16 v[54:57], v[164:167], v[190:193], v[54:57]
	v_mfma_f32_16x16x32_bf16 v[50:53], v[172:175], v[190:193], v[50:53]
	v_mfma_f32_16x16x32_bf16 v[38:41], v[164:167], v[198:201], v[38:41]
	v_mfma_f32_16x16x32_bf16 v[34:37], v[172:175], v[198:201], v[34:37]
	v_mfma_f32_16x16x32_bf16 v[22:25], v[164:167], v[212:215], v[22:25]
	v_mfma_f32_16x16x32_bf16 v[18:21], v[172:175], v[212:215], v[18:21]
	v_mfma_f32_16x16x32_bf16 v[6:9], v[164:167], v[220:223], v[6:9]
	v_mfma_f32_16x16x32_bf16 v[2:5], v[172:175], v[220:223], v[2:5]
	s_mov_b32 m0, s68
	s_nop 0
	global_load_lds_dwordx4 v[230:231], off
	v_mfma_f32_16x16x32_bf16 v[54:57], v[168:171], v[194:197], v[54:57]
	v_mfma_f32_16x16x32_bf16 v[50:53], v[182:185], v[194:197], v[50:53]
	v_mfma_f32_16x16x32_bf16 v[38:41], v[168:171], v[202:205], v[38:41]
	v_mfma_f32_16x16x32_bf16 v[34:37], v[182:185], v[202:205], v[34:37]
	v_mfma_f32_16x16x32_bf16 v[22:25], v[168:171], v[216:219], v[22:25]
	v_mfma_f32_16x16x32_bf16 v[18:21], v[182:185], v[216:219], v[18:21]
	v_mfma_f32_16x16x32_bf16 v[6:9], v[168:171], v[224:227], v[6:9]
	v_mfma_f32_16x16x32_bf16 v[2:5], v[182:185], v[224:227], v[2:5]
	s_setprio 0
	s_barrier
	s_add_i32 s79, 0, 0x18000
	v_add_u32_e32 v147, s79, v145
	s_add_i32 s80, 0, 0x1c000
	ds_read_b128 v[148:151], v147
	ds_read_b128 v[152:155], v147 offset:1024
	ds_read_b128 v[156:159], v147 offset:2048
	ds_read_b128 v[160:163], v147 offset:3072
	v_add_u32_e32 v147, s80, v145
	ds_read_b128 v[164:167], v147
	ds_read_b128 v[168:171], v147 offset:1024
	ds_read_b128 v[172:175], v147 offset:2048
	ds_read_b128 v[182:185], v147 offset:3072
	s_add_u32 s60, s60, 0x40000
	s_addc_u32 s61, s61, 0
	s_mov_b32 m0, s69
	v_lshl_add_u64 v[232:233], s[60:61], 0, v[136:137]
	ds_read_b128 v[190:193], v146 offset:32768
	ds_read_b128 v[194:197], v146 offset:33792
	ds_read_b128 v[198:201], v146 offset:34816
	ds_read_b128 v[202:205], v146 offset:35840
	ds_read_b128 v[212:215], v146 offset:36864
	ds_read_b128 v[216:219], v146 offset:37888
	ds_read_b128 v[220:223], v146 offset:38912
	ds_read_b128 v[224:227], v146 offset:39936
	global_load_lds_dwordx4 v[232:233], off
	v_lshl_add_u64 v[232:233], s[60:61], 0, v[132:133]
	s_mov_b32 m0, s70
	s_nop 0
	global_load_lds_dwordx4 v[232:233], off
	s_waitcnt vmcnt(8)
	s_waitcnt lgkmcnt(0)
	s_barrier
	s_setprio 1
	s_waitcnt lgkmcnt(0)
	v_mfma_f32_16x16x32_bf16 v[126:129], v[148:151], v[190:193], v[126:129]
	v_mfma_f32_16x16x32_bf16 v[122:125], v[156:159], v[190:193], v[122:125]
	v_mfma_f32_16x16x32_bf16 v[110:113], v[148:151], v[198:201], v[110:113]
	v_mfma_f32_16x16x32_bf16 v[106:109], v[156:159], v[198:201], v[106:109]
	v_mfma_f32_16x16x32_bf16 v[94:97], v[148:151], v[212:215], v[94:97]
	v_mfma_f32_16x16x32_bf16 v[90:93], v[156:159], v[212:215], v[90:93]
	v_mfma_f32_16x16x32_bf16 v[78:81], v[148:151], v[220:223], v[78:81]
	v_mfma_f32_16x16x32_bf16 v[74:77], v[156:159], v[220:223], v[74:77]
	v_mfma_f32_16x16x32_bf16 v[126:129], v[152:155], v[194:197], v[126:129]
	v_mfma_f32_16x16x32_bf16 v[122:125], v[160:163], v[194:197], v[122:125]
	v_mfma_f32_16x16x32_bf16 v[110:113], v[152:155], v[202:205], v[110:113]
	v_mfma_f32_16x16x32_bf16 v[106:109], v[160:163], v[202:205], v[106:109]
	v_mfma_f32_16x16x32_bf16 v[94:97], v[152:155], v[216:219], v[94:97]
	v_mfma_f32_16x16x32_bf16 v[90:93], v[160:163], v[216:219], v[90:93]
	v_mfma_f32_16x16x32_bf16 v[78:81], v[152:155], v[224:227], v[78:81]
	v_mfma_f32_16x16x32_bf16 v[74:77], v[160:163], v[224:227], v[74:77]
	s_setprio 0
	s_setprio 1
	v_mfma_f32_16x16x32_bf16 v[118:121], v[164:167], v[190:193], v[118:121]
	v_mfma_f32_16x16x32_bf16 v[114:117], v[172:175], v[190:193], v[114:117]
	v_mfma_f32_16x16x32_bf16 v[102:105], v[164:167], v[198:201], v[102:105]
	v_mfma_f32_16x16x32_bf16 v[98:101], v[172:175], v[198:201], v[98:101]
	v_mfma_f32_16x16x32_bf16 v[86:89], v[164:167], v[212:215], v[86:89]
	v_mfma_f32_16x16x32_bf16 v[82:85], v[172:175], v[212:215], v[82:85]
	v_mfma_f32_16x16x32_bf16 v[70:73], v[164:167], v[220:223], v[70:73]
	v_mfma_f32_16x16x32_bf16 v[66:69], v[172:175], v[220:223], v[66:69]
	v_mfma_f32_16x16x32_bf16 v[118:121], v[168:171], v[194:197], v[118:121]
	v_mfma_f32_16x16x32_bf16 v[114:117], v[182:185], v[194:197], v[114:117]
	v_mfma_f32_16x16x32_bf16 v[102:105], v[168:171], v[202:205], v[102:105]
	v_mfma_f32_16x16x32_bf16 v[98:101], v[182:185], v[202:205], v[98:101]
	v_mfma_f32_16x16x32_bf16 v[86:89], v[168:171], v[216:219], v[86:89]
	v_mfma_f32_16x16x32_bf16 v[82:85], v[182:185], v[216:219], v[82:85]
	v_mfma_f32_16x16x32_bf16 v[70:73], v[168:171], v[224:227], v[70:73]
	v_mfma_f32_16x16x32_bf16 v[66:69], v[182:185], v[224:227], v[66:69]
	s_setprio 0
	s_barrier
; #define PG8_STAGE(bufoff, gbase, voff) do { _Pragma("unroll") for (int _i = 0; _i < 2; ++_i) \
;         __builtin_amdgcn_global_load_lds((const unsigned*)((const char*)(gbase) + (voff)[_i]), (LAS unsigned*)(lds + (bufoff) + ldsw + _i * 8192), 16, 0, 0); } while (0)
; #define PG8_LDA(dst, b, h) do { _Pragma("unroll") for (int m = 0; m < 4; ++m) _Pragma("unroll") for (int k = 0; k < 2; ++k) dst[m][k] = *(const LAS bf16x8*)(lds + PG8_SA(b, h) + aoff + m * 2048 + k * 1024); } while (0)
; #define PG8_MMA(ai, bj, At, Bt) do { __builtin_amdgcn_s_setprio(1); _Pragma("unroll") for (int m = 0; m < 4; ++m) _Pragma("unroll") for (int n = 0; n < 2; ++n) _Pragma("unroll") for (int k = 0; k < 2; ++k) \
;         acc[ai][bj][m][n] = __builtin_amdgcn_mfma_f32_16x16x32_bf16(Bt[n][k], At[m][k], acc[ai][bj][m][n], 0, 0, 0); __builtin_amdgcn_s_setprio(0); } while (0)
; #define PG8_WAIT_V(n) asm volatile("s_waitcnt vmcnt(" #n ")" ::: "memory")
; #define PG8_WAIT_L(n) asm volatile("s_waitcnt lgkmcnt(" #n ")" ::: "memory")
; #define PG8_BAR __builtin_amdgcn_s_barrier()
; #define PG8_SCHED __builtin_amdgcn_sched_barrier(0)
; template <class Epi, class Sched>
; DI void gemm_phase(LAS unsigned char* lds, const int K, const Sched& S, const Epi& E) {
;     ...
;             PG8_LDA(At, 1, 1); PG8_STAGE(PG8_SB(1, 0), b3, voffB); PG8_STAGE(PG8_SB(1, 1), b3 + hstep, voffB); PG8_STAGE(PG8_SA(1, 0), a3, voffA);
;             PG8_WAIT_V(8); PG8_WAIT_L(0); PG8_BAR; PG8_MMA(1, 0, At, B0); PG8_MMA(1, 1, At, B1); PG8_BAR; PG8_SCHED;
;         }
;         if (wr == 0) PG8_BAR;
	s_add_i32 s60, s79, s66
	v_lshl_add_u64 v[142:143], v[142:143], 0, s[90:91]
	s_mov_b32 m0, s60
	ds_read_b128 v[190:193], v146 offset:49152
	ds_read_b128 v[194:197], v146 offset:50176
	ds_read_b128 v[198:201], v146 offset:51200
	ds_read_b128 v[202:205], v146 offset:52224
	ds_read_b128 v[212:215], v146 offset:53248
	ds_read_b128 v[216:219], v146 offset:54272
	ds_read_b128 v[220:223], v146 offset:55296
	ds_read_b128 v[224:227], v146 offset:56320
	global_load_lds_dwordx4 v[142:143], off
	s_add_i32 m0, s60, 0x2000
	s_add_u32 s58, s58, 0x40080
	v_lshl_add_u64 v[142:143], v[176:177], 0, s[90:91]
	s_addc_u32 s59, s59, 0
	s_add_i32 s60, s80, s66
	global_load_lds_dwordx4 v[142:143], off
	v_lshl_add_u64 v[142:143], s[58:59], 0, v[134:135]
	s_mov_b32 m0, s60
	s_nop 0
	global_load_lds_dwordx4 v[142:143], off
	v_lshl_add_u64 v[142:143], s[58:59], 0, v[130:131]
	s_add_i32 m0, s60, 0x2000
	s_nop 0
	global_load_lds_dwordx4 v[142:143], off
	s_waitcnt vmcnt(6)
	s_waitcnt lgkmcnt(0)
	s_barrier
	s_setprio 1
	s_waitcnt lgkmcnt(0)
	v_mfma_f32_16x16x32_bf16 v[62:65], v[148:151], v[190:193], v[62:65]
	v_mfma_f32_16x16x32_bf16 v[58:61], v[156:159], v[190:193], v[58:61]
	v_mfma_f32_16x16x32_bf16 v[46:49], v[148:151], v[198:201], v[46:49]
	v_mfma_f32_16x16x32_bf16 v[42:45], v[156:159], v[198:201], v[42:45]
	v_mfma_f32_16x16x32_bf16 v[30:33], v[148:151], v[212:215], v[30:33]
	v_mfma_f32_16x16x32_bf16 v[26:29], v[156:159], v[212:215], v[26:29]
	v_mfma_f32_16x16x32_bf16 v[14:17], v[148:151], v[220:223], v[14:17]
	v_mfma_f32_16x16x32_bf16 v[10:13], v[156:159], v[220:223], v[10:13]
	v_lshl_add_u64 v[142:143], v[228:229], 0, s[90:91]
	s_mov_b32 m0, s73
	s_nop 0
	global_load_lds_dwordx4 v[142:143], off
	v_mfma_f32_16x16x32_bf16 v[62:65], v[152:155], v[194:197], v[62:65]
	v_mfma_f32_16x16x32_bf16 v[58:61], v[160:163], v[194:197], v[58:61]
	v_mfma_f32_16x16x32_bf16 v[46:49], v[152:155], v[202:205], v[46:49]
	v_mfma_f32_16x16x32_bf16 v[42:45], v[160:163], v[202:205], v[42:45]
	v_mfma_f32_16x16x32_bf16 v[30:33], v[152:155], v[216:219], v[30:33]
	v_mfma_f32_16x16x32_bf16 v[26:29], v[160:163], v[216:219], v[26:29]
	v_mfma_f32_16x16x32_bf16 v[14:17], v[152:155], v[224:227], v[14:17]
	v_mfma_f32_16x16x32_bf16 v[10:13], v[160:163], v[224:227], v[10:13]
	s_setprio 0
	s_setprio 1
	v_mfma_f32_16x16x32_bf16 v[54:57], v[164:167], v[190:193], v[54:57]
	v_mfma_f32_16x16x32_bf16 v[50:53], v[172:175], v[190:193], v[50:53]
	v_mfma_f32_16x16x32_bf16 v[38:41], v[164:167], v[198:201], v[38:41]
	v_mfma_f32_16x16x32_bf16 v[34:37], v[172:175], v[198:201], v[34:37]
	v_mfma_f32_16x16x32_bf16 v[22:25], v[164:167], v[212:215], v[22:25]
	v_mfma_f32_16x16x32_bf16 v[18:21], v[172:175], v[212:215], v[18:21]
	v_mfma_f32_16x16x32_bf16 v[6:9], v[164:167], v[220:223], v[6:9]
	v_mfma_f32_16x16x32_bf16 v[2:5], v[172:175], v[220:223], v[2:5]
	v_lshl_add_u64 v[142:143], v[230:231], 0, s[90:91]
	s_mov_b32 m0, s74
	s_nop 0
	global_load_lds_dwordx4 v[142:143], off
	v_mfma_f32_16x16x32_bf16 v[54:57], v[168:171], v[194:197], v[54:57]
	v_mfma_f32_16x16x32_bf16 v[50:53], v[182:185], v[194:197], v[50:53]
	v_mfma_f32_16x16x32_bf16 v[38:41], v[168:171], v[202:205], v[38:41]
	v_mfma_f32_16x16x32_bf16 v[34:37], v[182:185], v[202:205], v[34:37]
	v_mfma_f32_16x16x32_bf16 v[22:25], v[168:171], v[216:219], v[22:25]
	v_mfma_f32_16x16x32_bf16 v[18:21], v[182:185], v[216:219], v[18:21]
	v_mfma_f32_16x16x32_bf16 v[6:9], v[168:171], v[224:227], v[6:9]
	v_mfma_f32_16x16x32_bf16 v[2:5], v[182:185], v[224:227], v[2:5]
	s_setprio 0
	s_barrier
	s_add_i32 s78, s78, 2
	s_add_u32 s49, s49, 0x100
	s_addc_u32 s51, s51, 0
	s_add_u32 s56, s56, 0x100
	s_addc_u32 s57, s57, 0
	s_cmp_gt_u32 s78, 13
	s_cbranch_scc0 .LBB0_338
	s_and_b64 vcc, exec, s[44:45]
	s_cbranch_vccz .LBB0_341
	s_barrier

; #define PG8_STAGE(bufoff, gbase, voff) do { _Pragma("unroll") for (int _i = 0; _i < 2; ++_i) \
;         __builtin_amdgcn_global_load_lds((const unsigned*)((const char*)(gbase) + (voff)[_i]), (LAS unsigned*)(lds + (bufoff) + ldsw + _i * 8192), 16, 0, 0); } while (0)
; #define PG8_LDA(dst, b, h) do { _Pragma("unroll") for (int m = 0; m < 4; ++m) _Pragma("unroll") for (int k = 0; k < 2; ++k) dst[m][k] = *(const LAS bf16x8*)(lds + PG8_SA(b, h) + aoff + m * 2048 + k * 1024); } while (0)
; #define PG8_LDB(dst, b, h) do { _Pragma("unroll") for (int n = 0; n < 2; ++n) _Pragma("unroll") for (int k = 0; k < 2; ++k) dst[n][k] = *(const LAS bf16x8*)(lds + PG8_SB(b, h) + boff + n * 2048 + k * 1024); } while (0)
; #define PG8_MMA(ai, bj, At, Bt) do { __builtin_amdgcn_s_setprio(1); _Pragma("unroll") for (int m = 0; m < 4; ++m) _Pragma("unroll") for (int n = 0; n < 2; ++n) _Pragma("unroll") for (int k = 0; k < 2; ++k) \
;         acc[ai][bj][m][n] = __builtin_amdgcn_mfma_f32_16x16x32_bf16(Bt[n][k], At[m][k], acc[ai][bj][m][n], 0, 0, 0); __builtin_amdgcn_s_setprio(0); } while (0)
; #define PG8_WAIT_V(n) asm volatile("s_waitcnt vmcnt(" #n ")" ::: "memory")
; #define PG8_WAIT_L(n) asm volatile("s_waitcnt lgkmcnt(" #n ")" ::: "memory")
; #define PG8_BAR __builtin_amdgcn_s_barrier()
; #define PG8_SCHED __builtin_amdgcn_sched_barrier(0)
; template <class Epi, class Sched>
; DI void gemm_phase(LAS unsigned char* lds, const int K, const Sched& S, const Epi& E) {
;     ...
;             const bool last = (t == nt - 2);
;             const char* a1 = cA + (size_t)(t + 1) * kstep;
;             const char* a2 = last ? nA : cA + (size_t)(t + 2) * kstep; const char* b2 = last ? nB : cB + (size_t)(t + 2) * kstep;
;             const char* a3 = a2 + kstep; const char* b3 = b2 + kstep;
;             PG8_LDB(B0, 0, 0); PG8_LDB(B1, 0, 1); PG8_SCHED; PG8_LDA(At, 0, 0); PG8_STAGE(PG8_SA(1, 1), a1 + hstep, voffA);
;             PG8_WAIT_V(8); PG8_WAIT_L(0); PG8_BAR; PG8_MMA(0, 0, At, B0); PG8_MMA(0, 1, At, B1); PG8_BAR; PG8_SCHED;
;             PG8_LDA(At, 0, 1); PG8_STAGE(PG8_SB(0, 0), b2, voffB); PG8_STAGE(PG8_SB(0, 1), b2 + hstep, voffB); PG8_STAGE(PG8_SA(0, 0), a2, voffA);
;             PG8_WAIT_V(8); PG8_WAIT_L(0); PG8_BAR; PG8_MMA(1, 0, At, B0); PG8_MMA(1, 1, At, B1); PG8_BAR; PG8_SCHED;
.LBB0_465:
	s_add_u32 s70, s68, 0xfffc0080
	s_addc_u32 s71, s69, -1
	s_add_i32 vcc_lo, 0, 0x10000
	s_cmp_eq_u32 s79, 12
	s_cselect_b32 s73, s65, s71
	s_cselect_b32 s72, s67, s70
	s_cselect_b32 s71, s74, s78
	s_cselect_b32 s70, s76, s77
	s_add_i32 s42, 0, 0x14000
	v_add_u32_e32 v142, vcc_lo, v203
	v_add_u32_e32 v158, s42, v203
	ds_read_b128 v[130:133], v142
	ds_read_b128 v[134:137], v142 offset:1024
	ds_read_b128 v[138:141], v142 offset:2048
	ds_read_b128 v[142:145], v142 offset:3072
	ds_read_b128 v[146:149], v158
	ds_read_b128 v[150:153], v158 offset:1024
	ds_read_b128 v[154:157], v158 offset:2048
	ds_read_b128 v[158:161], v158 offset:3072
	v_lshl_add_u64 v[224:225], s[68:69], 0, v[172:173]
	s_add_i32 m0, s86, 0xc000
	ds_read_b128 v[174:177], v204
	ds_read_b128 v[182:185], v204 offset:1024
	ds_read_b128 v[190:193], v204 offset:2048
	ds_read_b128 v[194:197], v204 offset:3072
	ds_read_b128 v[198:201], v204 offset:4096
	ds_read_b128 v[212:215], v204 offset:5120
	ds_read_b128 v[216:219], v204 offset:6144
	ds_read_b128 v[220:223], v204 offset:7168
	global_load_lds_dwordx4 v[224:225], off
	v_lshl_add_u64 v[224:225], s[68:69], 0, v[170:171]
	s_add_i32 m0, s86, 0xe000
	s_nop 0
	global_load_lds_dwordx4 v[224:225], off
	s_waitcnt vmcnt(8)
	s_waitcnt lgkmcnt(0)
	s_barrier
	s_setprio 1
	s_waitcnt lgkmcnt(0)
	v_mfma_f32_16x16x32_bf16 v[126:129], v[130:133], v[174:177], v[126:129]
	v_mfma_f32_16x16x32_bf16 v[122:125], v[138:141], v[174:177], v[122:125]
	v_mfma_f32_16x16x32_bf16 v[110:113], v[130:133], v[190:193], v[110:113]
	v_mfma_f32_16x16x32_bf16 v[106:109], v[138:141], v[190:193], v[106:109]
	v_mfma_f32_16x16x32_bf16 v[94:97], v[130:133], v[198:201], v[94:97]
	v_mfma_f32_16x16x32_bf16 v[90:93], v[138:141], v[198:201], v[90:93]
	v_mfma_f32_16x16x32_bf16 v[78:81], v[130:133], v[216:219], v[78:81]
	v_mfma_f32_16x16x32_bf16 v[74:77], v[138:141], v[216:219], v[74:77]
	v_mfma_f32_16x16x32_bf16 v[126:129], v[134:137], v[182:185], v[126:129]
	v_mfma_f32_16x16x32_bf16 v[122:125], v[142:145], v[182:185], v[122:125]
	v_mfma_f32_16x16x32_bf16 v[110:113], v[134:137], v[194:197], v[110:113]
	v_mfma_f32_16x16x32_bf16 v[106:109], v[142:145], v[194:197], v[106:109]
	v_mfma_f32_16x16x32_bf16 v[94:97], v[134:137], v[212:215], v[94:97]
	v_mfma_f32_16x16x32_bf16 v[90:93], v[142:145], v[212:215], v[90:93]
	v_mfma_f32_16x16x32_bf16 v[78:81], v[134:137], v[220:223], v[78:81]
	v_mfma_f32_16x16x32_bf16 v[74:77], v[142:145], v[220:223], v[74:77]
	s_setprio 0
	s_setprio 1
	v_mfma_f32_16x16x32_bf16 v[118:121], v[146:149], v[174:177], v[118:121]
	v_mfma_f32_16x16x32_bf16 v[114:117], v[154:157], v[174:177], v[114:117]
	v_mfma_f32_16x16x32_bf16 v[102:105], v[146:149], v[190:193], v[102:105]
	v_mfma_f32_16x16x32_bf16 v[98:101], v[154:157], v[190:193], v[98:101]
	v_mfma_f32_16x16x32_bf16 v[86:89], v[146:149], v[198:201], v[86:89]
	v_mfma_f32_16x16x32_bf16 v[82:85], v[154:157], v[198:201], v[82:85]
	v_mfma_f32_16x16x32_bf16 v[70:73], v[146:149], v[216:219], v[70:73]
	v_mfma_f32_16x16x32_bf16 v[66:69], v[154:157], v[216:219], v[66:69]
	v_mfma_f32_16x16x32_bf16 v[118:121], v[150:153], v[182:185], v[118:121]
	v_mfma_f32_16x16x32_bf16 v[114:117], v[158:161], v[182:185], v[114:117]
	v_mfma_f32_16x16x32_bf16 v[102:105], v[150:153], v[194:197], v[102:105]
	v_mfma_f32_16x16x32_bf16 v[98:101], v[158:161], v[194:197], v[98:101]
	v_mfma_f32_16x16x32_bf16 v[86:89], v[150:153], v[212:215], v[86:89]
	v_mfma_f32_16x16x32_bf16 v[82:85], v[158:161], v[212:215], v[82:85]
	v_mfma_f32_16x16x32_bf16 v[70:73], v[150:153], v[220:223], v[70:73]
	v_mfma_f32_16x16x32_bf16 v[66:69], v[158:161], v[220:223], v[66:69]
	s_setprio 0
	s_barrier
	s_add_i32 s43, vcc_lo, s85
	v_lshl_add_u64 v[224:225], s[70:71], 0, v[164:165]
	s_mov_b32 m0, s43
	ds_read_b128 v[174:177], v204 offset:16384
	ds_read_b128 v[182:185], v204 offset:17408
	ds_read_b128 v[190:193], v204 offset:18432
	ds_read_b128 v[194:197], v204 offset:19456
	ds_read_b128 v[198:201], v204 offset:20480
	ds_read_b128 v[212:215], v204 offset:21504
	ds_read_b128 v[216:219], v204 offset:22528
	ds_read_b128 v[220:223], v204 offset:23552
	global_load_lds_dwordx4 v[224:225], off
	s_add_i32 m0, s43, 0x2000
	s_add_u32 vcc_lo, s70, 0x40000
	v_lshl_add_u64 v[226:227], s[70:71], 0, v[168:169]
	s_addc_u32 vcc_hi, s71, 0
	s_add_i32 s42, s42, s85
	global_load_lds_dwordx4 v[226:227], off
	v_lshl_add_u64 v[228:229], vcc, 0, v[164:165]
	s_mov_b32 m0, s42
	v_lshl_add_u64 v[230:231], s[72:73], 0, v[166:167]
	global_load_lds_dwordx4 v[228:229], off
	v_lshl_add_u64 v[228:229], vcc, 0, v[168:169]
	s_add_i32 m0, s42, 0x2000
	s_nop 0
	global_load_lds_dwordx4 v[228:229], off
	s_waitcnt vmcnt(6)
	s_waitcnt lgkmcnt(0)
	s_barrier
; #define PG8_STAGE(bufoff, gbase, voff) do { _Pragma("unroll") for (int _i = 0; _i < 2; ++_i) \
;         __builtin_amdgcn_global_load_lds((const unsigned*)((const char*)(gbase) + (voff)[_i]), (LAS unsigned*)(lds + (bufoff) + ldsw + _i * 8192), 16, 0, 0); } while (0)
; #define PG8_LDA(dst, b, h) do { _Pragma("unroll") for (int m = 0; m < 4; ++m) _Pragma("unroll") for (int k = 0; k < 2; ++k) dst[m][k] = *(const LAS bf16x8*)(lds + PG8_SA(b, h) + aoff + m * 2048 + k * 1024); } while (0)
; #define PG8_LDB(dst, b, h) do { _Pragma("unroll") for (int n = 0; n < 2; ++n) _Pragma("unroll") for (int k = 0; k < 2; ++k) dst[n][k] = *(const LAS bf16x8*)(lds + PG8_SB(b, h) + boff + n * 2048 + k * 1024); } while (0)
; #define PG8_MMA(ai, bj, At, Bt) do { __builtin_amdgcn_s_setprio(1); _Pragma("unroll") for (int m = 0; m < 4; ++m) _Pragma("unroll") for (int n = 0; n < 2; ++n) _Pragma("unroll") for (int k = 0; k < 2; ++k) \
;         acc[ai][bj][m][n] = __builtin_amdgcn_mfma_f32_16x16x32_bf16(Bt[n][k], At[m][k], acc[ai][bj][m][n], 0, 0, 0); __builtin_amdgcn_s_setprio(0); } while (0)
; #define PG8_WAIT_V(n) asm volatile("s_waitcnt vmcnt(" #n ")" ::: "memory")
; #define PG8_WAIT_L(n) asm volatile("s_waitcnt lgkmcnt(" #n ")" ::: "memory")
; #define PG8_BAR __builtin_amdgcn_s_barrier()
; #define PG8_SCHED __builtin_amdgcn_sched_barrier(0)
; template <class Epi, class Sched>
; DI void gemm_phase(LAS unsigned char* lds, const int K, const Sched& S, const Epi& E) {
;     ...
;             PG8_WAIT_V(8); PG8_WAIT_L(0); PG8_BAR; PG8_MMA(1, 0, At, B0); PG8_MMA(1, 1, At, B1); PG8_BAR; PG8_SCHED;
;             PG8_LDB(B0, 1, 0); PG8_LDB(B1, 1, 1); PG8_SCHED; PG8_LDA(At, 1, 0); PG8_STAGE(PG8_SA(0, 1), a2 + hstep, voffA);
;             PG8_WAIT_V(8); PG8_WAIT_L(0); PG8_BAR; PG8_MMA(0, 0, At, B0); PG8_MMA(0, 1, At, B1); PG8_BAR; PG8_SCHED;
	s_setprio 1
	s_waitcnt lgkmcnt(0)
	v_mfma_f32_16x16x32_bf16 v[62:65], v[130:133], v[174:177], v[62:65]
	v_mfma_f32_16x16x32_bf16 v[58:61], v[138:141], v[174:177], v[58:61]
	v_mfma_f32_16x16x32_bf16 v[46:49], v[130:133], v[190:193], v[46:49]
	v_mfma_f32_16x16x32_bf16 v[42:45], v[138:141], v[190:193], v[42:45]
	v_mfma_f32_16x16x32_bf16 v[30:33], v[130:133], v[198:201], v[30:33]
	v_mfma_f32_16x16x32_bf16 v[26:29], v[138:141], v[198:201], v[26:29]
	v_mfma_f32_16x16x32_bf16 v[14:17], v[130:133], v[216:219], v[14:17]
	v_mfma_f32_16x16x32_bf16 v[10:13], v[138:141], v[216:219], v[10:13]
	v_lshl_add_u64 v[228:229], s[72:73], 0, v[162:163]
	s_mov_b32 m0, s86
	s_nop 0
	global_load_lds_dwordx4 v[228:229], off
	v_mfma_f32_16x16x32_bf16 v[62:65], v[134:137], v[182:185], v[62:65]
	v_mfma_f32_16x16x32_bf16 v[58:61], v[142:145], v[182:185], v[58:61]
	v_mfma_f32_16x16x32_bf16 v[46:49], v[134:137], v[194:197], v[46:49]
	v_mfma_f32_16x16x32_bf16 v[42:45], v[142:145], v[194:197], v[42:45]
	v_mfma_f32_16x16x32_bf16 v[30:33], v[134:137], v[212:215], v[30:33]
	v_mfma_f32_16x16x32_bf16 v[26:29], v[142:145], v[212:215], v[26:29]
	v_mfma_f32_16x16x32_bf16 v[14:17], v[134:137], v[220:223], v[14:17]
	v_mfma_f32_16x16x32_bf16 v[10:13], v[142:145], v[220:223], v[10:13]
	s_setprio 0
	s_setprio 1
	v_mfma_f32_16x16x32_bf16 v[54:57], v[146:149], v[174:177], v[54:57]
	v_mfma_f32_16x16x32_bf16 v[50:53], v[154:157], v[174:177], v[50:53]
	v_mfma_f32_16x16x32_bf16 v[38:41], v[146:149], v[190:193], v[38:41]
	v_mfma_f32_16x16x32_bf16 v[34:37], v[154:157], v[190:193], v[34:37]
	v_mfma_f32_16x16x32_bf16 v[22:25], v[146:149], v[198:201], v[22:25]
	v_mfma_f32_16x16x32_bf16 v[18:21], v[154:157], v[198:201], v[18:21]
	v_mfma_f32_16x16x32_bf16 v[6:9], v[146:149], v[216:219], v[6:9]
	v_mfma_f32_16x16x32_bf16 v[2:5], v[154:157], v[216:219], v[2:5]
	s_mov_b32 m0, s87
	s_nop 0
	global_load_lds_dwordx4 v[230:231], off
	v_mfma_f32_16x16x32_bf16 v[54:57], v[150:153], v[182:185], v[54:57]
	v_mfma_f32_16x16x32_bf16 v[50:53], v[158:161], v[182:185], v[50:53]
	v_mfma_f32_16x16x32_bf16 v[38:41], v[150:153], v[194:197], v[38:41]
	v_mfma_f32_16x16x32_bf16 v[34:37], v[158:161], v[194:197], v[34:37]
	v_mfma_f32_16x16x32_bf16 v[22:25], v[150:153], v[212:215], v[22:25]
	v_mfma_f32_16x16x32_bf16 v[18:21], v[158:161], v[212:215], v[18:21]
	v_mfma_f32_16x16x32_bf16 v[6:9], v[150:153], v[220:223], v[6:9]
	v_mfma_f32_16x16x32_bf16 v[2:5], v[158:161], v[220:223], v[2:5]
	s_setprio 0
	s_barrier
	s_add_i32 s42, 0, 0x18000
	s_add_i32 s43, 0, 0x1c000
	v_add_u32_e32 v142, s42, v203
	v_add_u32_e32 v158, s43, v203
	ds_read_b128 v[130:133], v142
	ds_read_b128 v[134:137], v142 offset:1024
	ds_read_b128 v[138:141], v142 offset:2048
	ds_read_b128 v[142:145], v142 offset:3072
	ds_read_b128 v[146:149], v158
	ds_read_b128 v[150:153], v158 offset:1024
	ds_read_b128 v[154:157], v158 offset:2048
	ds_read_b128 v[158:161], v158 offset:3072
	s_add_u32 s72, s72, 0x40000
	s_addc_u32 s73, s73, 0
	s_mov_b32 m0, s92
	v_lshl_add_u64 v[232:233], s[72:73], 0, v[162:163]
	ds_read_b128 v[174:177], v204 offset:32768
	ds_read_b128 v[182:185], v204 offset:33792
	ds_read_b128 v[190:193], v204 offset:34816
	ds_read_b128 v[194:197], v204 offset:35840
	ds_read_b128 v[198:201], v204 offset:36864
	ds_read_b128 v[212:215], v204 offset:37888
	ds_read_b128 v[216:219], v204 offset:38912
	ds_read_b128 v[220:223], v204 offset:39936
	global_load_lds_dwordx4 v[232:233], off
	v_lshl_add_u64 v[232:233], s[72:73], 0, v[166:167]
	s_mov_b32 m0, s94
	s_nop 0
	global_load_lds_dwordx4 v[232:233], off
	s_waitcnt vmcnt(8)
	s_waitcnt lgkmcnt(0)
	s_barrier
	s_setprio 1
	s_waitcnt lgkmcnt(0)
	v_mfma_f32_16x16x32_bf16 v[126:129], v[130:133], v[174:177], v[126:129]
	v_mfma_f32_16x16x32_bf16 v[122:125], v[138:141], v[174:177], v[122:125]
	v_mfma_f32_16x16x32_bf16 v[110:113], v[130:133], v[190:193], v[110:113]
	v_mfma_f32_16x16x32_bf16 v[106:109], v[138:141], v[190:193], v[106:109]
	v_mfma_f32_16x16x32_bf16 v[94:97], v[130:133], v[198:201], v[94:97]
	v_mfma_f32_16x16x32_bf16 v[90:93], v[138:141], v[198:201], v[90:93]
	v_mfma_f32_16x16x32_bf16 v[78:81], v[130:133], v[216:219], v[78:81]
	v_mfma_f32_16x16x32_bf16 v[74:77], v[138:141], v[216:219], v[74:77]
	v_mfma_f32_16x16x32_bf16 v[126:129], v[134:137], v[182:185], v[126:129]
	v_mfma_f32_16x16x32_bf16 v[122:125], v[142:145], v[182:185], v[122:125]
	v_mfma_f32_16x16x32_bf16 v[110:113], v[134:137], v[194:197], v[110:113]
	v_mfma_f32_16x16x32_bf16 v[106:109], v[142:145], v[194:197], v[106:109]
	v_mfma_f32_16x16x32_bf16 v[94:97], v[134:137], v[212:215], v[94:97]
	v_mfma_f32_16x16x32_bf16 v[90:93], v[142:145], v[212:215], v[90:93]
	v_mfma_f32_16x16x32_bf16 v[78:81], v[134:137], v[220:223], v[78:81]
	v_mfma_f32_16x16x32_bf16 v[74:77], v[142:145], v[220:223], v[74:77]
	s_setprio 0
	s_setprio 1
	v_mfma_f32_16x16x32_bf16 v[118:121], v[146:149], v[174:177], v[118:121]
	v_mfma_f32_16x16x32_bf16 v[114:117], v[154:157], v[174:177], v[114:117]
	v_mfma_f32_16x16x32_bf16 v[102:105], v[146:149], v[190:193], v[102:105]
	v_mfma_f32_16x16x32_bf16 v[98:101], v[154:157], v[190:193], v[98:101]
	v_mfma_f32_16x16x32_bf16 v[86:89], v[146:149], v[198:201], v[86:89]
	v_mfma_f32_16x16x32_bf16 v[82:85], v[154:157], v[198:201], v[82:85]
	v_mfma_f32_16x16x32_bf16 v[70:73], v[146:149], v[216:219], v[70:73]
	v_mfma_f32_16x16x32_bf16 v[66:69], v[154:157], v[216:219], v[66:69]
	v_mfma_f32_16x16x32_bf16 v[118:121], v[150:153], v[182:185], v[118:121]
	v_mfma_f32_16x16x32_bf16 v[114:117], v[158:161], v[182:185], v[114:117]
	v_mfma_f32_16x16x32_bf16 v[102:105], v[150:153], v[194:197], v[102:105]
	v_mfma_f32_16x16x32_bf16 v[98:101], v[158:161], v[194:197], v[98:101]
	v_mfma_f32_16x16x32_bf16 v[86:89], v[150:153], v[212:215], v[86:89]
	v_mfma_f32_16x16x32_bf16 v[82:85], v[158:161], v[212:215], v[82:85]
	v_mfma_f32_16x16x32_bf16 v[70:73], v[150:153], v[220:223], v[70:73]
	v_mfma_f32_16x16x32_bf16 v[66:69], v[158:161], v[220:223], v[66:69]
	s_setprio 0
	s_barrier
; #define PG8_STAGE(bufoff, gbase, voff) do { _Pragma("unroll") for (int _i = 0; _i < 2; ++_i) \
;         __builtin_amdgcn_global_load_lds((const unsigned*)((const char*)(gbase) + (voff)[_i]), (LAS unsigned*)(lds + (bufoff) + ldsw + _i * 8192), 16, 0, 0); } while (0)
; #define PG8_LDA(dst, b, h) do { _Pragma("unroll") for (int m = 0; m < 4; ++m) _Pragma("unroll") for (int k = 0; k < 2; ++k) dst[m][k] = *(const LAS bf16x8*)(lds + PG8_SA(b, h) + aoff + m * 2048 + k * 1024); } while (0)
; #define PG8_MMA(ai, bj, At, Bt) do { __builtin_amdgcn_s_setprio(1); _Pragma("unroll") for (int m = 0; m < 4; ++m) _Pragma("unroll") for (int n = 0; n < 2; ++n) _Pragma("unroll") for (int k = 0; k < 2; ++k) \
;         acc[ai][bj][m][n] = __builtin_amdgcn_mfma_f32_16x16x32_bf16(Bt[n][k], At[m][k], acc[ai][bj][m][n], 0, 0, 0); __builtin_amdgcn_s_setprio(0); } while (0)
; #define PG8_WAIT_V(n) asm volatile("s_waitcnt vmcnt(" #n ")" ::: "memory")
; #define PG8_WAIT_L(n) asm volatile("s_waitcnt lgkmcnt(" #n ")" ::: "memory")
; #define PG8_BAR __builtin_amdgcn_s_barrier()
; #define PG8_SCHED __builtin_amdgcn_sched_barrier(0)
; template <class Epi, class Sched>
; DI void gemm_phase(LAS unsigned char* lds, const int K, const Sched& S, const Epi& E) {
;     ...
;             PG8_LDA(At, 1, 1); PG8_STAGE(PG8_SB(1, 0), b3, voffB); PG8_STAGE(PG8_SB(1, 1), b3 + hstep, voffB); PG8_STAGE(PG8_SA(1, 0), a3, voffA);
;             PG8_WAIT_V(8); PG8_WAIT_L(0); PG8_BAR; PG8_MMA(1, 0, At, B0); PG8_MMA(1, 1, At, B1); PG8_BAR; PG8_SCHED;
;         }
;         if (wr == 0) PG8_BAR;
	s_add_i32 s42, s42, s85
	v_lshl_add_u64 v[224:225], v[224:225], 0, s[90:91]
	s_mov_b32 m0, s42
	ds_read_b128 v[174:177], v204 offset:49152
	ds_read_b128 v[182:185], v204 offset:50176
	ds_read_b128 v[190:193], v204 offset:51200
	ds_read_b128 v[194:197], v204 offset:52224
	ds_read_b128 v[198:201], v204 offset:53248
	ds_read_b128 v[212:215], v204 offset:54272
	ds_read_b128 v[216:219], v204 offset:55296
	ds_read_b128 v[220:223], v204 offset:56320
	global_load_lds_dwordx4 v[224:225], off
	s_add_i32 m0, s42, 0x2000
	s_add_u32 s70, s70, 0x40080
	v_lshl_add_u64 v[224:225], v[226:227], 0, s[90:91]
	s_addc_u32 s71, s71, 0
	s_add_i32 s42, s43, s85
	global_load_lds_dwordx4 v[224:225], off
	v_lshl_add_u64 v[224:225], s[70:71], 0, v[164:165]
	s_mov_b32 m0, s42
	s_nop 0
	global_load_lds_dwordx4 v[224:225], off
	v_lshl_add_u64 v[224:225], s[70:71], 0, v[168:169]
	s_add_i32 m0, s42, 0x2000
	s_nop 0
	global_load_lds_dwordx4 v[224:225], off
	s_waitcnt vmcnt(6)
	s_waitcnt lgkmcnt(0)
	s_barrier
	s_setprio 1
	s_waitcnt lgkmcnt(0)
	v_mfma_f32_16x16x32_bf16 v[62:65], v[130:133], v[174:177], v[62:65]
	v_mfma_f32_16x16x32_bf16 v[58:61], v[138:141], v[174:177], v[58:61]
	v_mfma_f32_16x16x32_bf16 v[46:49], v[130:133], v[190:193], v[46:49]
	v_mfma_f32_16x16x32_bf16 v[42:45], v[138:141], v[190:193], v[42:45]
	v_mfma_f32_16x16x32_bf16 v[30:33], v[130:133], v[198:201], v[30:33]
	v_mfma_f32_16x16x32_bf16 v[26:29], v[138:141], v[198:201], v[26:29]
	v_mfma_f32_16x16x32_bf16 v[14:17], v[130:133], v[216:219], v[14:17]
	v_mfma_f32_16x16x32_bf16 v[10:13], v[138:141], v[216:219], v[10:13]
	v_lshl_add_u64 v[224:225], v[228:229], 0, s[90:91]
	s_mov_b32 m0, s45
	s_nop 0
	global_load_lds_dwordx4 v[224:225], off
	v_mfma_f32_16x16x32_bf16 v[62:65], v[134:137], v[182:185], v[62:65]
	v_mfma_f32_16x16x32_bf16 v[58:61], v[142:145], v[182:185], v[58:61]
	v_mfma_f32_16x16x32_bf16 v[46:49], v[134:137], v[194:197], v[46:49]
	v_mfma_f32_16x16x32_bf16 v[42:45], v[142:145], v[194:197], v[42:45]
	v_mfma_f32_16x16x32_bf16 v[30:33], v[134:137], v[212:215], v[30:33]
	v_mfma_f32_16x16x32_bf16 v[26:29], v[142:145], v[212:215], v[26:29]
	v_mfma_f32_16x16x32_bf16 v[14:17], v[134:137], v[220:223], v[14:17]
	v_mfma_f32_16x16x32_bf16 v[10:13], v[142:145], v[220:223], v[10:13]
	s_setprio 0
	s_setprio 1
	v_mfma_f32_16x16x32_bf16 v[54:57], v[146:149], v[174:177], v[54:57]
	v_mfma_f32_16x16x32_bf16 v[50:53], v[154:157], v[174:177], v[50:53]
	v_mfma_f32_16x16x32_bf16 v[38:41], v[146:149], v[190:193], v[38:41]
	v_mfma_f32_16x16x32_bf16 v[34:37], v[154:157], v[190:193], v[34:37]
	v_mfma_f32_16x16x32_bf16 v[22:25], v[146:149], v[198:201], v[22:25]
	v_mfma_f32_16x16x32_bf16 v[18:21], v[154:157], v[198:201], v[18:21]
	v_mfma_f32_16x16x32_bf16 v[6:9], v[146:149], v[216:219], v[6:9]
	v_mfma_f32_16x16x32_bf16 v[2:5], v[154:157], v[216:219], v[2:5]
	v_lshl_add_u64 v[224:225], v[230:231], 0, s[90:91]
	s_mov_b32 m0, s50
	s_nop 0
	global_load_lds_dwordx4 v[224:225], off
	v_mfma_f32_16x16x32_bf16 v[54:57], v[150:153], v[182:185], v[54:57]
	v_mfma_f32_16x16x32_bf16 v[50:53], v[158:161], v[182:185], v[50:53]
	v_mfma_f32_16x16x32_bf16 v[38:41], v[150:153], v[194:197], v[38:41]
	v_mfma_f32_16x16x32_bf16 v[34:37], v[158:161], v[194:197], v[34:37]
	v_mfma_f32_16x16x32_bf16 v[22:25], v[150:153], v[212:215], v[22:25]
	v_mfma_f32_16x16x32_bf16 v[18:21], v[158:161], v[212:215], v[18:21]
	v_mfma_f32_16x16x32_bf16 v[6:9], v[150:153], v[220:223], v[6:9]
	v_mfma_f32_16x16x32_bf16 v[2:5], v[158:161], v[220:223], v[2:5]
	s_setprio 0
	s_barrier
	s_add_i32 s79, s79, 2
	s_add_u32 s77, s77, 0x100
	s_addc_u32 s78, s78, 0
	s_add_u32 s68, s68, 0x100
	s_addc_u32 s69, s69, 0
	s_cmp_gt_u32 s79, 13
	s_cbranch_scc0 .LBB0_465
	s_and_b64 vcc, exec, s[48:49]
	s_cbranch_vccz .LBB0_468
	s_barrier

; #define PG8_STAGE(bufoff, gbase, voff) do { _Pragma("unroll") for (int _i = 0; _i < 2; ++_i) \
;         __builtin_amdgcn_global_load_lds((const unsigned*)((const char*)(gbase) + (voff)[_i]), (LAS unsigned*)(lds + (bufoff) + ldsw + _i * 8192), 16, 0, 0); } while (0)
; #define PG8_LDA(dst, b, h) do { _Pragma("unroll") for (int m = 0; m < 4; ++m) _Pragma("unroll") for (int k = 0; k < 2; ++k) dst[m][k] = *(const LAS bf16x8*)(lds + PG8_SA(b, h) + aoff + m * 2048 + k * 1024); } while (0)
; #define PG8_LDB(dst, b, h) do { _Pragma("unroll") for (int n = 0; n < 2; ++n) _Pragma("unroll") for (int k = 0; k < 2; ++k) dst[n][k] = *(const LAS bf16x8*)(lds + PG8_SB(b, h) + boff + n * 2048 + k * 1024); } while (0)
; #define PG8_MMA(ai, bj, At, Bt) do { __builtin_amdgcn_s_setprio(1); _Pragma("unroll") for (int m = 0; m < 4; ++m) _Pragma("unroll") for (int n = 0; n < 2; ++n) _Pragma("unroll") for (int k = 0; k < 2; ++k) \
;         acc[ai][bj][m][n] = __builtin_amdgcn_mfma_f32_16x16x32_bf16(Bt[n][k], At[m][k], acc[ai][bj][m][n], 0, 0, 0); __builtin_amdgcn_s_setprio(0); } while (0)
; #define PG8_WAIT_V(n) asm volatile("s_waitcnt vmcnt(" #n ")" ::: "memory")
; #define PG8_WAIT_L(n) asm volatile("s_waitcnt lgkmcnt(" #n ")" ::: "memory")
; #define PG8_BAR __builtin_amdgcn_s_barrier()
; #define PG8_SCHED __builtin_amdgcn_sched_barrier(0)
; template <class Epi, class Sched>
; DI void gemm_phase(LAS unsigned char* lds, const int K, const Sched& S, const Epi& E) {
;     ...
;             const bool last = (t == nt - 2);
;             const char* a1 = cA + (size_t)(t + 1) * kstep;
;             const char* a2 = last ? nA : cA + (size_t)(t + 2) * kstep; const char* b2 = last ? nB : cB + (size_t)(t + 2) * kstep;
;             const char* a3 = a2 + kstep; const char* b3 = b2 + kstep;
;             PG8_LDB(B0, 0, 0); PG8_LDB(B1, 0, 1); PG8_SCHED; PG8_LDA(At, 0, 0); PG8_STAGE(PG8_SA(1, 1), a1 + hstep, voffA);
;             PG8_WAIT_V(8); PG8_WAIT_L(0); PG8_BAR; PG8_MMA(0, 0, At, B0); PG8_MMA(0, 1, At, B1); PG8_BAR; PG8_SCHED;
;             PG8_LDA(At, 0, 1); PG8_STAGE(PG8_SB(0, 0), b2, voffB); PG8_STAGE(PG8_SB(0, 1), b2 + hstep, voffB); PG8_STAGE(PG8_SA(0, 0), a2, voffA);
.LBB0_648:
	s_add_u32 s66, s64, 0xfffc0080
	s_addc_u32 s67, s65, -1
	s_add_i32 s92, 0, 0x10000
	s_cmp_eq_u32 s63, 12
	s_cselect_b32 s69, s59, s67
	s_cselect_b32 s68, s58, s66
	v_add_u32_e32 v1, s92, v154
	s_cselect_b32 s67, s61, s57
	s_cselect_b32 s66, s60, s55
	s_add_i32 s95, 0, 0x14000
	ds_read_b128 v[142:145], v1
	s_waitcnt lgkmcnt(0)
	ds_read_b128 v[146:149], v1 offset:1024
	ds_read_b128 v[156:159], v1 offset:2048
	ds_read_b128 v[160:163], v1 offset:3072
	v_add_u32_e32 v1, s95, v154
	ds_read_b128 v[164:167], v1
	ds_read_b128 v[168:171], v1 offset:1024
	ds_read_b128 v[172:175], v1 offset:2048
	ds_read_b128 v[182:185], v1 offset:3072
	v_lshl_add_u64 v[150:151], s[64:65], 0, v[140:141]
	s_add_i32 m0, s76, 0xc000
	ds_read_b128 v[190:193], v155
	ds_read_b128 v[194:197], v155 offset:1024
	ds_read_b128 v[198:201], v155 offset:2048
	ds_read_b128 v[202:205], v155 offset:3072
	ds_read_b128 v[212:215], v155 offset:4096
	ds_read_b128 v[216:219], v155 offset:5120
	ds_read_b128 v[220:223], v155 offset:6144
	ds_read_b128 v[224:227], v155 offset:7168
	global_load_lds_dwordx4 v[150:151], off
	v_lshl_add_u64 v[150:151], s[64:65], 0, v[138:139]
	s_add_i32 m0, s76, 0xe000
	s_nop 0
	global_load_lds_dwordx4 v[150:151], off
	s_waitcnt vmcnt(8)
	s_waitcnt lgkmcnt(0)
	s_barrier
	s_setprio 1
	s_waitcnt lgkmcnt(0)
	v_mfma_f32_16x16x32_bf16 v[126:129], v[142:145], v[190:193], v[126:129]
	v_mfma_f32_16x16x32_bf16 v[122:125], v[156:159], v[190:193], v[122:125]
	v_mfma_f32_16x16x32_bf16 v[110:113], v[142:145], v[198:201], v[110:113]
	v_mfma_f32_16x16x32_bf16 v[106:109], v[156:159], v[198:201], v[106:109]
	v_mfma_f32_16x16x32_bf16 v[94:97], v[142:145], v[212:215], v[94:97]
	v_mfma_f32_16x16x32_bf16 v[90:93], v[156:159], v[212:215], v[90:93]
	v_mfma_f32_16x16x32_bf16 v[78:81], v[142:145], v[220:223], v[78:81]
	v_mfma_f32_16x16x32_bf16 v[74:77], v[156:159], v[220:223], v[74:77]
	v_mfma_f32_16x16x32_bf16 v[126:129], v[146:149], v[194:197], v[126:129]
	v_mfma_f32_16x16x32_bf16 v[122:125], v[160:163], v[194:197], v[122:125]
	v_mfma_f32_16x16x32_bf16 v[110:113], v[146:149], v[202:205], v[110:113]
	v_mfma_f32_16x16x32_bf16 v[106:109], v[160:163], v[202:205], v[106:109]
	v_mfma_f32_16x16x32_bf16 v[94:97], v[146:149], v[216:219], v[94:97]
	v_mfma_f32_16x16x32_bf16 v[90:93], v[160:163], v[216:219], v[90:93]
	v_mfma_f32_16x16x32_bf16 v[78:81], v[146:149], v[224:227], v[78:81]
	v_mfma_f32_16x16x32_bf16 v[74:77], v[160:163], v[224:227], v[74:77]
	s_setprio 0
	s_setprio 1
	v_mfma_f32_16x16x32_bf16 v[118:121], v[164:167], v[190:193], v[118:121]
	v_mfma_f32_16x16x32_bf16 v[114:117], v[172:175], v[190:193], v[114:117]
	v_mfma_f32_16x16x32_bf16 v[102:105], v[164:167], v[198:201], v[102:105]
	v_mfma_f32_16x16x32_bf16 v[98:101], v[172:175], v[198:201], v[98:101]
	v_mfma_f32_16x16x32_bf16 v[86:89], v[164:167], v[212:215], v[86:89]
	v_mfma_f32_16x16x32_bf16 v[82:85], v[172:175], v[212:215], v[82:85]
	v_mfma_f32_16x16x32_bf16 v[70:73], v[164:167], v[220:223], v[70:73]
	v_mfma_f32_16x16x32_bf16 v[66:69], v[172:175], v[220:223], v[66:69]
	v_mfma_f32_16x16x32_bf16 v[118:121], v[168:171], v[194:197], v[118:121]
	v_mfma_f32_16x16x32_bf16 v[114:117], v[182:185], v[194:197], v[114:117]
	v_mfma_f32_16x16x32_bf16 v[102:105], v[168:171], v[202:205], v[102:105]
	v_mfma_f32_16x16x32_bf16 v[98:101], v[182:185], v[202:205], v[98:101]
	v_mfma_f32_16x16x32_bf16 v[86:89], v[168:171], v[216:219], v[86:89]
	v_mfma_f32_16x16x32_bf16 v[82:85], v[182:185], v[216:219], v[82:85]
	v_mfma_f32_16x16x32_bf16 v[70:73], v[168:171], v[224:227], v[70:73]
	v_mfma_f32_16x16x32_bf16 v[66:69], v[182:185], v[224:227], v[66:69]
	s_setprio 0
	s_barrier
	s_add_i32 s92, s92, s75
	v_lshl_add_u64 v[150:151], s[66:67], 0, v[132:133]
	s_mov_b32 m0, s92
	ds_read_b128 v[190:193], v155 offset:16384
	ds_read_b128 v[194:197], v155 offset:17408
	ds_read_b128 v[198:201], v155 offset:18432
	ds_read_b128 v[202:205], v155 offset:19456
	ds_read_b128 v[212:215], v155 offset:20480
	ds_read_b128 v[216:219], v155 offset:21504
	ds_read_b128 v[220:223], v155 offset:22528
	ds_read_b128 v[224:227], v155 offset:23552
	global_load_lds_dwordx4 v[150:151], off
	s_add_i32 m0, s92, 0x2000
	s_add_u32 vcc_lo, s66, 0x40000
	v_lshl_add_u64 v[176:177], s[66:67], 0, v[136:137]
	s_addc_u32 vcc_hi, s67, 0
	s_add_i32 s92, s95, s75
	global_load_lds_dwordx4 v[176:177], off
	v_lshl_add_u64 v[228:229], vcc, 0, v[132:133]
	s_mov_b32 m0, s92
	v_lshl_add_u64 v[230:231], s[68:69], 0, v[134:135]
	global_load_lds_dwordx4 v[228:229], off
	v_lshl_add_u64 v[228:229], vcc, 0, v[136:137]
	s_add_i32 m0, s92, 0x2000
	s_nop 0
	global_load_lds_dwordx4 v[228:229], off
	s_waitcnt vmcnt(6)
	s_waitcnt lgkmcnt(0)
	s_barrier
; #define PG8_STAGE(bufoff, gbase, voff) do { _Pragma("unroll") for (int _i = 0; _i < 2; ++_i) \
;         __builtin_amdgcn_global_load_lds((const unsigned*)((const char*)(gbase) + (voff)[_i]), (LAS unsigned*)(lds + (bufoff) + ldsw + _i * 8192), 16, 0, 0); } while (0)
; #define PG8_LDA(dst, b, h) do { _Pragma("unroll") for (int m = 0; m < 4; ++m) _Pragma("unroll") for (int k = 0; k < 2; ++k) dst[m][k] = *(const LAS bf16x8*)(lds + PG8_SA(b, h) + aoff + m * 2048 + k * 1024); } while (0)
; #define PG8_LDB(dst, b, h) do { _Pragma("unroll") for (int n = 0; n < 2; ++n) _Pragma("unroll") for (int k = 0; k < 2; ++k) dst[n][k] = *(const LAS bf16x8*)(lds + PG8_SB(b, h) + boff + n * 2048 + k * 1024); } while (0)
; #define PG8_MMA(ai, bj, At, Bt) do { __builtin_amdgcn_s_setprio(1); _Pragma("unroll") for (int m = 0; m < 4; ++m) _Pragma("unroll") for (int n = 0; n < 2; ++n) _Pragma("unroll") for (int k = 0; k < 2; ++k) \
;         acc[ai][bj][m][n] = __builtin_amdgcn_mfma_f32_16x16x32_bf16(Bt[n][k], At[m][k], acc[ai][bj][m][n], 0, 0, 0); __builtin_amdgcn_s_setprio(0); } while (0)
; #define PG8_WAIT_V(n) asm volatile("s_waitcnt vmcnt(" #n ")" ::: "memory")
; #define PG8_WAIT_L(n) asm volatile("s_waitcnt lgkmcnt(" #n ")" ::: "memory")
; #define PG8_BAR __builtin_amdgcn_s_barrier()
; #define PG8_SCHED __builtin_amdgcn_sched_barrier(0)
; template <class Epi, class Sched>
; DI void gemm_phase(LAS unsigned char* lds, const int K, const Sched& S, const Epi& E) {
;     ...
;             PG8_WAIT_V(8); PG8_WAIT_L(0); PG8_BAR; PG8_MMA(1, 0, At, B0); PG8_MMA(1, 1, At, B1); PG8_BAR; PG8_SCHED;
;             PG8_LDB(B0, 1, 0); PG8_LDB(B1, 1, 1); PG8_SCHED; PG8_LDA(At, 1, 0); PG8_STAGE(PG8_SA(0, 1), a2 + hstep, voffA);
;             PG8_WAIT_V(8); PG8_WAIT_L(0); PG8_BAR; PG8_MMA(0, 0, At, B0); PG8_MMA(0, 1, At, B1); PG8_BAR; PG8_SCHED;
	s_setprio 1
	s_waitcnt lgkmcnt(0)
	v_mfma_f32_16x16x32_bf16 v[62:65], v[142:145], v[190:193], v[62:65]
	v_mfma_f32_16x16x32_bf16 v[58:61], v[156:159], v[190:193], v[58:61]
	v_mfma_f32_16x16x32_bf16 v[46:49], v[142:145], v[198:201], v[46:49]
	v_mfma_f32_16x16x32_bf16 v[42:45], v[156:159], v[198:201], v[42:45]
	v_mfma_f32_16x16x32_bf16 v[30:33], v[142:145], v[212:215], v[30:33]
	v_mfma_f32_16x16x32_bf16 v[26:29], v[156:159], v[212:215], v[26:29]
	v_mfma_f32_16x16x32_bf16 v[14:17], v[142:145], v[220:223], v[14:17]
	v_mfma_f32_16x16x32_bf16 v[10:13], v[156:159], v[220:223], v[10:13]
	v_lshl_add_u64 v[228:229], s[68:69], 0, v[130:131]
	s_mov_b32 m0, s76
	s_nop 0
	global_load_lds_dwordx4 v[228:229], off
	v_mfma_f32_16x16x32_bf16 v[62:65], v[146:149], v[194:197], v[62:65]
	v_mfma_f32_16x16x32_bf16 v[58:61], v[160:163], v[194:197], v[58:61]
	v_mfma_f32_16x16x32_bf16 v[46:49], v[146:149], v[202:205], v[46:49]
	v_mfma_f32_16x16x32_bf16 v[42:45], v[160:163], v[202:205], v[42:45]
	v_mfma_f32_16x16x32_bf16 v[30:33], v[146:149], v[216:219], v[30:33]
	v_mfma_f32_16x16x32_bf16 v[26:29], v[160:163], v[216:219], v[26:29]
	v_mfma_f32_16x16x32_bf16 v[14:17], v[146:149], v[224:227], v[14:17]
	v_mfma_f32_16x16x32_bf16 v[10:13], v[160:163], v[224:227], v[10:13]
	s_setprio 0
	s_setprio 1
	v_mfma_f32_16x16x32_bf16 v[54:57], v[164:167], v[190:193], v[54:57]
	v_mfma_f32_16x16x32_bf16 v[50:53], v[172:175], v[190:193], v[50:53]
	v_mfma_f32_16x16x32_bf16 v[38:41], v[164:167], v[198:201], v[38:41]
	v_mfma_f32_16x16x32_bf16 v[34:37], v[172:175], v[198:201], v[34:37]
	v_mfma_f32_16x16x32_bf16 v[22:25], v[164:167], v[212:215], v[22:25]
	v_mfma_f32_16x16x32_bf16 v[18:21], v[172:175], v[212:215], v[18:21]
	v_mfma_f32_16x16x32_bf16 v[6:9], v[164:167], v[220:223], v[6:9]
	v_mfma_f32_16x16x32_bf16 v[2:5], v[172:175], v[220:223], v[2:5]
	s_mov_b32 m0, s77
	s_nop 0
	global_load_lds_dwordx4 v[230:231], off
	v_mfma_f32_16x16x32_bf16 v[54:57], v[168:171], v[194:197], v[54:57]
	v_mfma_f32_16x16x32_bf16 v[50:53], v[182:185], v[194:197], v[50:53]
	v_mfma_f32_16x16x32_bf16 v[38:41], v[168:171], v[202:205], v[38:41]
	v_mfma_f32_16x16x32_bf16 v[34:37], v[182:185], v[202:205], v[34:37]
	v_mfma_f32_16x16x32_bf16 v[22:25], v[168:171], v[216:219], v[22:25]
	v_mfma_f32_16x16x32_bf16 v[18:21], v[182:185], v[216:219], v[18:21]
	v_mfma_f32_16x16x32_bf16 v[6:9], v[168:171], v[224:227], v[6:9]
	v_mfma_f32_16x16x32_bf16 v[2:5], v[182:185], v[224:227], v[2:5]
	s_setprio 0
	s_barrier
	s_add_i32 s92, 0, 0x18000
	v_add_u32_e32 v1, s92, v154
	s_add_i32 s95, 0, 0x1c000
	ds_read_b128 v[142:145], v1
	ds_read_b128 v[146:149], v1 offset:1024
	ds_read_b128 v[156:159], v1 offset:2048
	ds_read_b128 v[160:163], v1 offset:3072
	v_add_u32_e32 v1, s95, v154
	ds_read_b128 v[164:167], v1
	ds_read_b128 v[168:171], v1 offset:1024
	ds_read_b128 v[172:175], v1 offset:2048
	ds_read_b128 v[182:185], v1 offset:3072
	s_add_u32 s68, s68, 0x40000
	s_addc_u32 s69, s69, 0
	s_mov_b32 m0, s78
	v_lshl_add_u64 v[232:233], s[68:69], 0, v[130:131]
	ds_read_b128 v[190:193], v155 offset:32768
	ds_read_b128 v[194:197], v155 offset:33792
	ds_read_b128 v[198:201], v155 offset:34816
	ds_read_b128 v[202:205], v155 offset:35840
	ds_read_b128 v[212:215], v155 offset:36864
	ds_read_b128 v[216:219], v155 offset:37888
	ds_read_b128 v[220:223], v155 offset:38912
	ds_read_b128 v[224:227], v155 offset:39936
	global_load_lds_dwordx4 v[232:233], off
	v_lshl_add_u64 v[232:233], s[68:69], 0, v[134:135]
	s_mov_b32 m0, s79
	s_nop 0
	global_load_lds_dwordx4 v[232:233], off
	s_waitcnt vmcnt(8)
	s_waitcnt lgkmcnt(0)
	s_barrier
	s_setprio 1
	s_waitcnt lgkmcnt(0)
	v_mfma_f32_16x16x32_bf16 v[126:129], v[142:145], v[190:193], v[126:129]
	v_mfma_f32_16x16x32_bf16 v[122:125], v[156:159], v[190:193], v[122:125]
	v_mfma_f32_16x16x32_bf16 v[110:113], v[142:145], v[198:201], v[110:113]
	v_mfma_f32_16x16x32_bf16 v[106:109], v[156:159], v[198:201], v[106:109]
	v_mfma_f32_16x16x32_bf16 v[94:97], v[142:145], v[212:215], v[94:97]
	v_mfma_f32_16x16x32_bf16 v[90:93], v[156:159], v[212:215], v[90:93]
	v_mfma_f32_16x16x32_bf16 v[78:81], v[142:145], v[220:223], v[78:81]
	v_mfma_f32_16x16x32_bf16 v[74:77], v[156:159], v[220:223], v[74:77]
	v_mfma_f32_16x16x32_bf16 v[126:129], v[146:149], v[194:197], v[126:129]
	v_mfma_f32_16x16x32_bf16 v[122:125], v[160:163], v[194:197], v[122:125]
	v_mfma_f32_16x16x32_bf16 v[110:113], v[146:149], v[202:205], v[110:113]
	v_mfma_f32_16x16x32_bf16 v[106:109], v[160:163], v[202:205], v[106:109]
	v_mfma_f32_16x16x32_bf16 v[94:97], v[146:149], v[216:219], v[94:97]
	v_mfma_f32_16x16x32_bf16 v[90:93], v[160:163], v[216:219], v[90:93]
	v_mfma_f32_16x16x32_bf16 v[78:81], v[146:149], v[224:227], v[78:81]
	v_mfma_f32_16x16x32_bf16 v[74:77], v[160:163], v[224:227], v[74:77]
	s_setprio 0
	s_setprio 1
	v_mfma_f32_16x16x32_bf16 v[118:121], v[164:167], v[190:193], v[118:121]
	v_mfma_f32_16x16x32_bf16 v[114:117], v[172:175], v[190:193], v[114:117]
	v_mfma_f32_16x16x32_bf16 v[102:105], v[164:167], v[198:201], v[102:105]
	v_mfma_f32_16x16x32_bf16 v[98:101], v[172:175], v[198:201], v[98:101]
	v_mfma_f32_16x16x32_bf16 v[86:89], v[164:167], v[212:215], v[86:89]
	v_mfma_f32_16x16x32_bf16 v[82:85], v[172:175], v[212:215], v[82:85]
	v_mfma_f32_16x16x32_bf16 v[70:73], v[164:167], v[220:223], v[70:73]
	v_mfma_f32_16x16x32_bf16 v[66:69], v[172:175], v[220:223], v[66:69]
	v_mfma_f32_16x16x32_bf16 v[118:121], v[168:171], v[194:197], v[118:121]
	v_mfma_f32_16x16x32_bf16 v[114:117], v[182:185], v[194:197], v[114:117]
	v_mfma_f32_16x16x32_bf16 v[102:105], v[168:171], v[202:205], v[102:105]
	v_mfma_f32_16x16x32_bf16 v[98:101], v[182:185], v[202:205], v[98:101]
	v_mfma_f32_16x16x32_bf16 v[86:89], v[168:171], v[216:219], v[86:89]
	v_mfma_f32_16x16x32_bf16 v[82:85], v[182:185], v[216:219], v[82:85]
	v_mfma_f32_16x16x32_bf16 v[70:73], v[168:171], v[224:227], v[70:73]
	v_mfma_f32_16x16x32_bf16 v[66:69], v[182:185], v[224:227], v[66:69]
	s_setprio 0
	s_barrier
; #define PG8_STAGE(bufoff, gbase, voff) do { _Pragma("unroll") for (int _i = 0; _i < 2; ++_i) \
;         __builtin_amdgcn_global_load_lds((const unsigned*)((const char*)(gbase) + (voff)[_i]), (LAS unsigned*)(lds + (bufoff) + ldsw + _i * 8192), 16, 0, 0); } while (0)
; #define PG8_LDA(dst, b, h) do { _Pragma("unroll") for (int m = 0; m < 4; ++m) _Pragma("unroll") for (int k = 0; k < 2; ++k) dst[m][k] = *(const LAS bf16x8*)(lds + PG8_SA(b, h) + aoff + m * 2048 + k * 1024); } while (0)
; #define PG8_MMA(ai, bj, At, Bt) do { __builtin_amdgcn_s_setprio(1); _Pragma("unroll") for (int m = 0; m < 4; ++m) _Pragma("unroll") for (int n = 0; n < 2; ++n) _Pragma("unroll") for (int k = 0; k < 2; ++k) \
;         acc[ai][bj][m][n] = __builtin_amdgcn_mfma_f32_16x16x32_bf16(Bt[n][k], At[m][k], acc[ai][bj][m][n], 0, 0, 0); __builtin_amdgcn_s_setprio(0); } while (0)
; #define PG8_WAIT_V(n) asm volatile("s_waitcnt vmcnt(" #n ")" ::: "memory")
; #define PG8_WAIT_L(n) asm volatile("s_waitcnt lgkmcnt(" #n ")" ::: "memory")
; #define PG8_BAR __builtin_amdgcn_s_barrier()
; #define PG8_SCHED __builtin_amdgcn_sched_barrier(0)
; template <class Epi, class Sched>
; DI void gemm_phase(LAS unsigned char* lds, const int K, const Sched& S, const Epi& E) {
;     ...
;             PG8_LDA(At, 1, 1); PG8_STAGE(PG8_SB(1, 0), b3, voffB); PG8_STAGE(PG8_SB(1, 1), b3 + hstep, voffB); PG8_STAGE(PG8_SA(1, 0), a3, voffA);
;             PG8_WAIT_V(8); PG8_WAIT_L(0); PG8_BAR; PG8_MMA(1, 0, At, B0); PG8_MMA(1, 1, At, B1); PG8_BAR; PG8_SCHED;
;         }
;         if (wr == 0) PG8_BAR;
	s_add_i32 s68, s92, s75
	v_lshl_add_u64 v[150:151], v[150:151], 0, s[90:91]
	s_mov_b32 m0, s68
	ds_read_b128 v[190:193], v155 offset:49152
	ds_read_b128 v[194:197], v155 offset:50176
	ds_read_b128 v[198:201], v155 offset:51200
	ds_read_b128 v[202:205], v155 offset:52224
	ds_read_b128 v[212:215], v155 offset:53248
	ds_read_b128 v[216:219], v155 offset:54272
	ds_read_b128 v[220:223], v155 offset:55296
	ds_read_b128 v[224:227], v155 offset:56320
	global_load_lds_dwordx4 v[150:151], off
	s_add_i32 m0, s68, 0x2000
	s_add_u32 s66, s66, 0x40080
	v_lshl_add_u64 v[150:151], v[176:177], 0, s[90:91]
	s_addc_u32 s67, s67, 0
	s_add_i32 s68, s95, s75
	global_load_lds_dwordx4 v[150:151], off
	v_lshl_add_u64 v[150:151], s[66:67], 0, v[132:133]
	s_mov_b32 m0, s68
	s_nop 0
	global_load_lds_dwordx4 v[150:151], off
	v_lshl_add_u64 v[150:151], s[66:67], 0, v[136:137]
	s_add_i32 m0, s68, 0x2000
	s_nop 0
	global_load_lds_dwordx4 v[150:151], off
	s_waitcnt vmcnt(6)
	s_waitcnt lgkmcnt(0)
	s_barrier
	s_setprio 1
	s_waitcnt lgkmcnt(0)
	v_mfma_f32_16x16x32_bf16 v[62:65], v[142:145], v[190:193], v[62:65]
	v_mfma_f32_16x16x32_bf16 v[58:61], v[156:159], v[190:193], v[58:61]
	v_mfma_f32_16x16x32_bf16 v[46:49], v[142:145], v[198:201], v[46:49]
	v_mfma_f32_16x16x32_bf16 v[42:45], v[156:159], v[198:201], v[42:45]
	v_mfma_f32_16x16x32_bf16 v[30:33], v[142:145], v[212:215], v[30:33]
	v_mfma_f32_16x16x32_bf16 v[26:29], v[156:159], v[212:215], v[26:29]
	v_mfma_f32_16x16x32_bf16 v[14:17], v[142:145], v[220:223], v[14:17]
	v_mfma_f32_16x16x32_bf16 v[10:13], v[156:159], v[220:223], v[10:13]
	v_lshl_add_u64 v[150:151], v[228:229], 0, s[90:91]
	s_mov_b32 m0, s83
	s_nop 0
	global_load_lds_dwordx4 v[150:151], off
	v_mfma_f32_16x16x32_bf16 v[62:65], v[146:149], v[194:197], v[62:65]
	v_mfma_f32_16x16x32_bf16 v[58:61], v[160:163], v[194:197], v[58:61]
	v_mfma_f32_16x16x32_bf16 v[46:49], v[146:149], v[202:205], v[46:49]
	v_mfma_f32_16x16x32_bf16 v[42:45], v[160:163], v[202:205], v[42:45]
	v_mfma_f32_16x16x32_bf16 v[30:33], v[146:149], v[216:219], v[30:33]
	v_mfma_f32_16x16x32_bf16 v[26:29], v[160:163], v[216:219], v[26:29]
	v_mfma_f32_16x16x32_bf16 v[14:17], v[146:149], v[224:227], v[14:17]
	v_mfma_f32_16x16x32_bf16 v[10:13], v[160:163], v[224:227], v[10:13]
	s_setprio 0
	s_setprio 1
	v_mfma_f32_16x16x32_bf16 v[54:57], v[164:167], v[190:193], v[54:57]
	v_mfma_f32_16x16x32_bf16 v[50:53], v[172:175], v[190:193], v[50:53]
	v_mfma_f32_16x16x32_bf16 v[38:41], v[164:167], v[198:201], v[38:41]
	v_mfma_f32_16x16x32_bf16 v[34:37], v[172:175], v[198:201], v[34:37]
	v_mfma_f32_16x16x32_bf16 v[22:25], v[164:167], v[212:215], v[22:25]
	v_mfma_f32_16x16x32_bf16 v[18:21], v[172:175], v[212:215], v[18:21]
	v_mfma_f32_16x16x32_bf16 v[6:9], v[164:167], v[220:223], v[6:9]
	v_mfma_f32_16x16x32_bf16 v[2:5], v[172:175], v[220:223], v[2:5]
	v_lshl_add_u64 v[150:151], v[230:231], 0, s[90:91]
	s_mov_b32 m0, s84
	s_nop 0
	global_load_lds_dwordx4 v[150:151], off
	v_mfma_f32_16x16x32_bf16 v[54:57], v[168:171], v[194:197], v[54:57]
	v_mfma_f32_16x16x32_bf16 v[50:53], v[182:185], v[194:197], v[50:53]
	v_mfma_f32_16x16x32_bf16 v[38:41], v[168:171], v[202:205], v[38:41]
	v_mfma_f32_16x16x32_bf16 v[34:37], v[182:185], v[202:205], v[34:37]
	v_mfma_f32_16x16x32_bf16 v[22:25], v[168:171], v[216:219], v[22:25]
	v_mfma_f32_16x16x32_bf16 v[18:21], v[182:185], v[216:219], v[18:21]
	v_mfma_f32_16x16x32_bf16 v[6:9], v[168:171], v[224:227], v[6:9]
	v_mfma_f32_16x16x32_bf16 v[2:5], v[182:185], v[224:227], v[2:5]
	s_setprio 0
	s_barrier
	s_add_i32 s63, s63, 2
	s_add_u32 s55, s55, 0x100
	s_addc_u32 s57, s57, 0
	s_add_u32 s64, s64, 0x100
	s_addc_u32 s65, s65, 0
	s_cmp_gt_u32 s63, 13
	s_cbranch_scc0 .LBB0_648
	s_and_b64 vcc, exec, s[46:47]
	s_cbranch_vccz .LBB0_651
	s_barrier

; #define PG8_STAGE(bufoff, gbase, voff) do { _Pragma("unroll") for (int _i = 0; _i < 2; ++_i) \
;         __builtin_amdgcn_global_load_lds((const unsigned*)((const char*)(gbase) + (voff)[_i]), (LAS unsigned*)(lds + (bufoff) + ldsw + _i * 8192), 16, 0, 0); } while (0)
; #define PG8_LDA(dst, b, h) do { _Pragma("unroll") for (int m = 0; m < 4; ++m) _Pragma("unroll") for (int k = 0; k < 2; ++k) dst[m][k] = *(const LAS bf16x8*)(lds + PG8_SA(b, h) + aoff + m * 2048 + k * 1024); } while (0)
; #define PG8_LDB(dst, b, h) do { _Pragma("unroll") for (int n = 0; n < 2; ++n) _Pragma("unroll") for (int k = 0; k < 2; ++k) dst[n][k] = *(const LAS bf16x8*)(lds + PG8_SB(b, h) + boff + n * 2048 + k * 1024); } while (0)
; #define PG8_MMA(ai, bj, At, Bt) do { __builtin_amdgcn_s_setprio(1); _Pragma("unroll") for (int m = 0; m < 4; ++m) _Pragma("unroll") for (int n = 0; n < 2; ++n) _Pragma("unroll") for (int k = 0; k < 2; ++k) \
;         acc[ai][bj][m][n] = __builtin_amdgcn_mfma_f32_16x16x32_bf16(Bt[n][k], At[m][k], acc[ai][bj][m][n], 0, 0, 0); __builtin_amdgcn_s_setprio(0); } while (0)
; #define PG8_WAIT_V(n) asm volatile("s_waitcnt vmcnt(" #n ")" ::: "memory")
; #define PG8_WAIT_L(n) asm volatile("s_waitcnt lgkmcnt(" #n ")" ::: "memory")
; #define PG8_BAR __builtin_amdgcn_s_barrier()
; #define PG8_SCHED __builtin_amdgcn_sched_barrier(0)
; template <class Epi, class Sched>
; DI void gemm_phase(LAS unsigned char* lds, const int K, const Sched& S, const Epi& E) {
;     ...
;         for (int t = 0; t < nt; t += 2) {
;             const bool last = (t == nt - 2);
;             const char* a1 = cA + (size_t)(t + 1) * kstep;
;             const char* a2 = last ? nA : cA + (size_t)(t + 2) * kstep; const char* b2 = last ? nB : cB + (size_t)(t + 2) * kstep;
;             const char* a3 = a2 + kstep; const char* b3 = b2 + kstep;
;             PG8_LDB(B0, 0, 0); PG8_LDB(B1, 0, 1); PG8_SCHED; PG8_LDA(At, 0, 0); PG8_STAGE(PG8_SA(1, 1), a1 + hstep, voffA);
;             PG8_WAIT_V(8); PG8_WAIT_L(0); PG8_BAR; PG8_MMA(0, 0, At, B0); PG8_MMA(0, 1, At, B1); PG8_BAR; PG8_SCHED;
;             PG8_LDA(At, 0, 1); PG8_STAGE(PG8_SB(0, 0), b2, voffB); PG8_STAGE(PG8_SB(0, 1), b2 + hstep, voffB); PG8_STAGE(PG8_SA(0, 0), a2, voffA);
;             PG8_WAIT_V(8); PG8_WAIT_L(0); PG8_BAR; PG8_MMA(1, 0, At, B0); PG8_MMA(1, 1, At, B1); PG8_BAR; PG8_SCHED;
.LBB0_784:
	s_add_u32 s48, s44, 0xfffc0080
	s_addc_u32 s49, s45, -1
	s_add_i32 s77, 0, 0x10000
	s_cmp_eq_u32 s76, 12
	s_cselect_b32 s75, s69, s49
	s_cselect_b32 s74, s68, s48
	s_cselect_b32 s73, s71, s67
	s_cselect_b32 s72, s70, s65
	s_add_i32 s48, 0, 0x14000
	v_add_u32_e32 v142, s77, v199
	v_add_u32_e32 v158, s48, v199
	ds_read_b128 v[130:133], v142
	ds_read_b128 v[134:137], v142 offset:1024
	ds_read_b128 v[138:141], v142 offset:2048
	ds_read_b128 v[142:145], v142 offset:3072
	ds_read_b128 v[146:149], v158
	ds_read_b128 v[150:153], v158 offset:1024
	ds_read_b128 v[154:157], v158 offset:2048
	ds_read_b128 v[158:161], v158 offset:3072
	v_lshl_add_u64 v[224:225], s[44:45], 0, v[172:173]
	s_add_i32 m0, s80, 0xc000
	ds_read_b128 v[174:177], v200
	ds_read_b128 v[182:185], v200 offset:1024
	ds_read_b128 v[190:193], v200 offset:2048
	ds_read_b128 v[194:197], v200 offset:3072
	ds_read_b128 v[202:205], v200 offset:4096
	ds_read_b128 v[212:215], v200 offset:5120
	ds_read_b128 v[216:219], v200 offset:6144
	ds_read_b128 v[220:223], v200 offset:7168
	global_load_lds_dwordx4 v[224:225], off
	v_lshl_add_u64 v[224:225], s[44:45], 0, v[170:171]
	s_add_i32 m0, s80, 0xe000
	s_nop 0
	global_load_lds_dwordx4 v[224:225], off
	s_waitcnt vmcnt(8)
	s_waitcnt lgkmcnt(0)
	s_barrier
	s_setprio 1
	s_waitcnt lgkmcnt(0)
	v_mfma_f32_16x16x32_bf16 v[126:129], v[130:133], v[174:177], v[126:129]
	v_mfma_f32_16x16x32_bf16 v[122:125], v[138:141], v[174:177], v[122:125]
	v_mfma_f32_16x16x32_bf16 v[118:121], v[130:133], v[190:193], v[118:121]
	v_mfma_f32_16x16x32_bf16 v[114:117], v[138:141], v[190:193], v[114:117]
	v_mfma_f32_16x16x32_bf16 v[110:113], v[130:133], v[202:205], v[110:113]
	v_mfma_f32_16x16x32_bf16 v[106:109], v[138:141], v[202:205], v[106:109]
	v_mfma_f32_16x16x32_bf16 v[102:105], v[130:133], v[216:219], v[102:105]
	v_mfma_f32_16x16x32_bf16 v[98:101], v[138:141], v[216:219], v[98:101]
	v_mfma_f32_16x16x32_bf16 v[126:129], v[134:137], v[182:185], v[126:129]
	v_mfma_f32_16x16x32_bf16 v[122:125], v[142:145], v[182:185], v[122:125]
	v_mfma_f32_16x16x32_bf16 v[118:121], v[134:137], v[194:197], v[118:121]
	v_mfma_f32_16x16x32_bf16 v[114:117], v[142:145], v[194:197], v[114:117]
	v_mfma_f32_16x16x32_bf16 v[110:113], v[134:137], v[212:215], v[110:113]
	v_mfma_f32_16x16x32_bf16 v[106:109], v[142:145], v[212:215], v[106:109]
	v_mfma_f32_16x16x32_bf16 v[102:105], v[134:137], v[220:223], v[102:105]
	v_mfma_f32_16x16x32_bf16 v[98:101], v[142:145], v[220:223], v[98:101]
	s_setprio 0
	s_setprio 1
	v_mfma_f32_16x16x32_bf16 v[94:97], v[146:149], v[174:177], v[94:97]
	v_mfma_f32_16x16x32_bf16 v[90:93], v[154:157], v[174:177], v[90:93]
	v_mfma_f32_16x16x32_bf16 v[86:89], v[146:149], v[190:193], v[86:89]
	v_mfma_f32_16x16x32_bf16 v[82:85], v[154:157], v[190:193], v[82:85]
	v_mfma_f32_16x16x32_bf16 v[78:81], v[146:149], v[202:205], v[78:81]
	v_mfma_f32_16x16x32_bf16 v[74:77], v[154:157], v[202:205], v[74:77]
	v_mfma_f32_16x16x32_bf16 v[70:73], v[146:149], v[216:219], v[70:73]
	v_mfma_f32_16x16x32_bf16 v[66:69], v[154:157], v[216:219], v[66:69]
	v_mfma_f32_16x16x32_bf16 v[94:97], v[150:153], v[182:185], v[94:97]
	v_mfma_f32_16x16x32_bf16 v[90:93], v[158:161], v[182:185], v[90:93]
	v_mfma_f32_16x16x32_bf16 v[86:89], v[150:153], v[194:197], v[86:89]
	v_mfma_f32_16x16x32_bf16 v[82:85], v[158:161], v[194:197], v[82:85]
	v_mfma_f32_16x16x32_bf16 v[78:81], v[150:153], v[212:215], v[78:81]
	v_mfma_f32_16x16x32_bf16 v[74:77], v[158:161], v[212:215], v[74:77]
	v_mfma_f32_16x16x32_bf16 v[70:73], v[150:153], v[220:223], v[70:73]
	v_mfma_f32_16x16x32_bf16 v[66:69], v[158:161], v[220:223], v[66:69]
	s_setprio 0
	s_barrier
	s_add_i32 s49, s77, s79
	v_lshl_add_u64 v[224:225], s[72:73], 0, v[164:165]
	s_mov_b32 m0, s49
	ds_read_b128 v[174:177], v200 offset:16384
	ds_read_b128 v[182:185], v200 offset:17408
	ds_read_b128 v[190:193], v200 offset:18432
	ds_read_b128 v[194:197], v200 offset:19456
	ds_read_b128 v[202:205], v200 offset:20480
	ds_read_b128 v[212:215], v200 offset:21504
	ds_read_b128 v[216:219], v200 offset:22528
	ds_read_b128 v[220:223], v200 offset:23552
	global_load_lds_dwordx4 v[224:225], off
	s_add_i32 m0, s49, 0x2000
	s_add_u32 vcc_lo, s72, 0x40000
	v_lshl_add_u64 v[226:227], s[72:73], 0, v[168:169]
	s_addc_u32 vcc_hi, s73, 0
	s_add_i32 s48, s48, s79
	global_load_lds_dwordx4 v[226:227], off
	v_lshl_add_u64 v[228:229], vcc, 0, v[164:165]
	s_mov_b32 m0, s48
	v_lshl_add_u64 v[230:231], s[74:75], 0, v[166:167]
	global_load_lds_dwordx4 v[228:229], off
	v_lshl_add_u64 v[228:229], vcc, 0, v[168:169]
	s_add_i32 m0, s48, 0x2000
	s_nop 0
	global_load_lds_dwordx4 v[228:229], off
	s_waitcnt vmcnt(6)
	s_waitcnt lgkmcnt(0)
	s_barrier
; #define PG8_STAGE(bufoff, gbase, voff) do { _Pragma("unroll") for (int _i = 0; _i < 2; ++_i) \
;         __builtin_amdgcn_global_load_lds((const unsigned*)((const char*)(gbase) + (voff)[_i]), (LAS unsigned*)(lds + (bufoff) + ldsw + _i * 8192), 16, 0, 0); } while (0)
; #define PG8_LDA(dst, b, h) do { _Pragma("unroll") for (int m = 0; m < 4; ++m) _Pragma("unroll") for (int k = 0; k < 2; ++k) dst[m][k] = *(const LAS bf16x8*)(lds + PG8_SA(b, h) + aoff + m * 2048 + k * 1024); } while (0)
; #define PG8_LDB(dst, b, h) do { _Pragma("unroll") for (int n = 0; n < 2; ++n) _Pragma("unroll") for (int k = 0; k < 2; ++k) dst[n][k] = *(const LAS bf16x8*)(lds + PG8_SB(b, h) + boff + n * 2048 + k * 1024); } while (0)
; #define PG8_MMA(ai, bj, At, Bt) do { __builtin_amdgcn_s_setprio(1); _Pragma("unroll") for (int m = 0; m < 4; ++m) _Pragma("unroll") for (int n = 0; n < 2; ++n) _Pragma("unroll") for (int k = 0; k < 2; ++k) \
;         acc[ai][bj][m][n] = __builtin_amdgcn_mfma_f32_16x16x32_bf16(Bt[n][k], At[m][k], acc[ai][bj][m][n], 0, 0, 0); __builtin_amdgcn_s_setprio(0); } while (0)
; #define PG8_WAIT_V(n) asm volatile("s_waitcnt vmcnt(" #n ")" ::: "memory")
; #define PG8_WAIT_L(n) asm volatile("s_waitcnt lgkmcnt(" #n ")" ::: "memory")
; #define PG8_BAR __builtin_amdgcn_s_barrier()
; #define PG8_SCHED __builtin_amdgcn_sched_barrier(0)
; template <class Epi, class Sched>
; DI void gemm_phase(LAS unsigned char* lds, const int K, const Sched& S, const Epi& E) {
;     ...
;             PG8_WAIT_V(8); PG8_WAIT_L(0); PG8_BAR; PG8_MMA(1, 0, At, B0); PG8_MMA(1, 1, At, B1); PG8_BAR; PG8_SCHED;
;             PG8_LDB(B0, 1, 0); PG8_LDB(B1, 1, 1); PG8_SCHED; PG8_LDA(At, 1, 0); PG8_STAGE(PG8_SA(0, 1), a2 + hstep, voffA);
;             PG8_WAIT_V(8); PG8_WAIT_L(0); PG8_BAR; PG8_MMA(0, 0, At, B0); PG8_MMA(0, 1, At, B1); PG8_BAR; PG8_SCHED;
	s_setprio 1
	s_waitcnt lgkmcnt(0)
	v_mfma_f32_16x16x32_bf16 v[62:65], v[130:133], v[174:177], v[62:65]
	v_mfma_f32_16x16x32_bf16 v[58:61], v[138:141], v[174:177], v[58:61]
	v_mfma_f32_16x16x32_bf16 v[54:57], v[130:133], v[190:193], v[54:57]
	v_mfma_f32_16x16x32_bf16 v[50:53], v[138:141], v[190:193], v[50:53]
	v_mfma_f32_16x16x32_bf16 v[46:49], v[130:133], v[202:205], v[46:49]
	v_mfma_f32_16x16x32_bf16 v[42:45], v[138:141], v[202:205], v[42:45]
	v_mfma_f32_16x16x32_bf16 v[38:41], v[130:133], v[216:219], v[38:41]
	v_mfma_f32_16x16x32_bf16 v[34:37], v[138:141], v[216:219], v[34:37]
	v_lshl_add_u64 v[228:229], s[74:75], 0, v[162:163]
	s_mov_b32 m0, s80
	s_nop 0
	global_load_lds_dwordx4 v[228:229], off
	v_mfma_f32_16x16x32_bf16 v[62:65], v[134:137], v[182:185], v[62:65]
	v_mfma_f32_16x16x32_bf16 v[58:61], v[142:145], v[182:185], v[58:61]
	v_mfma_f32_16x16x32_bf16 v[54:57], v[134:137], v[194:197], v[54:57]
	v_mfma_f32_16x16x32_bf16 v[50:53], v[142:145], v[194:197], v[50:53]
	v_mfma_f32_16x16x32_bf16 v[46:49], v[134:137], v[212:215], v[46:49]
	v_mfma_f32_16x16x32_bf16 v[42:45], v[142:145], v[212:215], v[42:45]
	v_mfma_f32_16x16x32_bf16 v[38:41], v[134:137], v[220:223], v[38:41]
	v_mfma_f32_16x16x32_bf16 v[34:37], v[142:145], v[220:223], v[34:37]
	s_setprio 0
	s_setprio 1
	v_mfma_f32_16x16x32_bf16 v[30:33], v[146:149], v[174:177], v[30:33]
	v_mfma_f32_16x16x32_bf16 v[26:29], v[154:157], v[174:177], v[26:29]
	v_mfma_f32_16x16x32_bf16 v[22:25], v[146:149], v[190:193], v[22:25]
	v_mfma_f32_16x16x32_bf16 v[18:21], v[154:157], v[190:193], v[18:21]
	v_mfma_f32_16x16x32_bf16 v[14:17], v[146:149], v[202:205], v[14:17]
	v_mfma_f32_16x16x32_bf16 v[10:13], v[154:157], v[202:205], v[10:13]
	v_mfma_f32_16x16x32_bf16 v[6:9], v[146:149], v[216:219], v[6:9]
	v_mfma_f32_16x16x32_bf16 v[2:5], v[154:157], v[216:219], v[2:5]
	s_mov_b32 m0, s81
	s_nop 0
	global_load_lds_dwordx4 v[230:231], off
	v_mfma_f32_16x16x32_bf16 v[30:33], v[150:153], v[182:185], v[30:33]
	v_mfma_f32_16x16x32_bf16 v[26:29], v[158:161], v[182:185], v[26:29]
	v_mfma_f32_16x16x32_bf16 v[22:25], v[150:153], v[194:197], v[22:25]
	v_mfma_f32_16x16x32_bf16 v[18:21], v[158:161], v[194:197], v[18:21]
	v_mfma_f32_16x16x32_bf16 v[14:17], v[150:153], v[212:215], v[14:17]
	v_mfma_f32_16x16x32_bf16 v[10:13], v[158:161], v[212:215], v[10:13]
	v_mfma_f32_16x16x32_bf16 v[6:9], v[150:153], v[220:223], v[6:9]
	v_mfma_f32_16x16x32_bf16 v[2:5], v[158:161], v[220:223], v[2:5]
	s_setprio 0
	s_barrier
	s_add_i32 s48, 0, 0x18000
	s_add_i32 s49, 0, 0x1c000
	v_add_u32_e32 v142, s48, v199
	v_add_u32_e32 v158, s49, v199
	ds_read_b128 v[130:133], v142
	ds_read_b128 v[134:137], v142 offset:1024
	ds_read_b128 v[138:141], v142 offset:2048
	ds_read_b128 v[142:145], v142 offset:3072
	ds_read_b128 v[146:149], v158
	ds_read_b128 v[150:153], v158 offset:1024
	ds_read_b128 v[154:157], v158 offset:2048
	ds_read_b128 v[158:161], v158 offset:3072
	s_add_u32 s74, s74, 0x40000
	s_addc_u32 s75, s75, 0
	s_mov_b32 m0, s85
	v_lshl_add_u64 v[232:233], s[74:75], 0, v[162:163]
	ds_read_b128 v[174:177], v200 offset:32768
	ds_read_b128 v[182:185], v200 offset:33792
	ds_read_b128 v[190:193], v200 offset:34816
	ds_read_b128 v[194:197], v200 offset:35840
	ds_read_b128 v[202:205], v200 offset:36864
	ds_read_b128 v[212:215], v200 offset:37888
	ds_read_b128 v[216:219], v200 offset:38912
	ds_read_b128 v[220:223], v200 offset:39936
	global_load_lds_dwordx4 v[232:233], off
	v_lshl_add_u64 v[232:233], s[74:75], 0, v[166:167]
	s_mov_b32 m0, s86
	s_nop 0
	global_load_lds_dwordx4 v[232:233], off
	s_waitcnt vmcnt(8)
	s_waitcnt lgkmcnt(0)
	s_barrier
	s_setprio 1
	s_waitcnt lgkmcnt(0)
	v_mfma_f32_16x16x32_bf16 v[126:129], v[130:133], v[174:177], v[126:129]
	v_mfma_f32_16x16x32_bf16 v[122:125], v[138:141], v[174:177], v[122:125]
	v_mfma_f32_16x16x32_bf16 v[118:121], v[130:133], v[190:193], v[118:121]
	v_mfma_f32_16x16x32_bf16 v[114:117], v[138:141], v[190:193], v[114:117]
	v_mfma_f32_16x16x32_bf16 v[110:113], v[130:133], v[202:205], v[110:113]
	v_mfma_f32_16x16x32_bf16 v[106:109], v[138:141], v[202:205], v[106:109]
	v_mfma_f32_16x16x32_bf16 v[102:105], v[130:133], v[216:219], v[102:105]
	v_mfma_f32_16x16x32_bf16 v[98:101], v[138:141], v[216:219], v[98:101]
	v_mfma_f32_16x16x32_bf16 v[126:129], v[134:137], v[182:185], v[126:129]
	v_mfma_f32_16x16x32_bf16 v[122:125], v[142:145], v[182:185], v[122:125]
	v_mfma_f32_16x16x32_bf16 v[118:121], v[134:137], v[194:197], v[118:121]
	v_mfma_f32_16x16x32_bf16 v[114:117], v[142:145], v[194:197], v[114:117]
	v_mfma_f32_16x16x32_bf16 v[110:113], v[134:137], v[212:215], v[110:113]
	v_mfma_f32_16x16x32_bf16 v[106:109], v[142:145], v[212:215], v[106:109]
	v_mfma_f32_16x16x32_bf16 v[102:105], v[134:137], v[220:223], v[102:105]
	v_mfma_f32_16x16x32_bf16 v[98:101], v[142:145], v[220:223], v[98:101]
	s_setprio 0
	s_setprio 1
	v_mfma_f32_16x16x32_bf16 v[94:97], v[146:149], v[174:177], v[94:97]
	v_mfma_f32_16x16x32_bf16 v[90:93], v[154:157], v[174:177], v[90:93]
	v_mfma_f32_16x16x32_bf16 v[86:89], v[146:149], v[190:193], v[86:89]
	v_mfma_f32_16x16x32_bf16 v[82:85], v[154:157], v[190:193], v[82:85]
	v_mfma_f32_16x16x32_bf16 v[78:81], v[146:149], v[202:205], v[78:81]
	v_mfma_f32_16x16x32_bf16 v[74:77], v[154:157], v[202:205], v[74:77]
	v_mfma_f32_16x16x32_bf16 v[70:73], v[146:149], v[216:219], v[70:73]
	v_mfma_f32_16x16x32_bf16 v[66:69], v[154:157], v[216:219], v[66:69]
	v_mfma_f32_16x16x32_bf16 v[94:97], v[150:153], v[182:185], v[94:97]
	v_mfma_f32_16x16x32_bf16 v[90:93], v[158:161], v[182:185], v[90:93]
	v_mfma_f32_16x16x32_bf16 v[86:89], v[150:153], v[194:197], v[86:89]
	v_mfma_f32_16x16x32_bf16 v[82:85], v[158:161], v[194:197], v[82:85]
	v_mfma_f32_16x16x32_bf16 v[78:81], v[150:153], v[212:215], v[78:81]
	v_mfma_f32_16x16x32_bf16 v[74:77], v[158:161], v[212:215], v[74:77]
	v_mfma_f32_16x16x32_bf16 v[70:73], v[150:153], v[220:223], v[70:73]
	v_mfma_f32_16x16x32_bf16 v[66:69], v[158:161], v[220:223], v[66:69]
	s_setprio 0
	s_barrier
; #define PG8_STAGE(bufoff, gbase, voff) do { _Pragma("unroll") for (int _i = 0; _i < 2; ++_i) \
;         __builtin_amdgcn_global_load_lds((const unsigned*)((const char*)(gbase) + (voff)[_i]), (LAS unsigned*)(lds + (bufoff) + ldsw + _i * 8192), 16, 0, 0); } while (0)
; #define PG8_LDA(dst, b, h) do { _Pragma("unroll") for (int m = 0; m < 4; ++m) _Pragma("unroll") for (int k = 0; k < 2; ++k) dst[m][k] = *(const LAS bf16x8*)(lds + PG8_SA(b, h) + aoff + m * 2048 + k * 1024); } while (0)
; #define PG8_MMA(ai, bj, At, Bt) do { __builtin_amdgcn_s_setprio(1); _Pragma("unroll") for (int m = 0; m < 4; ++m) _Pragma("unroll") for (int n = 0; n < 2; ++n) _Pragma("unroll") for (int k = 0; k < 2; ++k) \
;         acc[ai][bj][m][n] = __builtin_amdgcn_mfma_f32_16x16x32_bf16(Bt[n][k], At[m][k], acc[ai][bj][m][n], 0, 0, 0); __builtin_amdgcn_s_setprio(0); } while (0)
; #define PG8_WAIT_V(n) asm volatile("s_waitcnt vmcnt(" #n ")" ::: "memory")
; #define PG8_WAIT_L(n) asm volatile("s_waitcnt lgkmcnt(" #n ")" ::: "memory")
; #define PG8_BAR __builtin_amdgcn_s_barrier()
; #define PG8_SCHED __builtin_amdgcn_sched_barrier(0)
; template <class Epi, class Sched>
; DI void gemm_phase(LAS unsigned char* lds, const int K, const Sched& S, const Epi& E) {
;     ...
;             PG8_LDA(At, 1, 1); PG8_STAGE(PG8_SB(1, 0), b3, voffB); PG8_STAGE(PG8_SB(1, 1), b3 + hstep, voffB); PG8_STAGE(PG8_SA(1, 0), a3, voffA);
;             PG8_WAIT_V(8); PG8_WAIT_L(0); PG8_BAR; PG8_MMA(1, 0, At, B0); PG8_MMA(1, 1, At, B1); PG8_BAR; PG8_SCHED;
;         }
;         if (wr == 0) PG8_BAR;
	s_add_i32 s48, s48, s79
	v_lshl_add_u64 v[224:225], v[224:225], 0, s[90:91]
	s_mov_b32 m0, s48
	ds_read_b128 v[174:177], v200 offset:49152
	ds_read_b128 v[182:185], v200 offset:50176
	ds_read_b128 v[190:193], v200 offset:51200
	ds_read_b128 v[194:197], v200 offset:52224
	ds_read_b128 v[202:205], v200 offset:53248
	ds_read_b128 v[212:215], v200 offset:54272
	ds_read_b128 v[216:219], v200 offset:55296
	ds_read_b128 v[220:223], v200 offset:56320
	global_load_lds_dwordx4 v[224:225], off
	s_add_i32 m0, s48, 0x2000
	s_add_u32 s72, s72, 0x40080
	v_lshl_add_u64 v[224:225], v[226:227], 0, s[90:91]
	s_addc_u32 s73, s73, 0
	s_add_i32 s48, s49, s79
	global_load_lds_dwordx4 v[224:225], off
	v_lshl_add_u64 v[224:225], s[72:73], 0, v[164:165]
	s_mov_b32 m0, s48
	s_nop 0
	global_load_lds_dwordx4 v[224:225], off
	v_lshl_add_u64 v[224:225], s[72:73], 0, v[168:169]
	s_add_i32 m0, s48, 0x2000
	s_nop 0
	global_load_lds_dwordx4 v[224:225], off
	s_waitcnt vmcnt(6)
	s_waitcnt lgkmcnt(0)
	s_barrier
	s_setprio 1
	s_waitcnt lgkmcnt(0)
	v_mfma_f32_16x16x32_bf16 v[62:65], v[130:133], v[174:177], v[62:65]
	v_mfma_f32_16x16x32_bf16 v[58:61], v[138:141], v[174:177], v[58:61]
	v_mfma_f32_16x16x32_bf16 v[54:57], v[130:133], v[190:193], v[54:57]
	v_mfma_f32_16x16x32_bf16 v[50:53], v[138:141], v[190:193], v[50:53]
	v_mfma_f32_16x16x32_bf16 v[46:49], v[130:133], v[202:205], v[46:49]
	v_mfma_f32_16x16x32_bf16 v[42:45], v[138:141], v[202:205], v[42:45]
	v_mfma_f32_16x16x32_bf16 v[38:41], v[130:133], v[216:219], v[38:41]
	v_mfma_f32_16x16x32_bf16 v[34:37], v[138:141], v[216:219], v[34:37]
	v_lshl_add_u64 v[224:225], v[228:229], 0, s[90:91]
	s_mov_b32 m0, s94
	s_nop 0
	global_load_lds_dwordx4 v[224:225], off
	v_mfma_f32_16x16x32_bf16 v[62:65], v[134:137], v[182:185], v[62:65]
	v_mfma_f32_16x16x32_bf16 v[58:61], v[142:145], v[182:185], v[58:61]
	v_mfma_f32_16x16x32_bf16 v[54:57], v[134:137], v[194:197], v[54:57]
	v_mfma_f32_16x16x32_bf16 v[50:53], v[142:145], v[194:197], v[50:53]
	v_mfma_f32_16x16x32_bf16 v[46:49], v[134:137], v[212:215], v[46:49]
	v_mfma_f32_16x16x32_bf16 v[42:45], v[142:145], v[212:215], v[42:45]
	v_mfma_f32_16x16x32_bf16 v[38:41], v[134:137], v[220:223], v[38:41]
	v_mfma_f32_16x16x32_bf16 v[34:37], v[142:145], v[220:223], v[34:37]
	s_setprio 0
	s_setprio 1
	v_mfma_f32_16x16x32_bf16 v[30:33], v[146:149], v[174:177], v[30:33]
	v_mfma_f32_16x16x32_bf16 v[26:29], v[154:157], v[174:177], v[26:29]
	v_mfma_f32_16x16x32_bf16 v[22:25], v[146:149], v[190:193], v[22:25]
	v_mfma_f32_16x16x32_bf16 v[18:21], v[154:157], v[190:193], v[18:21]
	v_mfma_f32_16x16x32_bf16 v[14:17], v[146:149], v[202:205], v[14:17]
	v_mfma_f32_16x16x32_bf16 v[10:13], v[154:157], v[202:205], v[10:13]
	v_mfma_f32_16x16x32_bf16 v[6:9], v[146:149], v[216:219], v[6:9]
	v_mfma_f32_16x16x32_bf16 v[2:5], v[154:157], v[216:219], v[2:5]
	v_lshl_add_u64 v[224:225], v[230:231], 0, s[90:91]
	s_mov_b32 m0, s95
	s_nop 0
	global_load_lds_dwordx4 v[224:225], off
	v_mfma_f32_16x16x32_bf16 v[30:33], v[150:153], v[182:185], v[30:33]
	v_mfma_f32_16x16x32_bf16 v[26:29], v[158:161], v[182:185], v[26:29]
	v_mfma_f32_16x16x32_bf16 v[22:25], v[150:153], v[194:197], v[22:25]
	v_mfma_f32_16x16x32_bf16 v[18:21], v[158:161], v[194:197], v[18:21]
	v_mfma_f32_16x16x32_bf16 v[14:17], v[150:153], v[212:215], v[14:17]
	v_mfma_f32_16x16x32_bf16 v[10:13], v[158:161], v[212:215], v[10:13]
	v_mfma_f32_16x16x32_bf16 v[6:9], v[150:153], v[220:223], v[6:9]
	v_mfma_f32_16x16x32_bf16 v[2:5], v[158:161], v[220:223], v[2:5]
	s_setprio 0
	s_barrier
	s_add_i32 s76, s76, 2
	s_add_u32 s65, s65, 0x100
	s_addc_u32 s67, s67, 0
	s_add_u32 s44, s44, 0x100
	s_addc_u32 s45, s45, 0
	s_cmp_gt_u32 s76, 13
	s_cbranch_scc0 .LBB0_784
	s_and_b64 vcc, exec, s[58:59]
	s_cbranch_vccz .LBB0_787
	s_barrier

; #define PG8_STAGE(bufoff, gbase, voff) do { _Pragma("unroll") for (int _i = 0; _i < 2; ++_i) \
;         __builtin_amdgcn_global_load_lds((const unsigned*)((const char*)(gbase) + (voff)[_i]), (LAS unsigned*)(lds + (bufoff) + ldsw + _i * 8192), 16, 0, 0); } while (0)
; #define PG8_LDA(dst, b, h) do { _Pragma("unroll") for (int m = 0; m < 4; ++m) _Pragma("unroll") for (int k = 0; k < 2; ++k) dst[m][k] = *(const LAS bf16x8*)(lds + PG8_SA(b, h) + aoff + m * 2048 + k * 1024); } while (0)
; #define PG8_LDB(dst, b, h) do { _Pragma("unroll") for (int n = 0; n < 2; ++n) _Pragma("unroll") for (int k = 0; k < 2; ++k) dst[n][k] = *(const LAS bf16x8*)(lds + PG8_SB(b, h) + boff + n * 2048 + k * 1024); } while (0)
; #define PG8_MMA(ai, bj, At, Bt) do { __builtin_amdgcn_s_setprio(1); _Pragma("unroll") for (int m = 0; m < 4; ++m) _Pragma("unroll") for (int n = 0; n < 2; ++n) _Pragma("unroll") for (int k = 0; k < 2; ++k) \
;         acc[ai][bj][m][n] = __builtin_amdgcn_mfma_f32_16x16x32_bf16(Bt[n][k], At[m][k], acc[ai][bj][m][n], 0, 0, 0); __builtin_amdgcn_s_setprio(0); } while (0)
; #define PG8_WAIT_V(n) asm volatile("s_waitcnt vmcnt(" #n ")" ::: "memory")
; #define PG8_WAIT_L(n) asm volatile("s_waitcnt lgkmcnt(" #n ")" ::: "memory")
; #define PG8_BAR __builtin_amdgcn_s_barrier()
; #define PG8_SCHED __builtin_amdgcn_sched_barrier(0)
; template <class Epi, class Sched>
; DI void gemm_phase(LAS unsigned char* lds, const int K, const Sched& S, const Epi& E) {
;     ...
;         for (int t = 0; t < nt; t += 2) {
;             const bool last = (t == nt - 2);
;             const char* a1 = cA + (size_t)(t + 1) * kstep;
;             const char* a2 = last ? nA : cA + (size_t)(t + 2) * kstep; const char* b2 = last ? nB : cB + (size_t)(t + 2) * kstep;
;             const char* a3 = a2 + kstep; const char* b3 = b2 + kstep;
;             PG8_LDB(B0, 0, 0); PG8_LDB(B1, 0, 1); PG8_SCHED; PG8_LDA(At, 0, 0); PG8_STAGE(PG8_SA(1, 1), a1 + hstep, voffA);
;             PG8_WAIT_V(8); PG8_WAIT_L(0); PG8_BAR; PG8_MMA(0, 0, At, B0); PG8_MMA(0, 1, At, B1); PG8_BAR; PG8_SCHED;
;             PG8_LDA(At, 0, 1); PG8_STAGE(PG8_SB(0, 0), b2, voffB); PG8_STAGE(PG8_SB(0, 1), b2 + hstep, voffB); PG8_STAGE(PG8_SA(0, 0), a2, voffA);
;             PG8_WAIT_V(8); PG8_WAIT_L(0); PG8_BAR; PG8_MMA(1, 0, At, B0); PG8_MMA(1, 1, At, B1); PG8_BAR; PG8_SCHED;
.LBB0_945:
	s_add_u32 s48, s62, 0xfffc0080
	s_addc_u32 s49, s63, -1
	s_add_i32 s84, 0, 0x10000
	s_cmp_eq_u32 s83, 12
	s_cselect_b32 s67, s59, s49
	s_cselect_b32 s66, s58, s48
	v_add_u32_e32 v145, s84, v143
	s_cselect_b32 s65, s61, s57
	s_cselect_b32 s64, s60, s55
	s_add_i32 s48, 0, 0x14000
	ds_read_b128 v[146:149], v145
	ds_read_b128 v[150:153], v145 offset:1024
	ds_read_b128 v[154:157], v145 offset:2048
	ds_read_b128 v[158:161], v145 offset:3072
	v_add_u32_e32 v145, s48, v143
	ds_read_b128 v[162:165], v145
	ds_read_b128 v[166:169], v145 offset:1024
	ds_read_b128 v[170:173], v145 offset:2048
	ds_read_b128 v[174:177], v145 offset:3072
	v_lshl_add_u64 v[224:225], s[62:63], 0, v[140:141]
	s_add_i32 m0, s53, 0xc000
	ds_read_b128 v[182:185], v144
	ds_read_b128 v[190:193], v144 offset:1024
	ds_read_b128 v[194:197], v144 offset:2048
	ds_read_b128 v[198:201], v144 offset:3072
	ds_read_b128 v[202:205], v144 offset:4096
	ds_read_b128 v[212:215], v144 offset:5120
	ds_read_b128 v[216:219], v144 offset:6144
	ds_read_b128 v[220:223], v144 offset:7168
	global_load_lds_dwordx4 v[224:225], off
	v_lshl_add_u64 v[224:225], s[62:63], 0, v[138:139]
	s_add_i32 m0, s53, 0xe000
	s_nop 0
	global_load_lds_dwordx4 v[224:225], off
	s_waitcnt vmcnt(8)
	s_waitcnt lgkmcnt(0)
	s_barrier
	s_setprio 1
	s_waitcnt lgkmcnt(0)
	v_mfma_f32_16x16x32_bf16 v[126:129], v[146:149], v[182:185], v[126:129]
	v_mfma_f32_16x16x32_bf16 v[122:125], v[154:157], v[182:185], v[122:125]
	v_mfma_f32_16x16x32_bf16 v[118:121], v[146:149], v[194:197], v[118:121]
	v_mfma_f32_16x16x32_bf16 v[114:117], v[154:157], v[194:197], v[114:117]
	v_mfma_f32_16x16x32_bf16 v[102:105], v[146:149], v[202:205], v[102:105]
	v_mfma_f32_16x16x32_bf16 v[98:101], v[154:157], v[202:205], v[98:101]
	v_mfma_f32_16x16x32_bf16 v[86:89], v[146:149], v[216:219], v[86:89]
	v_mfma_f32_16x16x32_bf16 v[82:85], v[154:157], v[216:219], v[82:85]
	v_mfma_f32_16x16x32_bf16 v[126:129], v[150:153], v[190:193], v[126:129]
	v_mfma_f32_16x16x32_bf16 v[122:125], v[158:161], v[190:193], v[122:125]
	v_mfma_f32_16x16x32_bf16 v[118:121], v[150:153], v[198:201], v[118:121]
	v_mfma_f32_16x16x32_bf16 v[114:117], v[158:161], v[198:201], v[114:117]
	v_mfma_f32_16x16x32_bf16 v[102:105], v[150:153], v[212:215], v[102:105]
	v_mfma_f32_16x16x32_bf16 v[98:101], v[158:161], v[212:215], v[98:101]
	v_mfma_f32_16x16x32_bf16 v[86:89], v[150:153], v[220:223], v[86:89]
	v_mfma_f32_16x16x32_bf16 v[82:85], v[158:161], v[220:223], v[82:85]
	s_setprio 0
	s_setprio 1
	v_mfma_f32_16x16x32_bf16 v[110:113], v[162:165], v[182:185], v[110:113]
	v_mfma_f32_16x16x32_bf16 v[106:109], v[170:173], v[182:185], v[106:109]
	v_mfma_f32_16x16x32_bf16 v[94:97], v[162:165], v[194:197], v[94:97]
	v_mfma_f32_16x16x32_bf16 v[90:93], v[170:173], v[194:197], v[90:93]
	v_mfma_f32_16x16x32_bf16 v[78:81], v[162:165], v[202:205], v[78:81]
	v_mfma_f32_16x16x32_bf16 v[74:77], v[170:173], v[202:205], v[74:77]
	v_mfma_f32_16x16x32_bf16 v[70:73], v[162:165], v[216:219], v[70:73]
	v_mfma_f32_16x16x32_bf16 v[66:69], v[170:173], v[216:219], v[66:69]
	v_mfma_f32_16x16x32_bf16 v[110:113], v[166:169], v[190:193], v[110:113]
	v_mfma_f32_16x16x32_bf16 v[106:109], v[174:177], v[190:193], v[106:109]
	v_mfma_f32_16x16x32_bf16 v[94:97], v[166:169], v[198:201], v[94:97]
	v_mfma_f32_16x16x32_bf16 v[90:93], v[174:177], v[198:201], v[90:93]
	v_mfma_f32_16x16x32_bf16 v[78:81], v[166:169], v[212:215], v[78:81]
	v_mfma_f32_16x16x32_bf16 v[74:77], v[174:177], v[212:215], v[74:77]
	v_mfma_f32_16x16x32_bf16 v[70:73], v[166:169], v[220:223], v[70:73]
	v_mfma_f32_16x16x32_bf16 v[66:69], v[174:177], v[220:223], v[66:69]
	s_setprio 0
	s_barrier
	s_add_i32 s49, s84, s71
	v_lshl_add_u64 v[224:225], s[64:65], 0, v[134:135]
	s_mov_b32 m0, s49
	ds_read_b128 v[182:185], v144 offset:16384
	ds_read_b128 v[190:193], v144 offset:17408
	ds_read_b128 v[194:197], v144 offset:18432
	ds_read_b128 v[198:201], v144 offset:19456
	ds_read_b128 v[202:205], v144 offset:20480
	ds_read_b128 v[212:215], v144 offset:21504
	ds_read_b128 v[216:219], v144 offset:22528
	ds_read_b128 v[220:223], v144 offset:23552
	global_load_lds_dwordx4 v[224:225], off
	s_add_i32 m0, s49, 0x2000
	s_add_u32 s84, s64, 0x40000
	v_lshl_add_u64 v[226:227], s[64:65], 0, v[130:131]
	s_addc_u32 s85, s65, 0
	s_add_i32 s48, s48, s71
	global_load_lds_dwordx4 v[226:227], off
	v_lshl_add_u64 v[228:229], s[84:85], 0, v[134:135]
	s_mov_b32 m0, s48
	v_lshl_add_u64 v[230:231], s[66:67], 0, v[132:133]
	global_load_lds_dwordx4 v[228:229], off
	v_lshl_add_u64 v[228:229], s[84:85], 0, v[130:131]
	s_add_i32 m0, s48, 0x2000
	s_nop 0
	global_load_lds_dwordx4 v[228:229], off
	s_waitcnt vmcnt(6)
	s_waitcnt lgkmcnt(0)
	s_barrier
; #define PG8_STAGE(bufoff, gbase, voff) do { _Pragma("unroll") for (int _i = 0; _i < 2; ++_i) \
;         __builtin_amdgcn_global_load_lds((const unsigned*)((const char*)(gbase) + (voff)[_i]), (LAS unsigned*)(lds + (bufoff) + ldsw + _i * 8192), 16, 0, 0); } while (0)
; #define PG8_LDA(dst, b, h) do { _Pragma("unroll") for (int m = 0; m < 4; ++m) _Pragma("unroll") for (int k = 0; k < 2; ++k) dst[m][k] = *(const LAS bf16x8*)(lds + PG8_SA(b, h) + aoff + m * 2048 + k * 1024); } while (0)
; #define PG8_LDB(dst, b, h) do { _Pragma("unroll") for (int n = 0; n < 2; ++n) _Pragma("unroll") for (int k = 0; k < 2; ++k) dst[n][k] = *(const LAS bf16x8*)(lds + PG8_SB(b, h) + boff + n * 2048 + k * 1024); } while (0)
; #define PG8_MMA(ai, bj, At, Bt) do { __builtin_amdgcn_s_setprio(1); _Pragma("unroll") for (int m = 0; m < 4; ++m) _Pragma("unroll") for (int n = 0; n < 2; ++n) _Pragma("unroll") for (int k = 0; k < 2; ++k) \
;         acc[ai][bj][m][n] = __builtin_amdgcn_mfma_f32_16x16x32_bf16(Bt[n][k], At[m][k], acc[ai][bj][m][n], 0, 0, 0); __builtin_amdgcn_s_setprio(0); } while (0)
; #define PG8_WAIT_V(n) asm volatile("s_waitcnt vmcnt(" #n ")" ::: "memory")
; #define PG8_WAIT_L(n) asm volatile("s_waitcnt lgkmcnt(" #n ")" ::: "memory")
; #define PG8_BAR __builtin_amdgcn_s_barrier()
; #define PG8_SCHED __builtin_amdgcn_sched_barrier(0)
; template <class Epi, class Sched>
; DI void gemm_phase(LAS unsigned char* lds, const int K, const Sched& S, const Epi& E) {
;     ...
;             PG8_WAIT_V(8); PG8_WAIT_L(0); PG8_BAR; PG8_MMA(1, 0, At, B0); PG8_MMA(1, 1, At, B1); PG8_BAR; PG8_SCHED;
;             PG8_LDB(B0, 1, 0); PG8_LDB(B1, 1, 1); PG8_SCHED; PG8_LDA(At, 1, 0); PG8_STAGE(PG8_SA(0, 1), a2 + hstep, voffA);
;             PG8_WAIT_V(8); PG8_WAIT_L(0); PG8_BAR; PG8_MMA(0, 0, At, B0); PG8_MMA(0, 1, At, B1); PG8_BAR; PG8_SCHED;
	s_setprio 1
	s_waitcnt lgkmcnt(0)
	v_mfma_f32_16x16x32_bf16 v[62:65], v[146:149], v[182:185], v[62:65]
	v_mfma_f32_16x16x32_bf16 v[58:61], v[154:157], v[182:185], v[58:61]
	v_mfma_f32_16x16x32_bf16 v[54:57], v[146:149], v[194:197], v[54:57]
	v_mfma_f32_16x16x32_bf16 v[50:53], v[154:157], v[194:197], v[50:53]
	v_mfma_f32_16x16x32_bf16 v[38:41], v[146:149], v[202:205], v[38:41]
	v_mfma_f32_16x16x32_bf16 v[34:37], v[154:157], v[202:205], v[34:37]
	v_mfma_f32_16x16x32_bf16 v[22:25], v[146:149], v[216:219], v[22:25]
	v_mfma_f32_16x16x32_bf16 v[18:21], v[154:157], v[216:219], v[18:21]
	v_lshl_add_u64 v[228:229], s[66:67], 0, v[136:137]
	s_mov_b32 m0, s53
	s_nop 0
	global_load_lds_dwordx4 v[228:229], off
	v_mfma_f32_16x16x32_bf16 v[62:65], v[150:153], v[190:193], v[62:65]
	v_mfma_f32_16x16x32_bf16 v[58:61], v[158:161], v[190:193], v[58:61]
	v_mfma_f32_16x16x32_bf16 v[54:57], v[150:153], v[198:201], v[54:57]
	v_mfma_f32_16x16x32_bf16 v[50:53], v[158:161], v[198:201], v[50:53]
	v_mfma_f32_16x16x32_bf16 v[38:41], v[150:153], v[212:215], v[38:41]
	v_mfma_f32_16x16x32_bf16 v[34:37], v[158:161], v[212:215], v[34:37]
	v_mfma_f32_16x16x32_bf16 v[22:25], v[150:153], v[220:223], v[22:25]
	v_mfma_f32_16x16x32_bf16 v[18:21], v[158:161], v[220:223], v[18:21]
	s_setprio 0
	s_setprio 1
	v_mfma_f32_16x16x32_bf16 v[46:49], v[162:165], v[182:185], v[46:49]
	v_mfma_f32_16x16x32_bf16 v[42:45], v[170:173], v[182:185], v[42:45]
	v_mfma_f32_16x16x32_bf16 v[30:33], v[162:165], v[194:197], v[30:33]
	v_mfma_f32_16x16x32_bf16 v[26:29], v[170:173], v[194:197], v[26:29]
	v_mfma_f32_16x16x32_bf16 v[14:17], v[162:165], v[202:205], v[14:17]
	v_mfma_f32_16x16x32_bf16 v[10:13], v[170:173], v[202:205], v[10:13]
	v_mfma_f32_16x16x32_bf16 v[6:9], v[162:165], v[216:219], v[6:9]
	v_mfma_f32_16x16x32_bf16 v[2:5], v[170:173], v[216:219], v[2:5]
	s_mov_b32 m0, s73
	s_nop 0
	global_load_lds_dwordx4 v[230:231], off
	v_mfma_f32_16x16x32_bf16 v[46:49], v[166:169], v[190:193], v[46:49]
	v_mfma_f32_16x16x32_bf16 v[42:45], v[174:177], v[190:193], v[42:45]
	v_mfma_f32_16x16x32_bf16 v[30:33], v[166:169], v[198:201], v[30:33]
	v_mfma_f32_16x16x32_bf16 v[26:29], v[174:177], v[198:201], v[26:29]
	v_mfma_f32_16x16x32_bf16 v[14:17], v[166:169], v[212:215], v[14:17]
	v_mfma_f32_16x16x32_bf16 v[10:13], v[174:177], v[212:215], v[10:13]
	v_mfma_f32_16x16x32_bf16 v[6:9], v[166:169], v[220:223], v[6:9]
	v_mfma_f32_16x16x32_bf16 v[2:5], v[174:177], v[220:223], v[2:5]
	s_setprio 0
	s_barrier
	s_add_i32 s48, 0, 0x18000
	v_add_u32_e32 v145, s48, v143
	s_add_i32 s49, 0, 0x1c000
	ds_read_b128 v[146:149], v145
	ds_read_b128 v[150:153], v145 offset:1024
	ds_read_b128 v[154:157], v145 offset:2048
	ds_read_b128 v[158:161], v145 offset:3072
	v_add_u32_e32 v145, s49, v143
	ds_read_b128 v[162:165], v145
	ds_read_b128 v[166:169], v145 offset:1024
	ds_read_b128 v[170:173], v145 offset:2048
	ds_read_b128 v[174:177], v145 offset:3072
	s_add_u32 s66, s66, 0x40000
	s_addc_u32 s67, s67, 0
	s_mov_b32 m0, s74
	v_lshl_add_u64 v[232:233], s[66:67], 0, v[136:137]
	ds_read_b128 v[182:185], v144 offset:32768
	ds_read_b128 v[190:193], v144 offset:33792
	ds_read_b128 v[194:197], v144 offset:34816
	ds_read_b128 v[198:201], v144 offset:35840
	ds_read_b128 v[202:205], v144 offset:36864
	ds_read_b128 v[212:215], v144 offset:37888
	ds_read_b128 v[216:219], v144 offset:38912
	ds_read_b128 v[220:223], v144 offset:39936
	global_load_lds_dwordx4 v[232:233], off
	v_lshl_add_u64 v[232:233], s[66:67], 0, v[132:133]
	s_mov_b32 m0, s75
	s_nop 0
	global_load_lds_dwordx4 v[232:233], off
	s_waitcnt vmcnt(8)
	s_waitcnt lgkmcnt(0)
	s_barrier
	s_setprio 1
	s_waitcnt lgkmcnt(0)
	v_mfma_f32_16x16x32_bf16 v[126:129], v[146:149], v[182:185], v[126:129]
	v_mfma_f32_16x16x32_bf16 v[122:125], v[154:157], v[182:185], v[122:125]
	v_mfma_f32_16x16x32_bf16 v[118:121], v[146:149], v[194:197], v[118:121]
	v_mfma_f32_16x16x32_bf16 v[114:117], v[154:157], v[194:197], v[114:117]
	v_mfma_f32_16x16x32_bf16 v[102:105], v[146:149], v[202:205], v[102:105]
	v_mfma_f32_16x16x32_bf16 v[98:101], v[154:157], v[202:205], v[98:101]
	v_mfma_f32_16x16x32_bf16 v[86:89], v[146:149], v[216:219], v[86:89]
	v_mfma_f32_16x16x32_bf16 v[82:85], v[154:157], v[216:219], v[82:85]
	v_mfma_f32_16x16x32_bf16 v[126:129], v[150:153], v[190:193], v[126:129]
	v_mfma_f32_16x16x32_bf16 v[122:125], v[158:161], v[190:193], v[122:125]
	v_mfma_f32_16x16x32_bf16 v[118:121], v[150:153], v[198:201], v[118:121]
	v_mfma_f32_16x16x32_bf16 v[114:117], v[158:161], v[198:201], v[114:117]
	v_mfma_f32_16x16x32_bf16 v[102:105], v[150:153], v[212:215], v[102:105]
	v_mfma_f32_16x16x32_bf16 v[98:101], v[158:161], v[212:215], v[98:101]
	v_mfma_f32_16x16x32_bf16 v[86:89], v[150:153], v[220:223], v[86:89]
	v_mfma_f32_16x16x32_bf16 v[82:85], v[158:161], v[220:223], v[82:85]
	s_setprio 0
	s_setprio 1
	v_mfma_f32_16x16x32_bf16 v[110:113], v[162:165], v[182:185], v[110:113]
	v_mfma_f32_16x16x32_bf16 v[106:109], v[170:173], v[182:185], v[106:109]
	v_mfma_f32_16x16x32_bf16 v[94:97], v[162:165], v[194:197], v[94:97]
	v_mfma_f32_16x16x32_bf16 v[90:93], v[170:173], v[194:197], v[90:93]
	v_mfma_f32_16x16x32_bf16 v[78:81], v[162:165], v[202:205], v[78:81]
	v_mfma_f32_16x16x32_bf16 v[74:77], v[170:173], v[202:205], v[74:77]
	v_mfma_f32_16x16x32_bf16 v[70:73], v[162:165], v[216:219], v[70:73]
	v_mfma_f32_16x16x32_bf16 v[66:69], v[170:173], v[216:219], v[66:69]
	v_mfma_f32_16x16x32_bf16 v[110:113], v[166:169], v[190:193], v[110:113]
	v_mfma_f32_16x16x32_bf16 v[106:109], v[174:177], v[190:193], v[106:109]
	v_mfma_f32_16x16x32_bf16 v[94:97], v[166:169], v[198:201], v[94:97]
	v_mfma_f32_16x16x32_bf16 v[90:93], v[174:177], v[198:201], v[90:93]
	v_mfma_f32_16x16x32_bf16 v[78:81], v[166:169], v[212:215], v[78:81]
	v_mfma_f32_16x16x32_bf16 v[74:77], v[174:177], v[212:215], v[74:77]
	v_mfma_f32_16x16x32_bf16 v[70:73], v[166:169], v[220:223], v[70:73]
	v_mfma_f32_16x16x32_bf16 v[66:69], v[174:177], v[220:223], v[66:69]
	s_setprio 0
	s_barrier
; #define PG8_STAGE(bufoff, gbase, voff) do { _Pragma("unroll") for (int _i = 0; _i < 2; ++_i) \
;         __builtin_amdgcn_global_load_lds((const unsigned*)((const char*)(gbase) + (voff)[_i]), (LAS unsigned*)(lds + (bufoff) + ldsw + _i * 8192), 16, 0, 0); } while (0)
; #define PG8_LDA(dst, b, h) do { _Pragma("unroll") for (int m = 0; m < 4; ++m) _Pragma("unroll") for (int k = 0; k < 2; ++k) dst[m][k] = *(const LAS bf16x8*)(lds + PG8_SA(b, h) + aoff + m * 2048 + k * 1024); } while (0)
; #define PG8_MMA(ai, bj, At, Bt) do { __builtin_amdgcn_s_setprio(1); _Pragma("unroll") for (int m = 0; m < 4; ++m) _Pragma("unroll") for (int n = 0; n < 2; ++n) _Pragma("unroll") for (int k = 0; k < 2; ++k) \
;         acc[ai][bj][m][n] = __builtin_amdgcn_mfma_f32_16x16x32_bf16(Bt[n][k], At[m][k], acc[ai][bj][m][n], 0, 0, 0); __builtin_amdgcn_s_setprio(0); } while (0)
; #define PG8_WAIT_V(n) asm volatile("s_waitcnt vmcnt(" #n ")" ::: "memory")
; #define PG8_WAIT_L(n) asm volatile("s_waitcnt lgkmcnt(" #n ")" ::: "memory")
; #define PG8_BAR __builtin_amdgcn_s_barrier()
; #define PG8_SCHED __builtin_amdgcn_sched_barrier(0)
; template <class Epi, class Sched>
; DI void gemm_phase(LAS unsigned char* lds, const int K, const Sched& S, const Epi& E) {
;     ...
;             PG8_LDA(At, 1, 1); PG8_STAGE(PG8_SB(1, 0), b3, voffB); PG8_STAGE(PG8_SB(1, 1), b3 + hstep, voffB); PG8_STAGE(PG8_SA(1, 0), a3, voffA);
;             PG8_WAIT_V(8); PG8_WAIT_L(0); PG8_BAR; PG8_MMA(1, 0, At, B0); PG8_MMA(1, 1, At, B1); PG8_BAR; PG8_SCHED;
;         }
;         if (wr == 0) PG8_BAR;
	s_add_i32 s48, s48, s71
	v_lshl_add_u64 v[224:225], v[224:225], 0, s[90:91]
	s_mov_b32 m0, s48
	ds_read_b128 v[182:185], v144 offset:49152
	ds_read_b128 v[190:193], v144 offset:50176
	ds_read_b128 v[194:197], v144 offset:51200
	ds_read_b128 v[198:201], v144 offset:52224
	ds_read_b128 v[202:205], v144 offset:53248
	ds_read_b128 v[212:215], v144 offset:54272
	ds_read_b128 v[216:219], v144 offset:55296
	ds_read_b128 v[220:223], v144 offset:56320
	global_load_lds_dwordx4 v[224:225], off
	s_add_i32 m0, s48, 0x2000
	s_add_u32 s64, s64, 0x40080
	v_lshl_add_u64 v[224:225], v[226:227], 0, s[90:91]
	s_addc_u32 s65, s65, 0
	s_add_i32 s48, s49, s71
	global_load_lds_dwordx4 v[224:225], off
	v_lshl_add_u64 v[224:225], s[64:65], 0, v[134:135]
	s_mov_b32 m0, s48
	s_nop 0
	global_load_lds_dwordx4 v[224:225], off
	v_lshl_add_u64 v[224:225], s[64:65], 0, v[130:131]
	s_add_i32 m0, s48, 0x2000
	s_nop 0
	global_load_lds_dwordx4 v[224:225], off
	s_waitcnt vmcnt(6)
	s_waitcnt lgkmcnt(0)
	s_barrier
	s_setprio 1
	s_waitcnt lgkmcnt(0)
	v_mfma_f32_16x16x32_bf16 v[62:65], v[146:149], v[182:185], v[62:65]
	v_mfma_f32_16x16x32_bf16 v[58:61], v[154:157], v[182:185], v[58:61]
	v_mfma_f32_16x16x32_bf16 v[54:57], v[146:149], v[194:197], v[54:57]
	v_mfma_f32_16x16x32_bf16 v[50:53], v[154:157], v[194:197], v[50:53]
	v_mfma_f32_16x16x32_bf16 v[38:41], v[146:149], v[202:205], v[38:41]
	v_mfma_f32_16x16x32_bf16 v[34:37], v[154:157], v[202:205], v[34:37]
	v_mfma_f32_16x16x32_bf16 v[22:25], v[146:149], v[216:219], v[22:25]
	v_mfma_f32_16x16x32_bf16 v[18:21], v[154:157], v[216:219], v[18:21]
	v_lshl_add_u64 v[224:225], v[228:229], 0, s[90:91]
	s_mov_b32 m0, s78
	s_nop 0
	global_load_lds_dwordx4 v[224:225], off
	v_mfma_f32_16x16x32_bf16 v[62:65], v[150:153], v[190:193], v[62:65]
	v_mfma_f32_16x16x32_bf16 v[58:61], v[158:161], v[190:193], v[58:61]
	v_mfma_f32_16x16x32_bf16 v[54:57], v[150:153], v[198:201], v[54:57]
	v_mfma_f32_16x16x32_bf16 v[50:53], v[158:161], v[198:201], v[50:53]
	v_mfma_f32_16x16x32_bf16 v[38:41], v[150:153], v[212:215], v[38:41]
	v_mfma_f32_16x16x32_bf16 v[34:37], v[158:161], v[212:215], v[34:37]
	v_mfma_f32_16x16x32_bf16 v[22:25], v[150:153], v[220:223], v[22:25]
	v_mfma_f32_16x16x32_bf16 v[18:21], v[158:161], v[220:223], v[18:21]
	s_setprio 0
	s_setprio 1
	v_mfma_f32_16x16x32_bf16 v[46:49], v[162:165], v[182:185], v[46:49]
	v_mfma_f32_16x16x32_bf16 v[42:45], v[170:173], v[182:185], v[42:45]
	v_mfma_f32_16x16x32_bf16 v[30:33], v[162:165], v[194:197], v[30:33]
	v_mfma_f32_16x16x32_bf16 v[26:29], v[170:173], v[194:197], v[26:29]
	v_mfma_f32_16x16x32_bf16 v[14:17], v[162:165], v[202:205], v[14:17]
	v_mfma_f32_16x16x32_bf16 v[10:13], v[170:173], v[202:205], v[10:13]
	v_mfma_f32_16x16x32_bf16 v[6:9], v[162:165], v[216:219], v[6:9]
	v_mfma_f32_16x16x32_bf16 v[2:5], v[170:173], v[216:219], v[2:5]
	v_lshl_add_u64 v[224:225], v[230:231], 0, s[90:91]
	s_mov_b32 m0, s79
	s_nop 0
	global_load_lds_dwordx4 v[224:225], off
	v_mfma_f32_16x16x32_bf16 v[46:49], v[166:169], v[190:193], v[46:49]
	v_mfma_f32_16x16x32_bf16 v[42:45], v[174:177], v[190:193], v[42:45]
	v_mfma_f32_16x16x32_bf16 v[30:33], v[166:169], v[198:201], v[30:33]
	v_mfma_f32_16x16x32_bf16 v[26:29], v[174:177], v[198:201], v[26:29]
	v_mfma_f32_16x16x32_bf16 v[14:17], v[166:169], v[212:215], v[14:17]
	v_mfma_f32_16x16x32_bf16 v[10:13], v[174:177], v[212:215], v[10:13]
	v_mfma_f32_16x16x32_bf16 v[6:9], v[166:169], v[220:223], v[6:9]
	v_mfma_f32_16x16x32_bf16 v[2:5], v[174:177], v[220:223], v[2:5]
	s_setprio 0
	s_barrier
	s_add_i32 s83, s83, 2
	s_add_u32 s55, s55, 0x100
	s_addc_u32 s57, s57, 0
	s_add_u32 s62, s62, 0x100
	s_addc_u32 s63, s63, 0
	s_cmp_gt_u32 s83, 13
	s_cbranch_scc0 .LBB0_945
	s_and_b64 vcc, exec, s[50:51]
	s_cbranch_vccz .LBB0_948
	s_barrier

; #define PG8_STAGE(bufoff, gbase, voff) do { _Pragma("unroll") for (int _i = 0; _i < 2; ++_i) \
;         __builtin_amdgcn_global_load_lds((const unsigned*)((const char*)(gbase) + (voff)[_i]), (LAS unsigned*)(lds + (bufoff) + ldsw + _i * 8192), 16, 0, 0); } while (0)
; #define PG8_LDA(dst, b, h) do { _Pragma("unroll") for (int m = 0; m < 4; ++m) _Pragma("unroll") for (int k = 0; k < 2; ++k) dst[m][k] = *(const LAS bf16x8*)(lds + PG8_SA(b, h) + aoff + m * 2048 + k * 1024); } while (0)
; #define PG8_LDB(dst, b, h) do { _Pragma("unroll") for (int n = 0; n < 2; ++n) _Pragma("unroll") for (int k = 0; k < 2; ++k) dst[n][k] = *(const LAS bf16x8*)(lds + PG8_SB(b, h) + boff + n * 2048 + k * 1024); } while (0)
; #define PG8_MMA(ai, bj, At, Bt) do { __builtin_amdgcn_s_setprio(1); _Pragma("unroll") for (int m = 0; m < 4; ++m) _Pragma("unroll") for (int n = 0; n < 2; ++n) _Pragma("unroll") for (int k = 0; k < 2; ++k) \
;         acc[ai][bj][m][n] = __builtin_amdgcn_mfma_f32_16x16x32_bf16(Bt[n][k], At[m][k], acc[ai][bj][m][n], 0, 0, 0); __builtin_amdgcn_s_setprio(0); } while (0)
; #define PG8_WAIT_V(n) asm volatile("s_waitcnt vmcnt(" #n ")" ::: "memory")
; #define PG8_WAIT_L(n) asm volatile("s_waitcnt lgkmcnt(" #n ")" ::: "memory")
; #define PG8_BAR __builtin_amdgcn_s_barrier()
; #define PG8_SCHED __builtin_amdgcn_sched_barrier(0)
; template <class Epi, class Sched>
; DI void gemm_phase(LAS unsigned char* lds, const int K, const Sched& S, const Epi& E) {
;     ...
;         for (int t = 0; t < nt; t += 2) {
;             const bool last = (t == nt - 2);
;             const char* a1 = cA + (size_t)(t + 1) * kstep;
;             const char* a2 = last ? nA : cA + (size_t)(t + 2) * kstep; const char* b2 = last ? nB : cB + (size_t)(t + 2) * kstep;
;             const char* a3 = a2 + kstep; const char* b3 = b2 + kstep;
;             PG8_LDB(B0, 0, 0); PG8_LDB(B1, 0, 1); PG8_SCHED; PG8_LDA(At, 0, 0); PG8_STAGE(PG8_SA(1, 1), a1 + hstep, voffA);
;             PG8_WAIT_V(8); PG8_WAIT_L(0); PG8_BAR; PG8_MMA(0, 0, At, B0); PG8_MMA(0, 1, At, B1); PG8_BAR; PG8_SCHED;
;             PG8_LDA(At, 0, 1); PG8_STAGE(PG8_SB(0, 0), b2, voffB); PG8_STAGE(PG8_SB(0, 1), b2 + hstep, voffB); PG8_STAGE(PG8_SA(0, 0), a2, voffA);
;             PG8_WAIT_V(8); PG8_WAIT_L(0); PG8_BAR; PG8_MMA(1, 0, At, B0); PG8_MMA(1, 1, At, B1); PG8_BAR; PG8_SCHED;
.LBB0_1086:
	s_add_u32 s48, s68, 0xfffc0080
	s_addc_u32 s49, s69, -1
	s_add_i32 vcc_hi, 0, 0x10000
	s_cmp_eq_u32 vcc_lo, 12
	s_cselect_b32 s73, s65, s49
	s_cselect_b32 s72, s64, s48
	v_add_u32_e32 v145, vcc_hi, v143
	s_cselect_b32 s71, s67, s63
	s_cselect_b32 s70, s66, s61
	s_add_i32 s94, 0, 0x14000
	ds_read_b128 v[146:149], v145
	ds_read_b128 v[150:153], v145 offset:1024
	ds_read_b128 v[154:157], v145 offset:2048
	ds_read_b128 v[158:161], v145 offset:3072
	v_add_u32_e32 v145, s94, v143
	ds_read_b128 v[162:165], v145
	ds_read_b128 v[166:169], v145 offset:1024
	ds_read_b128 v[170:173], v145 offset:2048
	ds_read_b128 v[174:177], v145 offset:3072
	v_lshl_add_u64 v[224:225], s[68:69], 0, v[140:141]
	s_add_i32 m0, s59, 0xc000
	ds_read_b128 v[182:185], v144
	ds_read_b128 v[190:193], v144 offset:1024
	ds_read_b128 v[194:197], v144 offset:2048
	ds_read_b128 v[198:201], v144 offset:3072
	ds_read_b128 v[202:205], v144 offset:4096
	ds_read_b128 v[212:215], v144 offset:5120
	ds_read_b128 v[216:219], v144 offset:6144
	ds_read_b128 v[220:223], v144 offset:7168
	global_load_lds_dwordx4 v[224:225], off
	v_lshl_add_u64 v[224:225], s[68:69], 0, v[138:139]
	s_add_i32 m0, s59, 0xe000
	s_nop 0
	global_load_lds_dwordx4 v[224:225], off
	s_waitcnt vmcnt(8)
	s_waitcnt lgkmcnt(0)
	s_barrier
	s_setprio 1
	s_waitcnt lgkmcnt(0)
	v_mfma_f32_16x16x32_bf16 v[126:129], v[146:149], v[182:185], v[126:129]
	v_mfma_f32_16x16x32_bf16 v[122:125], v[154:157], v[182:185], v[122:125]
	v_mfma_f32_16x16x32_bf16 v[118:121], v[146:149], v[194:197], v[118:121]
	v_mfma_f32_16x16x32_bf16 v[114:117], v[154:157], v[194:197], v[114:117]
	v_mfma_f32_16x16x32_bf16 v[102:105], v[146:149], v[202:205], v[102:105]
	v_mfma_f32_16x16x32_bf16 v[98:101], v[154:157], v[202:205], v[98:101]
	v_mfma_f32_16x16x32_bf16 v[86:89], v[146:149], v[216:219], v[86:89]
	v_mfma_f32_16x16x32_bf16 v[82:85], v[154:157], v[216:219], v[82:85]
	v_mfma_f32_16x16x32_bf16 v[126:129], v[150:153], v[190:193], v[126:129]
	v_mfma_f32_16x16x32_bf16 v[122:125], v[158:161], v[190:193], v[122:125]
	v_mfma_f32_16x16x32_bf16 v[118:121], v[150:153], v[198:201], v[118:121]
	v_mfma_f32_16x16x32_bf16 v[114:117], v[158:161], v[198:201], v[114:117]
	v_mfma_f32_16x16x32_bf16 v[102:105], v[150:153], v[212:215], v[102:105]
	v_mfma_f32_16x16x32_bf16 v[98:101], v[158:161], v[212:215], v[98:101]
	v_mfma_f32_16x16x32_bf16 v[86:89], v[150:153], v[220:223], v[86:89]
	v_mfma_f32_16x16x32_bf16 v[82:85], v[158:161], v[220:223], v[82:85]
	s_setprio 0
	s_setprio 1
	v_mfma_f32_16x16x32_bf16 v[110:113], v[162:165], v[182:185], v[110:113]
	v_mfma_f32_16x16x32_bf16 v[106:109], v[170:173], v[182:185], v[106:109]
	v_mfma_f32_16x16x32_bf16 v[94:97], v[162:165], v[194:197], v[94:97]
	v_mfma_f32_16x16x32_bf16 v[90:93], v[170:173], v[194:197], v[90:93]
	v_mfma_f32_16x16x32_bf16 v[78:81], v[162:165], v[202:205], v[78:81]
	v_mfma_f32_16x16x32_bf16 v[74:77], v[170:173], v[202:205], v[74:77]
	v_mfma_f32_16x16x32_bf16 v[70:73], v[162:165], v[216:219], v[70:73]
	v_mfma_f32_16x16x32_bf16 v[66:69], v[170:173], v[216:219], v[66:69]
	v_mfma_f32_16x16x32_bf16 v[110:113], v[166:169], v[190:193], v[110:113]
	v_mfma_f32_16x16x32_bf16 v[106:109], v[174:177], v[190:193], v[106:109]
	v_mfma_f32_16x16x32_bf16 v[94:97], v[166:169], v[198:201], v[94:97]
	v_mfma_f32_16x16x32_bf16 v[90:93], v[174:177], v[198:201], v[90:93]
	v_mfma_f32_16x16x32_bf16 v[78:81], v[166:169], v[212:215], v[78:81]
	v_mfma_f32_16x16x32_bf16 v[74:77], v[174:177], v[212:215], v[74:77]
	v_mfma_f32_16x16x32_bf16 v[70:73], v[166:169], v[220:223], v[70:73]
	v_mfma_f32_16x16x32_bf16 v[66:69], v[174:177], v[220:223], v[66:69]
	s_setprio 0
	s_barrier
	s_add_i32 s48, vcc_hi, s78
	v_lshl_add_u64 v[224:225], s[70:71], 0, v[134:135]
	s_mov_b32 m0, s48
	ds_read_b128 v[182:185], v144 offset:16384
	ds_read_b128 v[190:193], v144 offset:17408
	ds_read_b128 v[194:197], v144 offset:18432
	ds_read_b128 v[198:201], v144 offset:19456
	ds_read_b128 v[202:205], v144 offset:20480
	ds_read_b128 v[212:215], v144 offset:21504
	ds_read_b128 v[216:219], v144 offset:22528
	ds_read_b128 v[220:223], v144 offset:23552
	global_load_lds_dwordx4 v[224:225], off
	s_add_i32 m0, s48, 0x2000
	s_add_u32 s48, s70, 0x40000
	v_lshl_add_u64 v[226:227], s[70:71], 0, v[130:131]
	s_addc_u32 s49, s71, 0
	s_add_i32 s94, s94, s78
	global_load_lds_dwordx4 v[226:227], off
	v_lshl_add_u64 v[228:229], s[48:49], 0, v[134:135]
	s_mov_b32 m0, s94
	v_lshl_add_u64 v[230:231], s[72:73], 0, v[132:133]
	global_load_lds_dwordx4 v[228:229], off
	v_lshl_add_u64 v[228:229], s[48:49], 0, v[130:131]
	s_add_i32 m0, s94, 0x2000
	s_nop 0
	global_load_lds_dwordx4 v[228:229], off
	s_waitcnt vmcnt(6)
	s_waitcnt lgkmcnt(0)
	s_barrier
; #define PG8_STAGE(bufoff, gbase, voff) do { _Pragma("unroll") for (int _i = 0; _i < 2; ++_i) \
;         __builtin_amdgcn_global_load_lds((const unsigned*)((const char*)(gbase) + (voff)[_i]), (LAS unsigned*)(lds + (bufoff) + ldsw + _i * 8192), 16, 0, 0); } while (0)
; #define PG8_LDA(dst, b, h) do { _Pragma("unroll") for (int m = 0; m < 4; ++m) _Pragma("unroll") for (int k = 0; k < 2; ++k) dst[m][k] = *(const LAS bf16x8*)(lds + PG8_SA(b, h) + aoff + m * 2048 + k * 1024); } while (0)
; #define PG8_LDB(dst, b, h) do { _Pragma("unroll") for (int n = 0; n < 2; ++n) _Pragma("unroll") for (int k = 0; k < 2; ++k) dst[n][k] = *(const LAS bf16x8*)(lds + PG8_SB(b, h) + boff + n * 2048 + k * 1024); } while (0)
; #define PG8_MMA(ai, bj, At, Bt) do { __builtin_amdgcn_s_setprio(1); _Pragma("unroll") for (int m = 0; m < 4; ++m) _Pragma("unroll") for (int n = 0; n < 2; ++n) _Pragma("unroll") for (int k = 0; k < 2; ++k) \
;         acc[ai][bj][m][n] = __builtin_amdgcn_mfma_f32_16x16x32_bf16(Bt[n][k], At[m][k], acc[ai][bj][m][n], 0, 0, 0); __builtin_amdgcn_s_setprio(0); } while (0)
; #define PG8_WAIT_V(n) asm volatile("s_waitcnt vmcnt(" #n ")" ::: "memory")
; #define PG8_WAIT_L(n) asm volatile("s_waitcnt lgkmcnt(" #n ")" ::: "memory")
; #define PG8_BAR __builtin_amdgcn_s_barrier()
; #define PG8_SCHED __builtin_amdgcn_sched_barrier(0)
; template <class Epi, class Sched>
; DI void gemm_phase(LAS unsigned char* lds, const int K, const Sched& S, const Epi& E) {
;     ...
;             PG8_WAIT_V(8); PG8_WAIT_L(0); PG8_BAR; PG8_MMA(1, 0, At, B0); PG8_MMA(1, 1, At, B1); PG8_BAR; PG8_SCHED;
;             PG8_LDB(B0, 1, 0); PG8_LDB(B1, 1, 1); PG8_SCHED; PG8_LDA(At, 1, 0); PG8_STAGE(PG8_SA(0, 1), a2 + hstep, voffA);
;             PG8_WAIT_V(8); PG8_WAIT_L(0); PG8_BAR; PG8_MMA(0, 0, At, B0); PG8_MMA(0, 1, At, B1); PG8_BAR; PG8_SCHED;
	s_setprio 1
	s_waitcnt lgkmcnt(0)
	v_mfma_f32_16x16x32_bf16 v[62:65], v[146:149], v[182:185], v[62:65]
	v_mfma_f32_16x16x32_bf16 v[58:61], v[154:157], v[182:185], v[58:61]
	v_mfma_f32_16x16x32_bf16 v[54:57], v[146:149], v[194:197], v[54:57]
	v_mfma_f32_16x16x32_bf16 v[50:53], v[154:157], v[194:197], v[50:53]
	v_mfma_f32_16x16x32_bf16 v[38:41], v[146:149], v[202:205], v[38:41]
	v_mfma_f32_16x16x32_bf16 v[34:37], v[154:157], v[202:205], v[34:37]
	v_mfma_f32_16x16x32_bf16 v[22:25], v[146:149], v[216:219], v[22:25]
	v_mfma_f32_16x16x32_bf16 v[18:21], v[154:157], v[216:219], v[18:21]
	v_lshl_add_u64 v[228:229], s[72:73], 0, v[136:137]
	s_mov_b32 m0, s59
	s_nop 0
	global_load_lds_dwordx4 v[228:229], off
	v_mfma_f32_16x16x32_bf16 v[62:65], v[150:153], v[190:193], v[62:65]
	v_mfma_f32_16x16x32_bf16 v[58:61], v[158:161], v[190:193], v[58:61]
	v_mfma_f32_16x16x32_bf16 v[54:57], v[150:153], v[198:201], v[54:57]
	v_mfma_f32_16x16x32_bf16 v[50:53], v[158:161], v[198:201], v[50:53]
	v_mfma_f32_16x16x32_bf16 v[38:41], v[150:153], v[212:215], v[38:41]
	v_mfma_f32_16x16x32_bf16 v[34:37], v[158:161], v[212:215], v[34:37]
	v_mfma_f32_16x16x32_bf16 v[22:25], v[150:153], v[220:223], v[22:25]
	v_mfma_f32_16x16x32_bf16 v[18:21], v[158:161], v[220:223], v[18:21]
	s_setprio 0
	s_setprio 1
	v_mfma_f32_16x16x32_bf16 v[46:49], v[162:165], v[182:185], v[46:49]
	v_mfma_f32_16x16x32_bf16 v[42:45], v[170:173], v[182:185], v[42:45]
	v_mfma_f32_16x16x32_bf16 v[30:33], v[162:165], v[194:197], v[30:33]
	v_mfma_f32_16x16x32_bf16 v[26:29], v[170:173], v[194:197], v[26:29]
	v_mfma_f32_16x16x32_bf16 v[14:17], v[162:165], v[202:205], v[14:17]
	v_mfma_f32_16x16x32_bf16 v[10:13], v[170:173], v[202:205], v[10:13]
	v_mfma_f32_16x16x32_bf16 v[6:9], v[162:165], v[216:219], v[6:9]
	v_mfma_f32_16x16x32_bf16 v[2:5], v[170:173], v[216:219], v[2:5]
	s_mov_b32 m0, s80
	s_nop 0
	global_load_lds_dwordx4 v[230:231], off
	v_mfma_f32_16x16x32_bf16 v[46:49], v[166:169], v[190:193], v[46:49]
	v_mfma_f32_16x16x32_bf16 v[42:45], v[174:177], v[190:193], v[42:45]
	v_mfma_f32_16x16x32_bf16 v[30:33], v[166:169], v[198:201], v[30:33]
	v_mfma_f32_16x16x32_bf16 v[26:29], v[174:177], v[198:201], v[26:29]
	v_mfma_f32_16x16x32_bf16 v[14:17], v[166:169], v[212:215], v[14:17]
	v_mfma_f32_16x16x32_bf16 v[10:13], v[174:177], v[212:215], v[10:13]
	v_mfma_f32_16x16x32_bf16 v[6:9], v[166:169], v[220:223], v[6:9]
	v_mfma_f32_16x16x32_bf16 v[2:5], v[174:177], v[220:223], v[2:5]
	s_setprio 0
	s_barrier
	s_add_i32 s94, 0, 0x18000
	v_add_u32_e32 v145, s94, v143
	s_add_i32 vcc_hi, 0, 0x1c000
	ds_read_b128 v[146:149], v145
	ds_read_b128 v[150:153], v145 offset:1024
	ds_read_b128 v[154:157], v145 offset:2048
	ds_read_b128 v[158:161], v145 offset:3072
	v_add_u32_e32 v145, vcc_hi, v143
	ds_read_b128 v[162:165], v145
	ds_read_b128 v[166:169], v145 offset:1024
	ds_read_b128 v[170:173], v145 offset:2048
	ds_read_b128 v[174:177], v145 offset:3072
	s_add_u32 s48, s72, 0x40000
	s_addc_u32 s49, s73, 0
	s_mov_b32 m0, s81
	v_lshl_add_u64 v[232:233], s[48:49], 0, v[136:137]
	ds_read_b128 v[182:185], v144 offset:32768
	ds_read_b128 v[190:193], v144 offset:33792
	ds_read_b128 v[194:197], v144 offset:34816
	ds_read_b128 v[198:201], v144 offset:35840
	ds_read_b128 v[202:205], v144 offset:36864
	ds_read_b128 v[212:215], v144 offset:37888
	ds_read_b128 v[216:219], v144 offset:38912
	ds_read_b128 v[220:223], v144 offset:39936
	global_load_lds_dwordx4 v[232:233], off
	v_lshl_add_u64 v[232:233], s[48:49], 0, v[132:133]
	s_mov_b32 m0, s83
	s_nop 0
	global_load_lds_dwordx4 v[232:233], off
	s_waitcnt vmcnt(8)
	s_waitcnt lgkmcnt(0)
	s_barrier
	s_setprio 1
	s_waitcnt lgkmcnt(0)
	v_mfma_f32_16x16x32_bf16 v[126:129], v[146:149], v[182:185], v[126:129]
	v_mfma_f32_16x16x32_bf16 v[122:125], v[154:157], v[182:185], v[122:125]
	v_mfma_f32_16x16x32_bf16 v[118:121], v[146:149], v[194:197], v[118:121]
	v_mfma_f32_16x16x32_bf16 v[114:117], v[154:157], v[194:197], v[114:117]
	v_mfma_f32_16x16x32_bf16 v[102:105], v[146:149], v[202:205], v[102:105]
	v_mfma_f32_16x16x32_bf16 v[98:101], v[154:157], v[202:205], v[98:101]
	v_mfma_f32_16x16x32_bf16 v[86:89], v[146:149], v[216:219], v[86:89]
	v_mfma_f32_16x16x32_bf16 v[82:85], v[154:157], v[216:219], v[82:85]
	v_mfma_f32_16x16x32_bf16 v[126:129], v[150:153], v[190:193], v[126:129]
	v_mfma_f32_16x16x32_bf16 v[122:125], v[158:161], v[190:193], v[122:125]
	v_mfma_f32_16x16x32_bf16 v[118:121], v[150:153], v[198:201], v[118:121]
	v_mfma_f32_16x16x32_bf16 v[114:117], v[158:161], v[198:201], v[114:117]
	v_mfma_f32_16x16x32_bf16 v[102:105], v[150:153], v[212:215], v[102:105]
	v_mfma_f32_16x16x32_bf16 v[98:101], v[158:161], v[212:215], v[98:101]
	v_mfma_f32_16x16x32_bf16 v[86:89], v[150:153], v[220:223], v[86:89]
	v_mfma_f32_16x16x32_bf16 v[82:85], v[158:161], v[220:223], v[82:85]
	s_setprio 0
	s_setprio 1
	v_mfma_f32_16x16x32_bf16 v[110:113], v[162:165], v[182:185], v[110:113]
	v_mfma_f32_16x16x32_bf16 v[106:109], v[170:173], v[182:185], v[106:109]
	v_mfma_f32_16x16x32_bf16 v[94:97], v[162:165], v[194:197], v[94:97]
	v_mfma_f32_16x16x32_bf16 v[90:93], v[170:173], v[194:197], v[90:93]
	v_mfma_f32_16x16x32_bf16 v[78:81], v[162:165], v[202:205], v[78:81]
	v_mfma_f32_16x16x32_bf16 v[74:77], v[170:173], v[202:205], v[74:77]
	v_mfma_f32_16x16x32_bf16 v[70:73], v[162:165], v[216:219], v[70:73]
	v_mfma_f32_16x16x32_bf16 v[66:69], v[170:173], v[216:219], v[66:69]
	v_mfma_f32_16x16x32_bf16 v[110:113], v[166:169], v[190:193], v[110:113]
	v_mfma_f32_16x16x32_bf16 v[106:109], v[174:177], v[190:193], v[106:109]
	v_mfma_f32_16x16x32_bf16 v[94:97], v[166:169], v[198:201], v[94:97]
	v_mfma_f32_16x16x32_bf16 v[90:93], v[174:177], v[198:201], v[90:93]
	v_mfma_f32_16x16x32_bf16 v[78:81], v[166:169], v[212:215], v[78:81]
	v_mfma_f32_16x16x32_bf16 v[74:77], v[174:177], v[212:215], v[74:77]
	v_mfma_f32_16x16x32_bf16 v[70:73], v[166:169], v[220:223], v[70:73]
	v_mfma_f32_16x16x32_bf16 v[66:69], v[174:177], v[220:223], v[66:69]
	s_setprio 0
	s_barrier
; #define PG8_STAGE(bufoff, gbase, voff) do { _Pragma("unroll") for (int _i = 0; _i < 2; ++_i) \
;         __builtin_amdgcn_global_load_lds((const unsigned*)((const char*)(gbase) + (voff)[_i]), (LAS unsigned*)(lds + (bufoff) + ldsw + _i * 8192), 16, 0, 0); } while (0)
; #define PG8_LDA(dst, b, h) do { _Pragma("unroll") for (int m = 0; m < 4; ++m) _Pragma("unroll") for (int k = 0; k < 2; ++k) dst[m][k] = *(const LAS bf16x8*)(lds + PG8_SA(b, h) + aoff + m * 2048 + k * 1024); } while (0)
; #define PG8_MMA(ai, bj, At, Bt) do { __builtin_amdgcn_s_setprio(1); _Pragma("unroll") for (int m = 0; m < 4; ++m) _Pragma("unroll") for (int n = 0; n < 2; ++n) _Pragma("unroll") for (int k = 0; k < 2; ++k) \
;         acc[ai][bj][m][n] = __builtin_amdgcn_mfma_f32_16x16x32_bf16(Bt[n][k], At[m][k], acc[ai][bj][m][n], 0, 0, 0); __builtin_amdgcn_s_setprio(0); } while (0)
; #define PG8_WAIT_V(n) asm volatile("s_waitcnt vmcnt(" #n ")" ::: "memory")
; #define PG8_WAIT_L(n) asm volatile("s_waitcnt lgkmcnt(" #n ")" ::: "memory")
; #define PG8_BAR __builtin_amdgcn_s_barrier()
; #define PG8_SCHED __builtin_amdgcn_sched_barrier(0)
; template <class Epi, class Sched>
; DI void gemm_phase(LAS unsigned char* lds, const int K, const Sched& S, const Epi& E) {
;     ...
;             PG8_LDA(At, 1, 1); PG8_STAGE(PG8_SB(1, 0), b3, voffB); PG8_STAGE(PG8_SB(1, 1), b3 + hstep, voffB); PG8_STAGE(PG8_SA(1, 0), a3, voffA);
;             PG8_WAIT_V(8); PG8_WAIT_L(0); PG8_BAR; PG8_MMA(1, 0, At, B0); PG8_MMA(1, 1, At, B1); PG8_BAR; PG8_SCHED;
;         }
;         if (wr == 0) PG8_BAR;
	s_add_i32 s48, s94, s78
	v_lshl_add_u64 v[224:225], v[224:225], 0, s[90:91]
	s_mov_b32 m0, s48
	ds_read_b128 v[182:185], v144 offset:49152
	ds_read_b128 v[190:193], v144 offset:50176
	ds_read_b128 v[194:197], v144 offset:51200
	ds_read_b128 v[198:201], v144 offset:52224
	ds_read_b128 v[202:205], v144 offset:53248
	ds_read_b128 v[212:215], v144 offset:54272
	ds_read_b128 v[216:219], v144 offset:55296
	ds_read_b128 v[220:223], v144 offset:56320
	global_load_lds_dwordx4 v[224:225], off
	s_add_i32 m0, s48, 0x2000
	s_add_u32 s48, s70, 0x40080
	v_lshl_add_u64 v[224:225], v[226:227], 0, s[90:91]
	s_addc_u32 s49, s71, 0
	s_add_i32 s70, vcc_hi, s78
	global_load_lds_dwordx4 v[224:225], off
	v_lshl_add_u64 v[224:225], s[48:49], 0, v[134:135]
	s_mov_b32 m0, s70
	s_nop 0
	global_load_lds_dwordx4 v[224:225], off
	v_lshl_add_u64 v[224:225], s[48:49], 0, v[130:131]
	s_add_i32 m0, s70, 0x2000
	s_nop 0
	global_load_lds_dwordx4 v[224:225], off
	s_waitcnt vmcnt(6)
	s_waitcnt lgkmcnt(0)
	s_barrier
	s_setprio 1
	s_waitcnt lgkmcnt(0)
	v_mfma_f32_16x16x32_bf16 v[62:65], v[146:149], v[182:185], v[62:65]
	v_mfma_f32_16x16x32_bf16 v[58:61], v[154:157], v[182:185], v[58:61]
	v_mfma_f32_16x16x32_bf16 v[54:57], v[146:149], v[194:197], v[54:57]
	v_mfma_f32_16x16x32_bf16 v[50:53], v[154:157], v[194:197], v[50:53]
	v_mfma_f32_16x16x32_bf16 v[38:41], v[146:149], v[202:205], v[38:41]
	v_mfma_f32_16x16x32_bf16 v[34:37], v[154:157], v[202:205], v[34:37]
	v_mfma_f32_16x16x32_bf16 v[22:25], v[146:149], v[216:219], v[22:25]
	v_mfma_f32_16x16x32_bf16 v[18:21], v[154:157], v[216:219], v[18:21]
	v_lshl_add_u64 v[224:225], v[228:229], 0, s[90:91]
	s_mov_b32 m0, s95
	s_nop 0
	global_load_lds_dwordx4 v[224:225], off
	v_mfma_f32_16x16x32_bf16 v[62:65], v[150:153], v[190:193], v[62:65]
	v_mfma_f32_16x16x32_bf16 v[58:61], v[158:161], v[190:193], v[58:61]
	v_mfma_f32_16x16x32_bf16 v[54:57], v[150:153], v[198:201], v[54:57]
	v_mfma_f32_16x16x32_bf16 v[50:53], v[158:161], v[198:201], v[50:53]
	v_mfma_f32_16x16x32_bf16 v[38:41], v[150:153], v[212:215], v[38:41]
	v_mfma_f32_16x16x32_bf16 v[34:37], v[158:161], v[212:215], v[34:37]
	v_mfma_f32_16x16x32_bf16 v[22:25], v[150:153], v[220:223], v[22:25]
	v_mfma_f32_16x16x32_bf16 v[18:21], v[158:161], v[220:223], v[18:21]
	s_setprio 0
	s_setprio 1
	v_mfma_f32_16x16x32_bf16 v[46:49], v[162:165], v[182:185], v[46:49]
	v_mfma_f32_16x16x32_bf16 v[42:45], v[170:173], v[182:185], v[42:45]
	v_mfma_f32_16x16x32_bf16 v[30:33], v[162:165], v[194:197], v[30:33]
	v_mfma_f32_16x16x32_bf16 v[26:29], v[170:173], v[194:197], v[26:29]
	v_mfma_f32_16x16x32_bf16 v[14:17], v[162:165], v[202:205], v[14:17]
	v_mfma_f32_16x16x32_bf16 v[10:13], v[170:173], v[202:205], v[10:13]
	v_mfma_f32_16x16x32_bf16 v[6:9], v[162:165], v[216:219], v[6:9]
	v_mfma_f32_16x16x32_bf16 v[2:5], v[170:173], v[216:219], v[2:5]
	v_lshl_add_u64 v[224:225], v[230:231], 0, s[90:91]
	s_mov_b32 m0, s42
	s_nop 0
	global_load_lds_dwordx4 v[224:225], off
	v_mfma_f32_16x16x32_bf16 v[46:49], v[166:169], v[190:193], v[46:49]
	v_mfma_f32_16x16x32_bf16 v[42:45], v[174:177], v[190:193], v[42:45]
	v_mfma_f32_16x16x32_bf16 v[30:33], v[166:169], v[198:201], v[30:33]
	v_mfma_f32_16x16x32_bf16 v[26:29], v[174:177], v[198:201], v[26:29]
	v_mfma_f32_16x16x32_bf16 v[14:17], v[166:169], v[212:215], v[14:17]
	v_mfma_f32_16x16x32_bf16 v[10:13], v[174:177], v[212:215], v[10:13]
	v_mfma_f32_16x16x32_bf16 v[6:9], v[166:169], v[220:223], v[6:9]
	v_mfma_f32_16x16x32_bf16 v[2:5], v[174:177], v[220:223], v[2:5]
	s_setprio 0
	s_barrier
	s_add_i32 vcc_lo, vcc_lo, 2
	s_add_u32 s61, s61, 0x100
	s_addc_u32 s63, s63, 0
	s_add_u32 s68, s68, 0x100
	s_addc_u32 s69, s69, 0
	s_cmp_gt_u32 vcc_lo, 13
	s_cbranch_scc0 .LBB0_1086
	s_and_b64 vcc, exec, s[56:57]
	s_cbranch_vccz .LBB0_1089
	s_barrier

; #define PG8_STAGE(bufoff, gbase, voff) do { _Pragma("unroll") for (int _i = 0; _i < 2; ++_i) \
;         __builtin_amdgcn_global_load_lds((const unsigned*)((const char*)(gbase) + (voff)[_i]), (LAS unsigned*)(lds + (bufoff) + ldsw + _i * 8192), 16, 0, 0); } while (0)
; #define PG8_LDA(dst, b, h) do { _Pragma("unroll") for (int m = 0; m < 4; ++m) _Pragma("unroll") for (int k = 0; k < 2; ++k) dst[m][k] = *(const LAS bf16x8*)(lds + PG8_SA(b, h) + aoff + m * 2048 + k * 1024); } while (0)
; #define PG8_LDB(dst, b, h) do { _Pragma("unroll") for (int n = 0; n < 2; ++n) _Pragma("unroll") for (int k = 0; k < 2; ++k) dst[n][k] = *(const LAS bf16x8*)(lds + PG8_SB(b, h) + boff + n * 2048 + k * 1024); } while (0)
; #define PG8_MMA(ai, bj, At, Bt) do { __builtin_amdgcn_s_setprio(1); _Pragma("unroll") for (int m = 0; m < 4; ++m) _Pragma("unroll") for (int n = 0; n < 2; ++n) _Pragma("unroll") for (int k = 0; k < 2; ++k) \
;         acc[ai][bj][m][n] = __builtin_amdgcn_mfma_f32_16x16x32_bf16(Bt[n][k], At[m][k], acc[ai][bj][m][n], 0, 0, 0); __builtin_amdgcn_s_setprio(0); } while (0)
; #define PG8_WAIT_V(n) asm volatile("s_waitcnt vmcnt(" #n ")" ::: "memory")
; #define PG8_WAIT_L(n) asm volatile("s_waitcnt lgkmcnt(" #n ")" ::: "memory")
; #define PG8_BAR __builtin_amdgcn_s_barrier()
; #define PG8_SCHED __builtin_amdgcn_sched_barrier(0)
; template <class Epi, class Sched>
; DI void gemm_phase(LAS unsigned char* lds, const int K, const Sched& S, const Epi& E) {
;     ...
;         for (int t = 0; t < nt; t += 2) {
;             const bool last = (t == nt - 2);
;             const char* a1 = cA + (size_t)(t + 1) * kstep;
;             const char* a2 = last ? nA : cA + (size_t)(t + 2) * kstep; const char* b2 = last ? nB : cB + (size_t)(t + 2) * kstep;
;             const char* a3 = a2 + kstep; const char* b3 = b2 + kstep;
;             PG8_LDB(B0, 0, 0); PG8_LDB(B1, 0, 1); PG8_SCHED; PG8_LDA(At, 0, 0); PG8_STAGE(PG8_SA(1, 1), a1 + hstep, voffA);
;             PG8_WAIT_V(8); PG8_WAIT_L(0); PG8_BAR; PG8_MMA(0, 0, At, B0); PG8_MMA(0, 1, At, B1); PG8_BAR; PG8_SCHED;
;             PG8_LDA(At, 0, 1); PG8_STAGE(PG8_SB(0, 0), b2, voffB); PG8_STAGE(PG8_SB(0, 1), b2 + hstep, voffB); PG8_STAGE(PG8_SA(0, 0), a2, voffA);
;             PG8_WAIT_V(8); PG8_WAIT_L(0); PG8_BAR; PG8_MMA(1, 0, At, B0); PG8_MMA(1, 1, At, B1); PG8_BAR; PG8_SCHED;
.LBB0_1204:
	s_add_u32 s60, s58, 0x100
	s_addc_u32 s61, s59, 0
	s_add_i32 s48, 0, 0x10000
	s_cmp_eq_u32 s85, 40
	s_cselect_b32 s65, s55, s61
	s_cselect_b32 s64, s54, s60
	v_add_u32_e32 v145, s48, v143
	s_cselect_b32 s63, s57, s84
	s_cselect_b32 s62, s56, s83
	s_add_i32 s86, 0, 0x14000
	ds_read_b128 v[146:149], v145
	ds_read_b128 v[150:153], v145 offset:1024
	ds_read_b128 v[154:157], v145 offset:2048
	ds_read_b128 v[158:161], v145 offset:3072
	v_add_u32_e32 v145, s86, v143
	ds_read_b128 v[162:165], v145
	ds_read_b128 v[166:169], v145 offset:1024
	ds_read_b128 v[170:173], v145 offset:2048
	ds_read_b128 v[174:177], v145 offset:3072
	v_lshl_add_u64 v[224:225], s[58:59], 0, v[140:141]
	s_add_i32 m0, s71, 0xc000
	ds_read_b128 v[182:185], v144
	ds_read_b128 v[190:193], v144 offset:1024
	ds_read_b128 v[194:197], v144 offset:2048
	ds_read_b128 v[198:201], v144 offset:3072
	ds_read_b128 v[202:205], v144 offset:4096
	ds_read_b128 v[212:215], v144 offset:5120
	ds_read_b128 v[216:219], v144 offset:6144
	ds_read_b128 v[220:223], v144 offset:7168
	global_load_lds_dwordx4 v[224:225], off
	v_lshl_add_u64 v[224:225], s[58:59], 0, v[138:139]
	s_add_i32 m0, s71, 0xe000
	s_nop 0
	global_load_lds_dwordx4 v[224:225], off
	s_waitcnt vmcnt(8)
	s_waitcnt lgkmcnt(0)
	s_barrier
	s_setprio 1
	s_waitcnt lgkmcnt(0)
	v_mfma_f32_16x16x32_bf16 v[126:129], v[146:149], v[182:185], v[126:129]
	v_mfma_f32_16x16x32_bf16 v[122:125], v[154:157], v[182:185], v[122:125]
	v_mfma_f32_16x16x32_bf16 v[118:121], v[146:149], v[194:197], v[118:121]
	v_mfma_f32_16x16x32_bf16 v[114:117], v[154:157], v[194:197], v[114:117]
	v_mfma_f32_16x16x32_bf16 v[102:105], v[146:149], v[202:205], v[102:105]
	v_mfma_f32_16x16x32_bf16 v[98:101], v[154:157], v[202:205], v[98:101]
	v_mfma_f32_16x16x32_bf16 v[86:89], v[146:149], v[216:219], v[86:89]
	v_mfma_f32_16x16x32_bf16 v[82:85], v[154:157], v[216:219], v[82:85]
	v_mfma_f32_16x16x32_bf16 v[126:129], v[150:153], v[190:193], v[126:129]
	v_mfma_f32_16x16x32_bf16 v[122:125], v[158:161], v[190:193], v[122:125]
	v_mfma_f32_16x16x32_bf16 v[118:121], v[150:153], v[198:201], v[118:121]
	v_mfma_f32_16x16x32_bf16 v[114:117], v[158:161], v[198:201], v[114:117]
	v_mfma_f32_16x16x32_bf16 v[102:105], v[150:153], v[212:215], v[102:105]
	v_mfma_f32_16x16x32_bf16 v[98:101], v[158:161], v[212:215], v[98:101]
	v_mfma_f32_16x16x32_bf16 v[86:89], v[150:153], v[220:223], v[86:89]
	v_mfma_f32_16x16x32_bf16 v[82:85], v[158:161], v[220:223], v[82:85]
	s_setprio 0
	s_setprio 1
	v_mfma_f32_16x16x32_bf16 v[110:113], v[162:165], v[182:185], v[110:113]
	v_mfma_f32_16x16x32_bf16 v[106:109], v[170:173], v[182:185], v[106:109]
	v_mfma_f32_16x16x32_bf16 v[94:97], v[162:165], v[194:197], v[94:97]
	v_mfma_f32_16x16x32_bf16 v[90:93], v[170:173], v[194:197], v[90:93]
	v_mfma_f32_16x16x32_bf16 v[78:81], v[162:165], v[202:205], v[78:81]
	v_mfma_f32_16x16x32_bf16 v[74:77], v[170:173], v[202:205], v[74:77]
	v_mfma_f32_16x16x32_bf16 v[70:73], v[162:165], v[216:219], v[70:73]
	v_mfma_f32_16x16x32_bf16 v[66:69], v[170:173], v[216:219], v[66:69]
	v_mfma_f32_16x16x32_bf16 v[110:113], v[166:169], v[190:193], v[110:113]
	v_mfma_f32_16x16x32_bf16 v[106:109], v[174:177], v[190:193], v[106:109]
	v_mfma_f32_16x16x32_bf16 v[94:97], v[166:169], v[198:201], v[94:97]
	v_mfma_f32_16x16x32_bf16 v[90:93], v[174:177], v[198:201], v[90:93]
	v_mfma_f32_16x16x32_bf16 v[78:81], v[166:169], v[212:215], v[78:81]
	v_mfma_f32_16x16x32_bf16 v[74:77], v[174:177], v[212:215], v[74:77]
	v_mfma_f32_16x16x32_bf16 v[70:73], v[166:169], v[220:223], v[70:73]
	v_mfma_f32_16x16x32_bf16 v[66:69], v[174:177], v[220:223], v[66:69]
	s_setprio 0
	s_barrier
	s_add_i32 s48, s48, s69
	v_lshl_add_u64 v[224:225], s[62:63], 0, v[134:135]
	s_mov_b32 m0, s48
	ds_read_b128 v[182:185], v144 offset:16384
	ds_read_b128 v[190:193], v144 offset:17408
	ds_read_b128 v[194:197], v144 offset:18432
	ds_read_b128 v[198:201], v144 offset:19456
	ds_read_b128 v[202:205], v144 offset:20480
	ds_read_b128 v[212:215], v144 offset:21504
	ds_read_b128 v[216:219], v144 offset:22528
	ds_read_b128 v[220:223], v144 offset:23552
	global_load_lds_dwordx4 v[224:225], off
	s_add_i32 m0, s48, 0x2000
	s_add_u32 s48, s62, 0xb0000
	v_lshl_add_u64 v[226:227], s[62:63], 0, v[130:131]
	s_addc_u32 s49, s63, 0
	s_add_i32 s58, s86, s69
	global_load_lds_dwordx4 v[226:227], off
	v_lshl_add_u64 v[228:229], s[48:49], 0, v[134:135]
	s_mov_b32 m0, s58
	v_lshl_add_u64 v[230:231], s[64:65], 0, v[132:133]
	global_load_lds_dwordx4 v[228:229], off
	v_lshl_add_u64 v[228:229], s[48:49], 0, v[130:131]
	s_add_i32 m0, s58, 0x2000
	s_nop 0
	global_load_lds_dwordx4 v[228:229], off
	s_waitcnt vmcnt(6)
	s_waitcnt lgkmcnt(0)
	s_barrier
; #define PG8_STAGE(bufoff, gbase, voff) do { _Pragma("unroll") for (int _i = 0; _i < 2; ++_i) \
;         __builtin_amdgcn_global_load_lds((const unsigned*)((const char*)(gbase) + (voff)[_i]), (LAS unsigned*)(lds + (bufoff) + ldsw + _i * 8192), 16, 0, 0); } while (0)
; #define PG8_LDA(dst, b, h) do { _Pragma("unroll") for (int m = 0; m < 4; ++m) _Pragma("unroll") for (int k = 0; k < 2; ++k) dst[m][k] = *(const LAS bf16x8*)(lds + PG8_SA(b, h) + aoff + m * 2048 + k * 1024); } while (0)
; #define PG8_LDB(dst, b, h) do { _Pragma("unroll") for (int n = 0; n < 2; ++n) _Pragma("unroll") for (int k = 0; k < 2; ++k) dst[n][k] = *(const LAS bf16x8*)(lds + PG8_SB(b, h) + boff + n * 2048 + k * 1024); } while (0)
; #define PG8_MMA(ai, bj, At, Bt) do { __builtin_amdgcn_s_setprio(1); _Pragma("unroll") for (int m = 0; m < 4; ++m) _Pragma("unroll") for (int n = 0; n < 2; ++n) _Pragma("unroll") for (int k = 0; k < 2; ++k) \
;         acc[ai][bj][m][n] = __builtin_amdgcn_mfma_f32_16x16x32_bf16(Bt[n][k], At[m][k], acc[ai][bj][m][n], 0, 0, 0); __builtin_amdgcn_s_setprio(0); } while (0)
; #define PG8_WAIT_V(n) asm volatile("s_waitcnt vmcnt(" #n ")" ::: "memory")
; #define PG8_WAIT_L(n) asm volatile("s_waitcnt lgkmcnt(" #n ")" ::: "memory")
; #define PG8_BAR __builtin_amdgcn_s_barrier()
; #define PG8_SCHED __builtin_amdgcn_sched_barrier(0)
; template <class Epi, class Sched>
; DI void gemm_phase(LAS unsigned char* lds, const int K, const Sched& S, const Epi& E) {
;     ...
;             PG8_WAIT_V(8); PG8_WAIT_L(0); PG8_BAR; PG8_MMA(1, 0, At, B0); PG8_MMA(1, 1, At, B1); PG8_BAR; PG8_SCHED;
;             PG8_LDB(B0, 1, 0); PG8_LDB(B1, 1, 1); PG8_SCHED; PG8_LDA(At, 1, 0); PG8_STAGE(PG8_SA(0, 1), a2 + hstep, voffA);
;             PG8_WAIT_V(8); PG8_WAIT_L(0); PG8_BAR; PG8_MMA(0, 0, At, B0); PG8_MMA(0, 1, At, B1); PG8_BAR; PG8_SCHED;
	s_setprio 1
	s_waitcnt lgkmcnt(0)
	v_mfma_f32_16x16x32_bf16 v[62:65], v[146:149], v[182:185], v[62:65]
	v_mfma_f32_16x16x32_bf16 v[58:61], v[154:157], v[182:185], v[58:61]
	v_mfma_f32_16x16x32_bf16 v[54:57], v[146:149], v[194:197], v[54:57]
	v_mfma_f32_16x16x32_bf16 v[50:53], v[154:157], v[194:197], v[50:53]
	v_mfma_f32_16x16x32_bf16 v[38:41], v[146:149], v[202:205], v[38:41]
	v_mfma_f32_16x16x32_bf16 v[34:37], v[154:157], v[202:205], v[34:37]
	v_mfma_f32_16x16x32_bf16 v[22:25], v[146:149], v[216:219], v[22:25]
	v_mfma_f32_16x16x32_bf16 v[18:21], v[154:157], v[216:219], v[18:21]
	v_lshl_add_u64 v[228:229], s[64:65], 0, v[136:137]
	s_mov_b32 m0, s71
	s_nop 0
	global_load_lds_dwordx4 v[228:229], off
	v_mfma_f32_16x16x32_bf16 v[62:65], v[150:153], v[190:193], v[62:65]
	v_mfma_f32_16x16x32_bf16 v[58:61], v[158:161], v[190:193], v[58:61]
	v_mfma_f32_16x16x32_bf16 v[54:57], v[150:153], v[198:201], v[54:57]
	v_mfma_f32_16x16x32_bf16 v[50:53], v[158:161], v[198:201], v[50:53]
	v_mfma_f32_16x16x32_bf16 v[38:41], v[150:153], v[212:215], v[38:41]
	v_mfma_f32_16x16x32_bf16 v[34:37], v[158:161], v[212:215], v[34:37]
	v_mfma_f32_16x16x32_bf16 v[22:25], v[150:153], v[220:223], v[22:25]
	v_mfma_f32_16x16x32_bf16 v[18:21], v[158:161], v[220:223], v[18:21]
	s_setprio 0
	s_setprio 1
	v_mfma_f32_16x16x32_bf16 v[46:49], v[162:165], v[182:185], v[46:49]
	v_mfma_f32_16x16x32_bf16 v[42:45], v[170:173], v[182:185], v[42:45]
	v_mfma_f32_16x16x32_bf16 v[30:33], v[162:165], v[194:197], v[30:33]
	v_mfma_f32_16x16x32_bf16 v[26:29], v[170:173], v[194:197], v[26:29]
	v_mfma_f32_16x16x32_bf16 v[14:17], v[162:165], v[202:205], v[14:17]
	v_mfma_f32_16x16x32_bf16 v[10:13], v[170:173], v[202:205], v[10:13]
	v_mfma_f32_16x16x32_bf16 v[6:9], v[162:165], v[216:219], v[6:9]
	v_mfma_f32_16x16x32_bf16 v[2:5], v[170:173], v[216:219], v[2:5]
	s_mov_b32 m0, s72
	s_nop 0
	global_load_lds_dwordx4 v[230:231], off
	v_mfma_f32_16x16x32_bf16 v[46:49], v[166:169], v[190:193], v[46:49]
	v_mfma_f32_16x16x32_bf16 v[42:45], v[174:177], v[190:193], v[42:45]
	v_mfma_f32_16x16x32_bf16 v[30:33], v[166:169], v[198:201], v[30:33]
	v_mfma_f32_16x16x32_bf16 v[26:29], v[174:177], v[198:201], v[26:29]
	v_mfma_f32_16x16x32_bf16 v[14:17], v[166:169], v[212:215], v[14:17]
	v_mfma_f32_16x16x32_bf16 v[10:13], v[174:177], v[212:215], v[10:13]
	v_mfma_f32_16x16x32_bf16 v[6:9], v[166:169], v[220:223], v[6:9]
	v_mfma_f32_16x16x32_bf16 v[2:5], v[174:177], v[220:223], v[2:5]
	s_setprio 0
	s_barrier
	s_add_i32 s58, 0, 0x18000
	v_add_u32_e32 v145, s58, v143
	s_add_i32 s59, 0, 0x1c000
	ds_read_b128 v[146:149], v145
	ds_read_b128 v[150:153], v145 offset:1024
	ds_read_b128 v[154:157], v145 offset:2048
	ds_read_b128 v[158:161], v145 offset:3072
	v_add_u32_e32 v145, s59, v143
	ds_read_b128 v[162:165], v145
	ds_read_b128 v[166:169], v145 offset:1024
	ds_read_b128 v[170:173], v145 offset:2048
	ds_read_b128 v[174:177], v145 offset:3072
	s_add_u32 s48, s64, 0xb0000
	s_addc_u32 s49, s65, 0
	s_mov_b32 m0, s73
	v_lshl_add_u64 v[232:233], s[48:49], 0, v[136:137]
	ds_read_b128 v[182:185], v144 offset:32768
	ds_read_b128 v[190:193], v144 offset:33792
	ds_read_b128 v[194:197], v144 offset:34816
	ds_read_b128 v[198:201], v144 offset:35840
	ds_read_b128 v[202:205], v144 offset:36864
	ds_read_b128 v[212:215], v144 offset:37888
	ds_read_b128 v[216:219], v144 offset:38912
	ds_read_b128 v[220:223], v144 offset:39936
	global_load_lds_dwordx4 v[232:233], off
	v_lshl_add_u64 v[232:233], s[48:49], 0, v[132:133]
	s_mov_b32 m0, s74
	s_nop 0
	global_load_lds_dwordx4 v[232:233], off
	s_waitcnt vmcnt(8)
	s_waitcnt lgkmcnt(0)
	s_barrier
	s_setprio 1
	s_waitcnt lgkmcnt(0)
	v_mfma_f32_16x16x32_bf16 v[126:129], v[146:149], v[182:185], v[126:129]
	v_mfma_f32_16x16x32_bf16 v[122:125], v[154:157], v[182:185], v[122:125]
	v_mfma_f32_16x16x32_bf16 v[118:121], v[146:149], v[194:197], v[118:121]
	v_mfma_f32_16x16x32_bf16 v[114:117], v[154:157], v[194:197], v[114:117]
	v_mfma_f32_16x16x32_bf16 v[102:105], v[146:149], v[202:205], v[102:105]
	v_mfma_f32_16x16x32_bf16 v[98:101], v[154:157], v[202:205], v[98:101]
	v_mfma_f32_16x16x32_bf16 v[86:89], v[146:149], v[216:219], v[86:89]
	v_mfma_f32_16x16x32_bf16 v[82:85], v[154:157], v[216:219], v[82:85]
	v_mfma_f32_16x16x32_bf16 v[126:129], v[150:153], v[190:193], v[126:129]
	v_mfma_f32_16x16x32_bf16 v[122:125], v[158:161], v[190:193], v[122:125]
	v_mfma_f32_16x16x32_bf16 v[118:121], v[150:153], v[198:201], v[118:121]
	v_mfma_f32_16x16x32_bf16 v[114:117], v[158:161], v[198:201], v[114:117]
	v_mfma_f32_16x16x32_bf16 v[102:105], v[150:153], v[212:215], v[102:105]
	v_mfma_f32_16x16x32_bf16 v[98:101], v[158:161], v[212:215], v[98:101]
	v_mfma_f32_16x16x32_bf16 v[86:89], v[150:153], v[220:223], v[86:89]
	v_mfma_f32_16x16x32_bf16 v[82:85], v[158:161], v[220:223], v[82:85]
	s_setprio 0
	s_setprio 1
	v_mfma_f32_16x16x32_bf16 v[110:113], v[162:165], v[182:185], v[110:113]
	v_mfma_f32_16x16x32_bf16 v[106:109], v[170:173], v[182:185], v[106:109]
	v_mfma_f32_16x16x32_bf16 v[94:97], v[162:165], v[194:197], v[94:97]
	v_mfma_f32_16x16x32_bf16 v[90:93], v[170:173], v[194:197], v[90:93]
	v_mfma_f32_16x16x32_bf16 v[78:81], v[162:165], v[202:205], v[78:81]
	v_mfma_f32_16x16x32_bf16 v[74:77], v[170:173], v[202:205], v[74:77]
	v_mfma_f32_16x16x32_bf16 v[70:73], v[162:165], v[216:219], v[70:73]
	v_mfma_f32_16x16x32_bf16 v[66:69], v[170:173], v[216:219], v[66:69]
	v_mfma_f32_16x16x32_bf16 v[110:113], v[166:169], v[190:193], v[110:113]
	v_mfma_f32_16x16x32_bf16 v[106:109], v[174:177], v[190:193], v[106:109]
	v_mfma_f32_16x16x32_bf16 v[94:97], v[166:169], v[198:201], v[94:97]
	v_mfma_f32_16x16x32_bf16 v[90:93], v[174:177], v[198:201], v[90:93]
	v_mfma_f32_16x16x32_bf16 v[78:81], v[166:169], v[212:215], v[78:81]
	v_mfma_f32_16x16x32_bf16 v[74:77], v[174:177], v[212:215], v[74:77]
	v_mfma_f32_16x16x32_bf16 v[70:73], v[166:169], v[220:223], v[70:73]
	v_mfma_f32_16x16x32_bf16 v[66:69], v[174:177], v[220:223], v[66:69]
	s_setprio 0
	s_barrier
; #define PG8_STAGE(bufoff, gbase, voff) do { _Pragma("unroll") for (int _i = 0; _i < 2; ++_i) \
;         __builtin_amdgcn_global_load_lds((const unsigned*)((const char*)(gbase) + (voff)[_i]), (LAS unsigned*)(lds + (bufoff) + ldsw + _i * 8192), 16, 0, 0); } while (0)
; #define PG8_LDA(dst, b, h) do { _Pragma("unroll") for (int m = 0; m < 4; ++m) _Pragma("unroll") for (int k = 0; k < 2; ++k) dst[m][k] = *(const LAS bf16x8*)(lds + PG8_SA(b, h) + aoff + m * 2048 + k * 1024); } while (0)
; #define PG8_MMA(ai, bj, At, Bt) do { __builtin_amdgcn_s_setprio(1); _Pragma("unroll") for (int m = 0; m < 4; ++m) _Pragma("unroll") for (int n = 0; n < 2; ++n) _Pragma("unroll") for (int k = 0; k < 2; ++k) \
;         acc[ai][bj][m][n] = __builtin_amdgcn_mfma_f32_16x16x32_bf16(Bt[n][k], At[m][k], acc[ai][bj][m][n], 0, 0, 0); __builtin_amdgcn_s_setprio(0); } while (0)
; #define PG8_WAIT_V(n) asm volatile("s_waitcnt vmcnt(" #n ")" ::: "memory")
; #define PG8_WAIT_L(n) asm volatile("s_waitcnt lgkmcnt(" #n ")" ::: "memory")
; #define PG8_BAR __builtin_amdgcn_s_barrier()
; #define PG8_SCHED __builtin_amdgcn_sched_barrier(0)
; template <class Epi, class Sched>
; DI void gemm_phase(LAS unsigned char* lds, const int K, const Sched& S, const Epi& E) {
;     ...
;             PG8_LDA(At, 1, 1); PG8_STAGE(PG8_SB(1, 0), b3, voffB); PG8_STAGE(PG8_SB(1, 1), b3 + hstep, voffB); PG8_STAGE(PG8_SA(1, 0), a3, voffA);
;             PG8_WAIT_V(8); PG8_WAIT_L(0); PG8_BAR; PG8_MMA(1, 0, At, B0); PG8_MMA(1, 1, At, B1); PG8_BAR; PG8_SCHED;
;         }
;         if (wr == 0) PG8_BAR;
	s_add_i32 s48, s58, s69
	v_lshl_add_u64 v[224:225], v[224:225], 0, s[90:91]
	s_mov_b32 m0, s48
	ds_read_b128 v[182:185], v144 offset:49152
	ds_read_b128 v[190:193], v144 offset:50176
	ds_read_b128 v[194:197], v144 offset:51200
	ds_read_b128 v[198:201], v144 offset:52224
	ds_read_b128 v[202:205], v144 offset:53248
	ds_read_b128 v[212:215], v144 offset:54272
	ds_read_b128 v[216:219], v144 offset:55296
	ds_read_b128 v[220:223], v144 offset:56320
	global_load_lds_dwordx4 v[224:225], off
	s_add_i32 m0, s48, 0x2000
	s_add_u32 s48, s62, 0xb0080
	v_lshl_add_u64 v[224:225], v[226:227], 0, s[90:91]
	s_addc_u32 s49, s63, 0
	s_add_i32 s58, s59, s69
	global_load_lds_dwordx4 v[224:225], off
	v_lshl_add_u64 v[224:225], s[48:49], 0, v[134:135]
	s_mov_b32 m0, s58
	s_nop 0
	global_load_lds_dwordx4 v[224:225], off
	v_lshl_add_u64 v[224:225], s[48:49], 0, v[130:131]
	s_add_i32 m0, s58, 0x2000
	s_nop 0
	global_load_lds_dwordx4 v[224:225], off
	s_waitcnt vmcnt(6)
	s_waitcnt lgkmcnt(0)
	s_barrier
	s_setprio 1
	s_waitcnt lgkmcnt(0)
	v_mfma_f32_16x16x32_bf16 v[62:65], v[146:149], v[182:185], v[62:65]
	v_mfma_f32_16x16x32_bf16 v[58:61], v[154:157], v[182:185], v[58:61]
	v_mfma_f32_16x16x32_bf16 v[54:57], v[146:149], v[194:197], v[54:57]
	v_mfma_f32_16x16x32_bf16 v[50:53], v[154:157], v[194:197], v[50:53]
	v_mfma_f32_16x16x32_bf16 v[38:41], v[146:149], v[202:205], v[38:41]
	v_mfma_f32_16x16x32_bf16 v[34:37], v[154:157], v[202:205], v[34:37]
	v_mfma_f32_16x16x32_bf16 v[22:25], v[146:149], v[216:219], v[22:25]
	v_mfma_f32_16x16x32_bf16 v[18:21], v[154:157], v[216:219], v[18:21]
	v_lshl_add_u64 v[224:225], v[228:229], 0, s[90:91]
	s_mov_b32 m0, s77
	s_nop 0
	global_load_lds_dwordx4 v[224:225], off
	v_mfma_f32_16x16x32_bf16 v[62:65], v[150:153], v[190:193], v[62:65]
	v_mfma_f32_16x16x32_bf16 v[58:61], v[158:161], v[190:193], v[58:61]
	v_mfma_f32_16x16x32_bf16 v[54:57], v[150:153], v[198:201], v[54:57]
	v_mfma_f32_16x16x32_bf16 v[50:53], v[158:161], v[198:201], v[50:53]
	v_mfma_f32_16x16x32_bf16 v[38:41], v[150:153], v[212:215], v[38:41]
	v_mfma_f32_16x16x32_bf16 v[34:37], v[158:161], v[212:215], v[34:37]
	v_mfma_f32_16x16x32_bf16 v[22:25], v[150:153], v[220:223], v[22:25]
	v_mfma_f32_16x16x32_bf16 v[18:21], v[158:161], v[220:223], v[18:21]
	s_setprio 0
	s_setprio 1
	v_mfma_f32_16x16x32_bf16 v[46:49], v[162:165], v[182:185], v[46:49]
	v_mfma_f32_16x16x32_bf16 v[42:45], v[170:173], v[182:185], v[42:45]
	v_mfma_f32_16x16x32_bf16 v[30:33], v[162:165], v[194:197], v[30:33]
	v_mfma_f32_16x16x32_bf16 v[26:29], v[170:173], v[194:197], v[26:29]
	v_mfma_f32_16x16x32_bf16 v[14:17], v[162:165], v[202:205], v[14:17]
	v_mfma_f32_16x16x32_bf16 v[10:13], v[170:173], v[202:205], v[10:13]
	v_mfma_f32_16x16x32_bf16 v[6:9], v[162:165], v[216:219], v[6:9]
	v_mfma_f32_16x16x32_bf16 v[2:5], v[170:173], v[216:219], v[2:5]
	v_lshl_add_u64 v[224:225], v[230:231], 0, s[90:91]
	s_mov_b32 m0, s78
	s_nop 0
	global_load_lds_dwordx4 v[224:225], off
	v_mfma_f32_16x16x32_bf16 v[46:49], v[166:169], v[190:193], v[46:49]
	v_mfma_f32_16x16x32_bf16 v[42:45], v[174:177], v[190:193], v[42:45]
	v_mfma_f32_16x16x32_bf16 v[30:33], v[166:169], v[198:201], v[30:33]
	v_mfma_f32_16x16x32_bf16 v[26:29], v[174:177], v[198:201], v[26:29]
	v_mfma_f32_16x16x32_bf16 v[14:17], v[166:169], v[212:215], v[14:17]
	v_mfma_f32_16x16x32_bf16 v[10:13], v[174:177], v[212:215], v[10:13]
	v_mfma_f32_16x16x32_bf16 v[6:9], v[166:169], v[220:223], v[6:9]
	v_mfma_f32_16x16x32_bf16 v[2:5], v[174:177], v[220:223], v[2:5]
	s_setprio 0
	s_barrier
	s_add_i32 s85, s85, 2
	s_add_u32 s83, s83, 0x100
	s_addc_u32 s84, s84, 0
	s_cmp_gt_u32 s85, 41
	s_mov_b64 s[58:59], s[60:61]
	s_cbranch_scc0 .LBB0_1204
	s_and_b64 vcc, exec, s[52:53]
	s_cbranch_vccz .LBB0_1207
	s_barrier
